# P7: half-rendezvous K-loop sync, un-aligned epilogues, leading-half MFMAs chain-ordered (same accumulator back-to-back), cached row stats in SwiGLU epilogue; sgu pass1 16 loads in flight; barrier TOPG
# speedup vs baseline: 1.0151x; 1.0151x over previous
.LBB0_241:
	s_add_u32 s94, s26, s92
	s_addc_u32 s95, s27, s93
	s_add_u32 s94, s94, 0x100
	s_addc_u32 s95, s95, 0
	s_add_u32 vcc_lo, s41, s92
	s_addc_u32 vcc_hi, s44, s93
	s_add_i32 s43, 0, 0x10000
	v_add_u32_e32 v152, s43, v171
	ds_read_b128 v[132:135], v152
	ds_read_b128 v[136:139], v152 offset:1024
	ds_read_b128 v[140:143], v152 offset:2048
	ds_read_b128 v[166:169], v152 offset:3072
	v_add_u32_e32 v152, s8, v171
	ds_read_b128 v[178:181], v152
	ds_read_b128 v[182:185], v152 offset:1024
	ds_read_b128 v[186:189], v152 offset:2048
	ds_read_b128 v[190:193], v152 offset:3072
	s_cmpk_eq_i32 s92, 0xf00
	s_cselect_b32 s97, s45, s95
	s_cselect_b32 s96, s50, s94
	s_cselect_b32 s95, s51, vcc_hi
	s_cselect_b32 s94, s81, vcc_lo
	v_lshl_add_u64 v[226:227], v[128:129], 0, s[92:93]
	s_add_i32 m0, s21, 0xc000
	ds_read_b128 v[194:197], v173
	ds_read_b128 v[198:201], v173 offset:1024
	ds_read_b128 v[202:205], v173 offset:2048
	ds_read_b128 v[206:209], v173 offset:3072
	ds_read_b128 v[210:213], v173 offset:4096
	ds_read_b128 v[214:217], v173 offset:5120
	ds_read_b128 v[218:221], v173 offset:6144
	ds_read_b128 v[222:225], v173 offset:7168
	global_load_lds_dwordx4 v[226:227], off
	v_lshl_add_u64 v[226:227], v[130:131], 0, s[92:93]
	s_add_i32 m0, s21, 0xe000
	s_nop 0
	global_load_lds_dwordx4 v[226:227], off
	s_waitcnt vmcnt(8)
	s_waitcnt lgkmcnt(0)
	s_barrier
	s_setprio 1
	s_waitcnt lgkmcnt(0)
	v_mfma_f32_16x16x32_bf16 v[124:127], v[132:135], v[194:197], v[124:127]
	v_mfma_f32_16x16x32_bf16 v[124:127], v[136:139], v[198:201], v[124:127]
	v_mfma_f32_16x16x32_bf16 v[120:123], v[140:143], v[194:197], v[120:123]
	v_mfma_f32_16x16x32_bf16 v[120:123], v[166:169], v[198:201], v[120:123]
	v_mfma_f32_16x16x32_bf16 v[116:119], v[132:135], v[202:205], v[116:119]
	v_mfma_f32_16x16x32_bf16 v[116:119], v[136:139], v[206:209], v[116:119]
	v_mfma_f32_16x16x32_bf16 v[112:115], v[140:143], v[202:205], v[112:115]
	v_mfma_f32_16x16x32_bf16 v[112:115], v[166:169], v[206:209], v[112:115]
	v_mfma_f32_16x16x32_bf16 v[108:111], v[132:135], v[210:213], v[108:111]
	v_mfma_f32_16x16x32_bf16 v[108:111], v[136:139], v[214:217], v[108:111]
	v_mfma_f32_16x16x32_bf16 v[104:107], v[140:143], v[210:213], v[104:107]
	v_mfma_f32_16x16x32_bf16 v[104:107], v[166:169], v[214:217], v[104:107]
	v_mfma_f32_16x16x32_bf16 v[100:103], v[132:135], v[218:221], v[100:103]
	v_mfma_f32_16x16x32_bf16 v[100:103], v[136:139], v[222:225], v[100:103]
	v_mfma_f32_16x16x32_bf16 v[96:99], v[140:143], v[218:221], v[96:99]
	v_mfma_f32_16x16x32_bf16 v[96:99], v[166:169], v[222:225], v[96:99]
	s_setprio 0
	s_setprio 1
	v_mfma_f32_16x16x32_bf16 v[92:95], v[178:181], v[194:197], v[92:95]
	v_mfma_f32_16x16x32_bf16 v[92:95], v[182:185], v[198:201], v[92:95]
	v_mfma_f32_16x16x32_bf16 v[88:91], v[186:189], v[194:197], v[88:91]
	v_mfma_f32_16x16x32_bf16 v[88:91], v[190:193], v[198:201], v[88:91]
	v_mfma_f32_16x16x32_bf16 v[84:87], v[178:181], v[202:205], v[84:87]
	v_mfma_f32_16x16x32_bf16 v[84:87], v[182:185], v[206:209], v[84:87]
	v_mfma_f32_16x16x32_bf16 v[80:83], v[186:189], v[202:205], v[80:83]
	v_mfma_f32_16x16x32_bf16 v[80:83], v[190:193], v[206:209], v[80:83]
	v_mfma_f32_16x16x32_bf16 v[76:79], v[178:181], v[210:213], v[76:79]
	v_mfma_f32_16x16x32_bf16 v[76:79], v[182:185], v[214:217], v[76:79]
	v_mfma_f32_16x16x32_bf16 v[72:75], v[186:189], v[210:213], v[72:75]
	v_mfma_f32_16x16x32_bf16 v[72:75], v[190:193], v[214:217], v[72:75]
	v_mfma_f32_16x16x32_bf16 v[68:71], v[178:181], v[218:221], v[68:71]
	v_mfma_f32_16x16x32_bf16 v[68:71], v[182:185], v[222:225], v[68:71]
	v_mfma_f32_16x16x32_bf16 v[64:67], v[186:189], v[218:221], v[64:67]
	v_mfma_f32_16x16x32_bf16 v[64:67], v[190:193], v[222:225], v[64:67]
	s_setprio 0
	s_barrier
	s_add_i32 s43, s43, s17
	v_lshl_add_u64 v[226:227], s[94:95], 0, v[146:147]
	s_mov_b32 m0, s43
	ds_read_b128 v[194:197], v173 offset:16384
	ds_read_b128 v[198:201], v173 offset:17408
	ds_read_b128 v[202:205], v173 offset:18432
	ds_read_b128 v[206:209], v173 offset:19456
	ds_read_b128 v[210:213], v173 offset:20480
	ds_read_b128 v[214:217], v173 offset:21504
	ds_read_b128 v[218:221], v173 offset:22528
	ds_read_b128 v[222:225], v173 offset:23552
	global_load_lds_dwordx4 v[226:227], off
	s_add_i32 m0, s43, 0x2000
	s_add_u32 vcc_lo, s94, 0x80000
	v_lshl_add_u64 v[228:229], s[94:95], 0, v[150:151]
	s_addc_u32 vcc_hi, s95, 0
	s_add_i32 s43, s8, s17
	global_load_lds_dwordx4 v[228:229], off
	v_lshl_add_u64 v[230:231], vcc, 0, v[146:147]
	s_mov_b32 m0, s43
	v_lshl_add_u64 v[232:233], s[96:97], 0, v[148:149]
	global_load_lds_dwordx4 v[230:231], off
	v_lshl_add_u64 v[230:231], vcc, 0, v[150:151]
	s_add_i32 m0, s43, 0x2000
	s_nop 0
	global_load_lds_dwordx4 v[230:231], off
	v_lshl_add_u64 v[230:231], s[96:97], 0, v[144:145]
	s_mov_b32 m0, s21
	s_nop 0
	global_load_lds_dwordx4 v[230:231], off
	s_mov_b32 m0, s39
	s_nop 0
	global_load_lds_dwordx4 v[232:233], off
	s_waitcnt vmcnt(8)
	s_waitcnt lgkmcnt(0)
	s_barrier
	s_setprio 1
	s_waitcnt lgkmcnt(0)
	v_mfma_f32_16x16x32_bf16 v[60:63], v[132:135], v[194:197], v[60:63]
	v_mfma_f32_16x16x32_bf16 v[60:63], v[136:139], v[198:201], v[60:63]
	v_mfma_f32_16x16x32_bf16 v[56:59], v[140:143], v[194:197], v[56:59]
	v_mfma_f32_16x16x32_bf16 v[56:59], v[166:169], v[198:201], v[56:59]
	v_mfma_f32_16x16x32_bf16 v[52:55], v[132:135], v[202:205], v[52:55]
	v_mfma_f32_16x16x32_bf16 v[52:55], v[136:139], v[206:209], v[52:55]
	v_mfma_f32_16x16x32_bf16 v[48:51], v[140:143], v[202:205], v[48:51]
	v_mfma_f32_16x16x32_bf16 v[48:51], v[166:169], v[206:209], v[48:51]
	v_mfma_f32_16x16x32_bf16 v[44:47], v[132:135], v[210:213], v[44:47]
	v_mfma_f32_16x16x32_bf16 v[44:47], v[136:139], v[214:217], v[44:47]
	v_mfma_f32_16x16x32_bf16 v[40:43], v[140:143], v[210:213], v[40:43]
	v_mfma_f32_16x16x32_bf16 v[40:43], v[166:169], v[214:217], v[40:43]
	v_mfma_f32_16x16x32_bf16 v[36:39], v[132:135], v[218:221], v[36:39]
	v_mfma_f32_16x16x32_bf16 v[36:39], v[136:139], v[222:225], v[36:39]
	v_mfma_f32_16x16x32_bf16 v[32:35], v[140:143], v[218:221], v[32:35]
	v_mfma_f32_16x16x32_bf16 v[32:35], v[166:169], v[222:225], v[32:35]
	s_setprio 0
	s_setprio 1
	v_mfma_f32_16x16x32_bf16 v[28:31], v[178:181], v[194:197], v[28:31]
	v_mfma_f32_16x16x32_bf16 v[28:31], v[182:185], v[198:201], v[28:31]
	v_mfma_f32_16x16x32_bf16 v[24:27], v[186:189], v[194:197], v[24:27]
	v_mfma_f32_16x16x32_bf16 v[24:27], v[190:193], v[198:201], v[24:27]
	v_mfma_f32_16x16x32_bf16 v[20:23], v[178:181], v[202:205], v[20:23]
	v_mfma_f32_16x16x32_bf16 v[20:23], v[182:185], v[206:209], v[20:23]
	v_mfma_f32_16x16x32_bf16 v[16:19], v[186:189], v[202:205], v[16:19]
	v_mfma_f32_16x16x32_bf16 v[16:19], v[190:193], v[206:209], v[16:19]
	v_mfma_f32_16x16x32_bf16 v[12:15], v[178:181], v[210:213], v[12:15]
	v_mfma_f32_16x16x32_bf16 v[12:15], v[182:185], v[214:217], v[12:15]
	v_mfma_f32_16x16x32_bf16 v[8:11], v[186:189], v[210:213], v[8:11]
	v_mfma_f32_16x16x32_bf16 v[8:11], v[190:193], v[214:217], v[8:11]
	v_mfma_f32_16x16x32_bf16 v[4:7], v[178:181], v[218:221], v[4:7]
	v_mfma_f32_16x16x32_bf16 v[4:7], v[182:185], v[222:225], v[4:7]
	v_mfma_f32_16x16x32_bf16 v[0:3], v[186:189], v[218:221], v[0:3]
	v_mfma_f32_16x16x32_bf16 v[0:3], v[190:193], v[222:225], v[0:3]
	s_setprio 0
	s_barrier
	s_add_i32 s43, 0, 0x18000
	v_add_u32_e32 v152, s43, v171
	s_add_i32 vcc_lo, 0, 0x1c000
	ds_read_b128 v[132:135], v152
	ds_read_b128 v[136:139], v152 offset:1024
	ds_read_b128 v[140:143], v152 offset:2048
	ds_read_b128 v[166:169], v152 offset:3072
	v_add_u32_e32 v152, vcc_lo, v171
	ds_read_b128 v[178:181], v152
	ds_read_b128 v[182:185], v152 offset:1024
	ds_read_b128 v[186:189], v152 offset:2048
	ds_read_b128 v[190:193], v152 offset:3072
	s_add_u32 s96, s96, 0x80000
	s_addc_u32 s97, s97, 0
	s_mov_b32 m0, s6
	v_lshl_add_u64 v[234:235], s[96:97], 0, v[144:145]
	ds_read_b128 v[194:197], v173 offset:32768
	ds_read_b128 v[198:201], v173 offset:33792
	ds_read_b128 v[202:205], v173 offset:34816
	ds_read_b128 v[206:209], v173 offset:35840
	ds_read_b128 v[210:213], v173 offset:36864
	ds_read_b128 v[214:217], v173 offset:37888
	ds_read_b128 v[218:221], v173 offset:38912
	ds_read_b128 v[222:225], v173 offset:39936
	global_load_lds_dwordx4 v[234:235], off
	v_lshl_add_u64 v[234:235], s[96:97], 0, v[148:149]
	s_mov_b32 m0, s10
	s_nop 0
	global_load_lds_dwordx4 v[234:235], off
	s_waitcnt vmcnt(8)
	s_waitcnt lgkmcnt(0)
	s_barrier
	s_setprio 1
	s_waitcnt lgkmcnt(0)
	v_mfma_f32_16x16x32_bf16 v[124:127], v[132:135], v[194:197], v[124:127]
	v_mfma_f32_16x16x32_bf16 v[124:127], v[136:139], v[198:201], v[124:127]
	v_mfma_f32_16x16x32_bf16 v[120:123], v[140:143], v[194:197], v[120:123]
	v_mfma_f32_16x16x32_bf16 v[120:123], v[166:169], v[198:201], v[120:123]
	v_mfma_f32_16x16x32_bf16 v[116:119], v[132:135], v[202:205], v[116:119]
	v_mfma_f32_16x16x32_bf16 v[116:119], v[136:139], v[206:209], v[116:119]
	v_mfma_f32_16x16x32_bf16 v[112:115], v[140:143], v[202:205], v[112:115]
	v_mfma_f32_16x16x32_bf16 v[112:115], v[166:169], v[206:209], v[112:115]
	v_mfma_f32_16x16x32_bf16 v[108:111], v[132:135], v[210:213], v[108:111]
	v_mfma_f32_16x16x32_bf16 v[108:111], v[136:139], v[214:217], v[108:111]
	v_mfma_f32_16x16x32_bf16 v[104:107], v[140:143], v[210:213], v[104:107]
	v_mfma_f32_16x16x32_bf16 v[104:107], v[166:169], v[214:217], v[104:107]
	v_mfma_f32_16x16x32_bf16 v[100:103], v[132:135], v[218:221], v[100:103]
	v_mfma_f32_16x16x32_bf16 v[100:103], v[136:139], v[222:225], v[100:103]
	v_mfma_f32_16x16x32_bf16 v[96:99], v[140:143], v[218:221], v[96:99]
	v_mfma_f32_16x16x32_bf16 v[96:99], v[166:169], v[222:225], v[96:99]
	s_setprio 0
	s_setprio 1
	v_mfma_f32_16x16x32_bf16 v[92:95], v[178:181], v[194:197], v[92:95]
	v_mfma_f32_16x16x32_bf16 v[92:95], v[182:185], v[198:201], v[92:95]
	v_mfma_f32_16x16x32_bf16 v[88:91], v[186:189], v[194:197], v[88:91]
	v_mfma_f32_16x16x32_bf16 v[88:91], v[190:193], v[198:201], v[88:91]
	v_mfma_f32_16x16x32_bf16 v[84:87], v[178:181], v[202:205], v[84:87]
	v_mfma_f32_16x16x32_bf16 v[84:87], v[182:185], v[206:209], v[84:87]
	v_mfma_f32_16x16x32_bf16 v[80:83], v[186:189], v[202:205], v[80:83]
	v_mfma_f32_16x16x32_bf16 v[80:83], v[190:193], v[206:209], v[80:83]
	v_mfma_f32_16x16x32_bf16 v[76:79], v[178:181], v[210:213], v[76:79]
	v_mfma_f32_16x16x32_bf16 v[76:79], v[182:185], v[214:217], v[76:79]
	v_mfma_f32_16x16x32_bf16 v[72:75], v[186:189], v[210:213], v[72:75]
	v_mfma_f32_16x16x32_bf16 v[72:75], v[190:193], v[214:217], v[72:75]
	v_mfma_f32_16x16x32_bf16 v[68:71], v[178:181], v[218:221], v[68:71]
	v_mfma_f32_16x16x32_bf16 v[68:71], v[182:185], v[222:225], v[68:71]
	v_mfma_f32_16x16x32_bf16 v[64:67], v[186:189], v[218:221], v[64:67]
	v_mfma_f32_16x16x32_bf16 v[64:67], v[190:193], v[222:225], v[64:67]
	s_setprio 0
	s_barrier
	s_add_i32 s43, s43, s17
	v_lshl_add_u64 v[226:227], v[226:227], 0, s[70:71]
	s_mov_b32 m0, s43
	ds_read_b128 v[194:197], v173 offset:49152
	ds_read_b128 v[198:201], v173 offset:50176
	ds_read_b128 v[202:205], v173 offset:51200
	ds_read_b128 v[206:209], v173 offset:52224
	ds_read_b128 v[210:213], v173 offset:53248
	ds_read_b128 v[214:217], v173 offset:54272
	ds_read_b128 v[218:221], v173 offset:55296
	ds_read_b128 v[222:225], v173 offset:56320
	global_load_lds_dwordx4 v[226:227], off
	s_add_i32 m0, s43, 0x2000
	s_add_u32 s94, s94, 0x80080
	v_lshl_add_u64 v[226:227], v[228:229], 0, s[70:71]
	s_addc_u32 s95, s95, 0
	s_add_i32 s43, vcc_lo, s17
	global_load_lds_dwordx4 v[226:227], off
	v_lshl_add_u64 v[226:227], s[94:95], 0, v[146:147]
	s_mov_b32 m0, s43
	s_nop 0
	global_load_lds_dwordx4 v[226:227], off
	v_lshl_add_u64 v[226:227], s[94:95], 0, v[150:151]
	s_add_i32 m0, s43, 0x2000
	s_nop 0
	global_load_lds_dwordx4 v[226:227], off
	v_lshl_add_u64 v[226:227], v[230:231], 0, s[70:71]
	s_mov_b32 m0, s33
	s_nop 0
	global_load_lds_dwordx4 v[226:227], off
	v_lshl_add_u64 v[226:227], v[232:233], 0, s[70:71]
	s_mov_b32 m0, s7
	s_nop 0
	global_load_lds_dwordx4 v[226:227], off
	s_waitcnt vmcnt(8)
	s_waitcnt lgkmcnt(0)
	s_barrier
	s_setprio 1
	s_waitcnt lgkmcnt(0)
	v_mfma_f32_16x16x32_bf16 v[60:63], v[132:135], v[194:197], v[60:63]
	v_mfma_f32_16x16x32_bf16 v[60:63], v[136:139], v[198:201], v[60:63]
	v_mfma_f32_16x16x32_bf16 v[56:59], v[140:143], v[194:197], v[56:59]
	v_mfma_f32_16x16x32_bf16 v[56:59], v[166:169], v[198:201], v[56:59]
	v_mfma_f32_16x16x32_bf16 v[52:55], v[132:135], v[202:205], v[52:55]
	v_mfma_f32_16x16x32_bf16 v[52:55], v[136:139], v[206:209], v[52:55]
	v_mfma_f32_16x16x32_bf16 v[48:51], v[140:143], v[202:205], v[48:51]
	v_mfma_f32_16x16x32_bf16 v[48:51], v[166:169], v[206:209], v[48:51]
	v_mfma_f32_16x16x32_bf16 v[44:47], v[132:135], v[210:213], v[44:47]
	v_mfma_f32_16x16x32_bf16 v[44:47], v[136:139], v[214:217], v[44:47]
	v_mfma_f32_16x16x32_bf16 v[40:43], v[140:143], v[210:213], v[40:43]
	v_mfma_f32_16x16x32_bf16 v[40:43], v[166:169], v[214:217], v[40:43]
	v_mfma_f32_16x16x32_bf16 v[36:39], v[132:135], v[218:221], v[36:39]
	v_mfma_f32_16x16x32_bf16 v[36:39], v[136:139], v[222:225], v[36:39]
	v_mfma_f32_16x16x32_bf16 v[32:35], v[140:143], v[218:221], v[32:35]
	v_mfma_f32_16x16x32_bf16 v[32:35], v[166:169], v[222:225], v[32:35]
	s_setprio 0
	s_setprio 1
	v_mfma_f32_16x16x32_bf16 v[28:31], v[178:181], v[194:197], v[28:31]
	v_mfma_f32_16x16x32_bf16 v[28:31], v[182:185], v[198:201], v[28:31]
	v_mfma_f32_16x16x32_bf16 v[24:27], v[186:189], v[194:197], v[24:27]
	v_mfma_f32_16x16x32_bf16 v[24:27], v[190:193], v[198:201], v[24:27]
	v_mfma_f32_16x16x32_bf16 v[20:23], v[178:181], v[202:205], v[20:23]
	v_mfma_f32_16x16x32_bf16 v[20:23], v[182:185], v[206:209], v[20:23]
	v_mfma_f32_16x16x32_bf16 v[16:19], v[186:189], v[202:205], v[16:19]
	v_mfma_f32_16x16x32_bf16 v[16:19], v[190:193], v[206:209], v[16:19]
	v_mfma_f32_16x16x32_bf16 v[12:15], v[178:181], v[210:213], v[12:15]
	v_mfma_f32_16x16x32_bf16 v[12:15], v[182:185], v[214:217], v[12:15]
	v_mfma_f32_16x16x32_bf16 v[8:11], v[186:189], v[210:213], v[8:11]
	v_mfma_f32_16x16x32_bf16 v[8:11], v[190:193], v[214:217], v[8:11]
	v_mfma_f32_16x16x32_bf16 v[4:7], v[178:181], v[218:221], v[4:7]
	v_mfma_f32_16x16x32_bf16 v[4:7], v[182:185], v[222:225], v[4:7]
	v_mfma_f32_16x16x32_bf16 v[0:3], v[186:189], v[218:221], v[0:3]
	v_mfma_f32_16x16x32_bf16 v[0:3], v[190:193], v[222:225], v[0:3]
	s_setprio 0
	s_barrier
	s_add_i32 s83, s83, 2
	s_add_u32 s92, s92, 0x100
	s_addc_u32 s93, s93, 0
	s_cmp_gt_u32 s83, 29
	s_cbranch_scc0 .LBB0_241
	s_and_b64 vcc, exec, s[72:73]
	s_cbranch_vccz .LBB0_244
	s_barrier

.LBB0_273:
	ds_read_b128 v[146:149], v141
	ds_read_b128 v[150:153], v141 offset:1024
	ds_read_b128 v[154:157], v141 offset:2048
	ds_read_b128 v[158:161], v141 offset:3072
	ds_read_b128 v[162:165], v142
	ds_read_b128 v[166:169], v142 offset:1024
	ds_read_b128 v[170:173], v142 offset:2048
	ds_read_b128 v[176:179], v142 offset:3072
	s_add_u32 s48, s46, 0xfff80080
	s_addc_u32 s49, s47, -1
	s_cmp_eq_u32 s80, 4
	s_cselect_b32 s69, s39, s49
	s_cselect_b32 s68, s38, s48
	s_cselect_b32 s49, s43, s79
	s_cselect_b32 s48, s42, s27
	v_lshl_add_u64 v[212:213], s[46:47], 0, v[136:137]
	s_add_i32 m0, s10, 0xc000
	ds_read_b128 v[180:183], v143
	ds_read_b128 v[184:187], v143 offset:1024
	ds_read_b128 v[188:191], v143 offset:2048
	ds_read_b128 v[192:195], v143 offset:3072
	ds_read_b128 v[196:199], v143 offset:4096
	ds_read_b128 v[200:203], v143 offset:5120
	ds_read_b128 v[204:207], v143 offset:6144
	ds_read_b128 v[208:211], v143 offset:7168
	global_load_lds_dwordx4 v[212:213], off
	v_lshl_add_u64 v[212:213], s[46:47], 0, v[138:139]
	s_add_i32 m0, s10, 0xe000
	s_nop 0
	global_load_lds_dwordx4 v[212:213], off
	s_waitcnt vmcnt(8)
	s_waitcnt lgkmcnt(0)
	s_barrier
	s_setprio 1
	s_waitcnt lgkmcnt(0)
	v_mfma_f32_16x16x32_bf16 v[124:127], v[146:149], v[180:183], v[124:127]
	v_mfma_f32_16x16x32_bf16 v[124:127], v[150:153], v[184:187], v[124:127]
	v_mfma_f32_16x16x32_bf16 v[120:123], v[154:157], v[180:183], v[120:123]
	v_mfma_f32_16x16x32_bf16 v[120:123], v[158:161], v[184:187], v[120:123]
	v_mfma_f32_16x16x32_bf16 v[116:119], v[146:149], v[188:191], v[116:119]
	v_mfma_f32_16x16x32_bf16 v[116:119], v[150:153], v[192:195], v[116:119]
	v_mfma_f32_16x16x32_bf16 v[112:115], v[154:157], v[188:191], v[112:115]
	v_mfma_f32_16x16x32_bf16 v[112:115], v[158:161], v[192:195], v[112:115]
	v_mfma_f32_16x16x32_bf16 v[100:103], v[146:149], v[196:199], v[100:103]
	v_mfma_f32_16x16x32_bf16 v[100:103], v[150:153], v[200:203], v[100:103]
	v_mfma_f32_16x16x32_bf16 v[96:99], v[154:157], v[196:199], v[96:99]
	v_mfma_f32_16x16x32_bf16 v[96:99], v[158:161], v[200:203], v[96:99]
	v_mfma_f32_16x16x32_bf16 v[84:87], v[146:149], v[204:207], v[84:87]
	v_mfma_f32_16x16x32_bf16 v[84:87], v[150:153], v[208:211], v[84:87]
	v_mfma_f32_16x16x32_bf16 v[80:83], v[154:157], v[204:207], v[80:83]
	v_mfma_f32_16x16x32_bf16 v[80:83], v[158:161], v[208:211], v[80:83]
	s_setprio 0
	s_setprio 1
	v_mfma_f32_16x16x32_bf16 v[108:111], v[162:165], v[180:183], v[108:111]
	v_mfma_f32_16x16x32_bf16 v[108:111], v[166:169], v[184:187], v[108:111]
	v_mfma_f32_16x16x32_bf16 v[104:107], v[170:173], v[180:183], v[104:107]
	v_mfma_f32_16x16x32_bf16 v[104:107], v[176:179], v[184:187], v[104:107]
	v_mfma_f32_16x16x32_bf16 v[92:95], v[162:165], v[188:191], v[92:95]
	v_mfma_f32_16x16x32_bf16 v[92:95], v[166:169], v[192:195], v[92:95]
	v_mfma_f32_16x16x32_bf16 v[88:91], v[170:173], v[188:191], v[88:91]
	v_mfma_f32_16x16x32_bf16 v[88:91], v[176:179], v[192:195], v[88:91]
	v_mfma_f32_16x16x32_bf16 v[76:79], v[162:165], v[196:199], v[76:79]
	v_mfma_f32_16x16x32_bf16 v[76:79], v[166:169], v[200:203], v[76:79]
	v_mfma_f32_16x16x32_bf16 v[72:75], v[170:173], v[196:199], v[72:75]
	v_mfma_f32_16x16x32_bf16 v[72:75], v[176:179], v[200:203], v[72:75]
	v_mfma_f32_16x16x32_bf16 v[68:71], v[162:165], v[204:207], v[68:71]
	v_mfma_f32_16x16x32_bf16 v[68:71], v[166:169], v[208:211], v[68:71]
	v_mfma_f32_16x16x32_bf16 v[64:67], v[170:173], v[204:207], v[64:67]
	v_mfma_f32_16x16x32_bf16 v[64:67], v[176:179], v[208:211], v[64:67]
	s_setprio 0
	s_barrier
	s_add_i32 s81, s45, s6
	v_lshl_add_u64 v[212:213], s[48:49], 0, v[132:133]
	s_mov_b32 m0, s81
	ds_read_b128 v[180:183], v143 offset:16384
	ds_read_b128 v[184:187], v143 offset:17408
	ds_read_b128 v[188:191], v143 offset:18432
	ds_read_b128 v[192:195], v143 offset:19456
	ds_read_b128 v[196:199], v143 offset:20480
	ds_read_b128 v[200:203], v143 offset:21504
	ds_read_b128 v[204:207], v143 offset:22528
	ds_read_b128 v[208:211], v143 offset:23552
	global_load_lds_dwordx4 v[212:213], off
	s_add_i32 m0, s81, 0x2000
	s_add_u32 s82, s48, 0x80000
	v_lshl_add_u64 v[214:215], s[48:49], 0, v[128:129]
	s_addc_u32 s83, s49, 0
	s_add_i32 s81, s50, s6
	global_load_lds_dwordx4 v[214:215], off
	v_lshl_add_u64 v[216:217], s[82:83], 0, v[132:133]
	s_mov_b32 m0, s81
	v_lshl_add_u64 v[218:219], s[68:69], 0, v[130:131]
	global_load_lds_dwordx4 v[216:217], off
	v_lshl_add_u64 v[216:217], s[82:83], 0, v[128:129]
	s_add_i32 m0, s81, 0x2000
	s_nop 0
	global_load_lds_dwordx4 v[216:217], off
	v_lshl_add_u64 v[216:217], s[68:69], 0, v[134:135]
	s_mov_b32 m0, s10
	s_nop 0
	global_load_lds_dwordx4 v[216:217], off
	s_mov_b32 m0, s22
	s_nop 0
	global_load_lds_dwordx4 v[218:219], off
	s_waitcnt vmcnt(8)
	s_waitcnt lgkmcnt(0)
	s_barrier
	s_setprio 1
	s_waitcnt lgkmcnt(0)
	v_mfma_f32_16x16x32_bf16 v[60:63], v[146:149], v[180:183], v[60:63]
	v_mfma_f32_16x16x32_bf16 v[60:63], v[150:153], v[184:187], v[60:63]
	v_mfma_f32_16x16x32_bf16 v[56:59], v[154:157], v[180:183], v[56:59]
	v_mfma_f32_16x16x32_bf16 v[56:59], v[158:161], v[184:187], v[56:59]
	v_mfma_f32_16x16x32_bf16 v[52:55], v[146:149], v[188:191], v[52:55]
	v_mfma_f32_16x16x32_bf16 v[52:55], v[150:153], v[192:195], v[52:55]
	v_mfma_f32_16x16x32_bf16 v[48:51], v[154:157], v[188:191], v[48:51]
	v_mfma_f32_16x16x32_bf16 v[48:51], v[158:161], v[192:195], v[48:51]
	v_mfma_f32_16x16x32_bf16 v[36:39], v[146:149], v[196:199], v[36:39]
	v_mfma_f32_16x16x32_bf16 v[36:39], v[150:153], v[200:203], v[36:39]
	v_mfma_f32_16x16x32_bf16 v[32:35], v[154:157], v[196:199], v[32:35]
	v_mfma_f32_16x16x32_bf16 v[32:35], v[158:161], v[200:203], v[32:35]
	v_mfma_f32_16x16x32_bf16 v[20:23], v[146:149], v[204:207], v[20:23]
	v_mfma_f32_16x16x32_bf16 v[20:23], v[150:153], v[208:211], v[20:23]
	v_mfma_f32_16x16x32_bf16 v[16:19], v[154:157], v[204:207], v[16:19]
	v_mfma_f32_16x16x32_bf16 v[16:19], v[158:161], v[208:211], v[16:19]
	s_setprio 0
	s_setprio 1
	v_mfma_f32_16x16x32_bf16 v[44:47], v[162:165], v[180:183], v[44:47]
	v_mfma_f32_16x16x32_bf16 v[44:47], v[166:169], v[184:187], v[44:47]
	v_mfma_f32_16x16x32_bf16 v[40:43], v[170:173], v[180:183], v[40:43]
	v_mfma_f32_16x16x32_bf16 v[40:43], v[176:179], v[184:187], v[40:43]
	v_mfma_f32_16x16x32_bf16 v[28:31], v[162:165], v[188:191], v[28:31]
	v_mfma_f32_16x16x32_bf16 v[28:31], v[166:169], v[192:195], v[28:31]
	v_mfma_f32_16x16x32_bf16 v[24:27], v[170:173], v[188:191], v[24:27]
	v_mfma_f32_16x16x32_bf16 v[24:27], v[176:179], v[192:195], v[24:27]
	v_mfma_f32_16x16x32_bf16 v[12:15], v[162:165], v[196:199], v[12:15]
	v_mfma_f32_16x16x32_bf16 v[12:15], v[166:169], v[200:203], v[12:15]
	v_mfma_f32_16x16x32_bf16 v[8:11], v[170:173], v[196:199], v[8:11]
	v_mfma_f32_16x16x32_bf16 v[8:11], v[176:179], v[200:203], v[8:11]
	v_mfma_f32_16x16x32_bf16 v[4:7], v[162:165], v[204:207], v[4:7]
	v_mfma_f32_16x16x32_bf16 v[4:7], v[166:169], v[208:211], v[4:7]
	v_mfma_f32_16x16x32_bf16 v[0:3], v[170:173], v[204:207], v[0:3]
	v_mfma_f32_16x16x32_bf16 v[0:3], v[176:179], v[208:211], v[0:3]
	s_setprio 0
	s_barrier
	s_add_i32 s81, 0, 0x18000
	v_add_u32_e32 v145, s81, v140
	s_add_i32 s82, 0, 0x1c000
	ds_read_b128 v[146:149], v145
	ds_read_b128 v[150:153], v145 offset:1024
	ds_read_b128 v[154:157], v145 offset:2048
	ds_read_b128 v[158:161], v145 offset:3072
	v_add_u32_e32 v145, s82, v140
	ds_read_b128 v[162:165], v145
	ds_read_b128 v[166:169], v145 offset:1024
	ds_read_b128 v[170:173], v145 offset:2048
	ds_read_b128 v[176:179], v145 offset:3072
	s_add_u32 s68, s68, 0x80000
	s_addc_u32 s69, s69, 0
	s_mov_b32 m0, s23
	v_lshl_add_u64 v[220:221], s[68:69], 0, v[134:135]
	ds_read_b128 v[180:183], v143 offset:32768
	ds_read_b128 v[184:187], v143 offset:33792
	ds_read_b128 v[188:191], v143 offset:34816
	ds_read_b128 v[192:195], v143 offset:35840
	ds_read_b128 v[196:199], v143 offset:36864
	ds_read_b128 v[200:203], v143 offset:37888
	ds_read_b128 v[204:207], v143 offset:38912
	ds_read_b128 v[208:211], v143 offset:39936
	global_load_lds_dwordx4 v[220:221], off
	v_lshl_add_u64 v[220:221], s[68:69], 0, v[130:131]
	s_mov_b32 m0, s33
	s_nop 0
	global_load_lds_dwordx4 v[220:221], off
	s_waitcnt vmcnt(8)
	s_waitcnt lgkmcnt(0)
	s_barrier
	s_setprio 1
	s_waitcnt lgkmcnt(0)
	v_mfma_f32_16x16x32_bf16 v[124:127], v[146:149], v[180:183], v[124:127]
	v_mfma_f32_16x16x32_bf16 v[124:127], v[150:153], v[184:187], v[124:127]
	v_mfma_f32_16x16x32_bf16 v[120:123], v[154:157], v[180:183], v[120:123]
	v_mfma_f32_16x16x32_bf16 v[120:123], v[158:161], v[184:187], v[120:123]
	v_mfma_f32_16x16x32_bf16 v[116:119], v[146:149], v[188:191], v[116:119]
	v_mfma_f32_16x16x32_bf16 v[116:119], v[150:153], v[192:195], v[116:119]
	v_mfma_f32_16x16x32_bf16 v[112:115], v[154:157], v[188:191], v[112:115]
	v_mfma_f32_16x16x32_bf16 v[112:115], v[158:161], v[192:195], v[112:115]
	v_mfma_f32_16x16x32_bf16 v[100:103], v[146:149], v[196:199], v[100:103]
	v_mfma_f32_16x16x32_bf16 v[100:103], v[150:153], v[200:203], v[100:103]
	v_mfma_f32_16x16x32_bf16 v[96:99], v[154:157], v[196:199], v[96:99]
	v_mfma_f32_16x16x32_bf16 v[96:99], v[158:161], v[200:203], v[96:99]
	v_mfma_f32_16x16x32_bf16 v[84:87], v[146:149], v[204:207], v[84:87]
	v_mfma_f32_16x16x32_bf16 v[84:87], v[150:153], v[208:211], v[84:87]
	v_mfma_f32_16x16x32_bf16 v[80:83], v[154:157], v[204:207], v[80:83]
	v_mfma_f32_16x16x32_bf16 v[80:83], v[158:161], v[208:211], v[80:83]
	s_setprio 0
	s_setprio 1
	v_mfma_f32_16x16x32_bf16 v[108:111], v[162:165], v[180:183], v[108:111]
	v_mfma_f32_16x16x32_bf16 v[108:111], v[166:169], v[184:187], v[108:111]
	v_mfma_f32_16x16x32_bf16 v[104:107], v[170:173], v[180:183], v[104:107]
	v_mfma_f32_16x16x32_bf16 v[104:107], v[176:179], v[184:187], v[104:107]
	v_mfma_f32_16x16x32_bf16 v[92:95], v[162:165], v[188:191], v[92:95]
	v_mfma_f32_16x16x32_bf16 v[92:95], v[166:169], v[192:195], v[92:95]
	v_mfma_f32_16x16x32_bf16 v[88:91], v[170:173], v[188:191], v[88:91]
	v_mfma_f32_16x16x32_bf16 v[88:91], v[176:179], v[192:195], v[88:91]
	v_mfma_f32_16x16x32_bf16 v[76:79], v[162:165], v[196:199], v[76:79]
	v_mfma_f32_16x16x32_bf16 v[76:79], v[166:169], v[200:203], v[76:79]
	v_mfma_f32_16x16x32_bf16 v[72:75], v[170:173], v[196:199], v[72:75]
	v_mfma_f32_16x16x32_bf16 v[72:75], v[176:179], v[200:203], v[72:75]
	v_mfma_f32_16x16x32_bf16 v[68:71], v[162:165], v[204:207], v[68:71]
	v_mfma_f32_16x16x32_bf16 v[68:71], v[166:169], v[208:211], v[68:71]
	v_mfma_f32_16x16x32_bf16 v[64:67], v[170:173], v[204:207], v[64:67]
	v_mfma_f32_16x16x32_bf16 v[64:67], v[176:179], v[208:211], v[64:67]
	s_setprio 0
	s_barrier
	s_add_i32 s68, s81, s6
	v_lshl_add_u64 v[212:213], v[212:213], 0, s[16:17]
	s_mov_b32 m0, s68
	ds_read_b128 v[180:183], v143 offset:49152
	ds_read_b128 v[184:187], v143 offset:50176
	ds_read_b128 v[188:191], v143 offset:51200
	ds_read_b128 v[192:195], v143 offset:52224
	ds_read_b128 v[196:199], v143 offset:53248
	ds_read_b128 v[200:203], v143 offset:54272
	ds_read_b128 v[204:207], v143 offset:55296
	ds_read_b128 v[208:211], v143 offset:56320
	global_load_lds_dwordx4 v[212:213], off
	s_add_i32 m0, s68, 0x2000
	s_add_u32 s48, s48, 0x80080
	v_lshl_add_u64 v[212:213], v[214:215], 0, s[16:17]
	s_addc_u32 s49, s49, 0
	s_add_i32 s68, s82, s6
	global_load_lds_dwordx4 v[212:213], off
	v_lshl_add_u64 v[212:213], s[48:49], 0, v[132:133]
	s_mov_b32 m0, s68
	s_nop 0
	global_load_lds_dwordx4 v[212:213], off
	v_lshl_add_u64 v[212:213], s[48:49], 0, v[128:129]
	s_add_i32 m0, s68, 0x2000
	s_nop 0
	global_load_lds_dwordx4 v[212:213], off
	v_lshl_add_u64 v[212:213], v[216:217], 0, s[16:17]
	s_mov_b32 m0, s41
	s_nop 0
	global_load_lds_dwordx4 v[212:213], off
	v_lshl_add_u64 v[212:213], v[218:219], 0, s[16:17]
	s_mov_b32 m0, s44
	s_nop 0
	global_load_lds_dwordx4 v[212:213], off
	s_waitcnt vmcnt(8)
	s_waitcnt lgkmcnt(0)
	s_barrier
	s_setprio 1
	s_waitcnt lgkmcnt(0)
	v_mfma_f32_16x16x32_bf16 v[60:63], v[146:149], v[180:183], v[60:63]
	v_mfma_f32_16x16x32_bf16 v[60:63], v[150:153], v[184:187], v[60:63]
	v_mfma_f32_16x16x32_bf16 v[56:59], v[154:157], v[180:183], v[56:59]
	v_mfma_f32_16x16x32_bf16 v[56:59], v[158:161], v[184:187], v[56:59]
	v_mfma_f32_16x16x32_bf16 v[52:55], v[146:149], v[188:191], v[52:55]
	v_mfma_f32_16x16x32_bf16 v[52:55], v[150:153], v[192:195], v[52:55]
	v_mfma_f32_16x16x32_bf16 v[48:51], v[154:157], v[188:191], v[48:51]
	v_mfma_f32_16x16x32_bf16 v[48:51], v[158:161], v[192:195], v[48:51]
	v_mfma_f32_16x16x32_bf16 v[36:39], v[146:149], v[196:199], v[36:39]
	v_mfma_f32_16x16x32_bf16 v[36:39], v[150:153], v[200:203], v[36:39]
	v_mfma_f32_16x16x32_bf16 v[32:35], v[154:157], v[196:199], v[32:35]
	v_mfma_f32_16x16x32_bf16 v[32:35], v[158:161], v[200:203], v[32:35]
	v_mfma_f32_16x16x32_bf16 v[20:23], v[146:149], v[204:207], v[20:23]
	v_mfma_f32_16x16x32_bf16 v[20:23], v[150:153], v[208:211], v[20:23]
	v_mfma_f32_16x16x32_bf16 v[16:19], v[154:157], v[204:207], v[16:19]
	v_mfma_f32_16x16x32_bf16 v[16:19], v[158:161], v[208:211], v[16:19]
	s_setprio 0
	s_setprio 1
	v_mfma_f32_16x16x32_bf16 v[44:47], v[162:165], v[180:183], v[44:47]
	v_mfma_f32_16x16x32_bf16 v[44:47], v[166:169], v[184:187], v[44:47]
	v_mfma_f32_16x16x32_bf16 v[40:43], v[170:173], v[180:183], v[40:43]
	v_mfma_f32_16x16x32_bf16 v[40:43], v[176:179], v[184:187], v[40:43]
	v_mfma_f32_16x16x32_bf16 v[28:31], v[162:165], v[188:191], v[28:31]
	v_mfma_f32_16x16x32_bf16 v[28:31], v[166:169], v[192:195], v[28:31]
	v_mfma_f32_16x16x32_bf16 v[24:27], v[170:173], v[188:191], v[24:27]
	v_mfma_f32_16x16x32_bf16 v[24:27], v[176:179], v[192:195], v[24:27]
	v_mfma_f32_16x16x32_bf16 v[12:15], v[162:165], v[196:199], v[12:15]
	v_mfma_f32_16x16x32_bf16 v[12:15], v[166:169], v[200:203], v[12:15]
	v_mfma_f32_16x16x32_bf16 v[8:11], v[170:173], v[196:199], v[8:11]
	v_mfma_f32_16x16x32_bf16 v[8:11], v[176:179], v[200:203], v[8:11]
	v_mfma_f32_16x16x32_bf16 v[4:7], v[162:165], v[204:207], v[4:7]
	v_mfma_f32_16x16x32_bf16 v[4:7], v[166:169], v[208:211], v[4:7]
	v_mfma_f32_16x16x32_bf16 v[0:3], v[170:173], v[204:207], v[0:3]
	v_mfma_f32_16x16x32_bf16 v[0:3], v[176:179], v[208:211], v[0:3]
	s_setprio 0
	s_barrier
	s_add_i32 s80, s80, 2
	s_add_u32 s46, s46, 0x100
	s_addc_u32 s47, s47, 0
	s_add_u32 s27, s27, 0x100
	s_addc_u32 s79, s79, 0
	s_cmp_gt_u32 s80, 5
	s_cbranch_scc0 .LBB0_273
	s_and_b64 vcc, exec, s[20:21]
	s_cbranch_vccz .LBB0_276
	s_barrier

.LBB0_414:
	ds_read_b128 v[146:149], v141
	ds_read_b128 v[150:153], v141 offset:1024
	ds_read_b128 v[154:157], v141 offset:2048
	ds_read_b128 v[158:161], v141 offset:3072
	ds_read_b128 v[162:165], v142
	ds_read_b128 v[166:169], v142 offset:1024
	ds_read_b128 v[170:173], v142 offset:2048
	ds_read_b128 v[176:179], v142 offset:3072
	s_add_u32 s46, s44, 0xfff80080
	s_addc_u32 s47, s45, -1
	s_cmp_eq_u32 s82, 4
	s_cselect_b32 s49, s41, s47
	s_cselect_b32 s48, s40, s46
	s_cselect_b32 s47, s43, s81
	s_cselect_b32 s46, s42, s39
	s_mov_b32 m0, s64
	v_lshl_add_u64 v[212:213], s[44:45], 0, v[136:137]
	ds_read_b128 v[180:183], v143
	ds_read_b128 v[184:187], v143 offset:1024
	ds_read_b128 v[188:191], v143 offset:2048
	ds_read_b128 v[192:195], v143 offset:3072
	ds_read_b128 v[196:199], v143 offset:4096
	ds_read_b128 v[200:203], v143 offset:5120
	ds_read_b128 v[204:207], v143 offset:6144
	ds_read_b128 v[208:211], v143 offset:7168
	global_load_lds_dwordx4 v[212:213], off
	v_lshl_add_u64 v[212:213], s[44:45], 0, v[138:139]
	s_mov_b32 m0, s65
	s_nop 0
	global_load_lds_dwordx4 v[212:213], off
	s_waitcnt vmcnt(8)
	s_waitcnt lgkmcnt(0)
	s_barrier
	s_setprio 1
	s_waitcnt lgkmcnt(0)
	v_mfma_f32_16x16x32_bf16 v[124:127], v[146:149], v[180:183], v[124:127]
	v_mfma_f32_16x16x32_bf16 v[124:127], v[150:153], v[184:187], v[124:127]
	v_mfma_f32_16x16x32_bf16 v[120:123], v[154:157], v[180:183], v[120:123]
	v_mfma_f32_16x16x32_bf16 v[120:123], v[158:161], v[184:187], v[120:123]
	v_mfma_f32_16x16x32_bf16 v[116:119], v[146:149], v[188:191], v[116:119]
	v_mfma_f32_16x16x32_bf16 v[116:119], v[150:153], v[192:195], v[116:119]
	v_mfma_f32_16x16x32_bf16 v[112:115], v[154:157], v[188:191], v[112:115]
	v_mfma_f32_16x16x32_bf16 v[112:115], v[158:161], v[192:195], v[112:115]
	v_mfma_f32_16x16x32_bf16 v[100:103], v[146:149], v[196:199], v[100:103]
	v_mfma_f32_16x16x32_bf16 v[100:103], v[150:153], v[200:203], v[100:103]
	v_mfma_f32_16x16x32_bf16 v[96:99], v[154:157], v[196:199], v[96:99]
	v_mfma_f32_16x16x32_bf16 v[96:99], v[158:161], v[200:203], v[96:99]
	v_mfma_f32_16x16x32_bf16 v[84:87], v[146:149], v[204:207], v[84:87]
	v_mfma_f32_16x16x32_bf16 v[84:87], v[150:153], v[208:211], v[84:87]
	v_mfma_f32_16x16x32_bf16 v[80:83], v[154:157], v[204:207], v[80:83]
	v_mfma_f32_16x16x32_bf16 v[80:83], v[158:161], v[208:211], v[80:83]
	s_setprio 0
	s_setprio 1
	v_mfma_f32_16x16x32_bf16 v[108:111], v[162:165], v[180:183], v[108:111]
	v_mfma_f32_16x16x32_bf16 v[108:111], v[166:169], v[184:187], v[108:111]
	v_mfma_f32_16x16x32_bf16 v[104:107], v[170:173], v[180:183], v[104:107]
	v_mfma_f32_16x16x32_bf16 v[104:107], v[176:179], v[184:187], v[104:107]
	v_mfma_f32_16x16x32_bf16 v[92:95], v[162:165], v[188:191], v[92:95]
	v_mfma_f32_16x16x32_bf16 v[92:95], v[166:169], v[192:195], v[92:95]
	v_mfma_f32_16x16x32_bf16 v[88:91], v[170:173], v[188:191], v[88:91]
	v_mfma_f32_16x16x32_bf16 v[88:91], v[176:179], v[192:195], v[88:91]
	v_mfma_f32_16x16x32_bf16 v[76:79], v[162:165], v[196:199], v[76:79]
	v_mfma_f32_16x16x32_bf16 v[76:79], v[166:169], v[200:203], v[76:79]
	v_mfma_f32_16x16x32_bf16 v[72:75], v[170:173], v[196:199], v[72:75]
	v_mfma_f32_16x16x32_bf16 v[72:75], v[176:179], v[200:203], v[72:75]
	v_mfma_f32_16x16x32_bf16 v[68:71], v[162:165], v[204:207], v[68:71]
	v_mfma_f32_16x16x32_bf16 v[68:71], v[166:169], v[208:211], v[68:71]
	v_mfma_f32_16x16x32_bf16 v[64:67], v[170:173], v[204:207], v[64:67]
	v_mfma_f32_16x16x32_bf16 v[64:67], v[176:179], v[208:211], v[64:67]
	s_setprio 0
	s_barrier
	s_mov_b32 m0, s68
	v_lshl_add_u64 v[212:213], s[46:47], 0, v[132:133]
	s_add_u32 s84, s46, 0x80000
	ds_read_b128 v[180:183], v143 offset:16384
	ds_read_b128 v[184:187], v143 offset:17408
	ds_read_b128 v[188:191], v143 offset:18432
	ds_read_b128 v[192:195], v143 offset:19456
	ds_read_b128 v[196:199], v143 offset:20480
	ds_read_b128 v[200:203], v143 offset:21504
	ds_read_b128 v[204:207], v143 offset:22528
	ds_read_b128 v[208:211], v143 offset:23552
	global_load_lds_dwordx4 v[212:213], off
	v_lshl_add_u64 v[214:215], s[46:47], 0, v[128:129]
	s_mov_b32 m0, s69
	s_addc_u32 s85, s47, 0
	global_load_lds_dwordx4 v[214:215], off
	v_lshl_add_u64 v[216:217], s[84:85], 0, v[132:133]
	s_mov_b32 m0, s77
	v_lshl_add_u64 v[218:219], s[48:49], 0, v[130:131]
	global_load_lds_dwordx4 v[216:217], off
	v_lshl_add_u64 v[216:217], s[84:85], 0, v[128:129]
	s_add_i32 m0, s77, 0x2000
	s_nop 0
	global_load_lds_dwordx4 v[216:217], off
	v_lshl_add_u64 v[216:217], s[48:49], 0, v[134:135]
	s_mov_b32 m0, s22
	s_nop 0
	global_load_lds_dwordx4 v[216:217], off
	s_mov_b32 m0, s23
	s_nop 0
	global_load_lds_dwordx4 v[218:219], off
	s_waitcnt vmcnt(8)
	s_waitcnt lgkmcnt(0)
	s_barrier
	s_setprio 1
	s_waitcnt lgkmcnt(0)
	v_mfma_f32_16x16x32_bf16 v[60:63], v[146:149], v[180:183], v[60:63]
	v_mfma_f32_16x16x32_bf16 v[60:63], v[150:153], v[184:187], v[60:63]
	v_mfma_f32_16x16x32_bf16 v[56:59], v[154:157], v[180:183], v[56:59]
	v_mfma_f32_16x16x32_bf16 v[56:59], v[158:161], v[184:187], v[56:59]
	v_mfma_f32_16x16x32_bf16 v[52:55], v[146:149], v[188:191], v[52:55]
	v_mfma_f32_16x16x32_bf16 v[52:55], v[150:153], v[192:195], v[52:55]
	v_mfma_f32_16x16x32_bf16 v[48:51], v[154:157], v[188:191], v[48:51]
	v_mfma_f32_16x16x32_bf16 v[48:51], v[158:161], v[192:195], v[48:51]
	v_mfma_f32_16x16x32_bf16 v[36:39], v[146:149], v[196:199], v[36:39]
	v_mfma_f32_16x16x32_bf16 v[36:39], v[150:153], v[200:203], v[36:39]
	v_mfma_f32_16x16x32_bf16 v[32:35], v[154:157], v[196:199], v[32:35]
	v_mfma_f32_16x16x32_bf16 v[32:35], v[158:161], v[200:203], v[32:35]
	v_mfma_f32_16x16x32_bf16 v[20:23], v[146:149], v[204:207], v[20:23]
	v_mfma_f32_16x16x32_bf16 v[20:23], v[150:153], v[208:211], v[20:23]
	v_mfma_f32_16x16x32_bf16 v[16:19], v[154:157], v[204:207], v[16:19]
	v_mfma_f32_16x16x32_bf16 v[16:19], v[158:161], v[208:211], v[16:19]
	s_setprio 0
	s_setprio 1
	v_mfma_f32_16x16x32_bf16 v[44:47], v[162:165], v[180:183], v[44:47]
	v_mfma_f32_16x16x32_bf16 v[44:47], v[166:169], v[184:187], v[44:47]
	v_mfma_f32_16x16x32_bf16 v[40:43], v[170:173], v[180:183], v[40:43]
	v_mfma_f32_16x16x32_bf16 v[40:43], v[176:179], v[184:187], v[40:43]
	v_mfma_f32_16x16x32_bf16 v[28:31], v[162:165], v[188:191], v[28:31]
	v_mfma_f32_16x16x32_bf16 v[28:31], v[166:169], v[192:195], v[28:31]
	v_mfma_f32_16x16x32_bf16 v[24:27], v[170:173], v[188:191], v[24:27]
	v_mfma_f32_16x16x32_bf16 v[24:27], v[176:179], v[192:195], v[24:27]
	v_mfma_f32_16x16x32_bf16 v[12:15], v[162:165], v[196:199], v[12:15]
	v_mfma_f32_16x16x32_bf16 v[12:15], v[166:169], v[200:203], v[12:15]
	v_mfma_f32_16x16x32_bf16 v[8:11], v[170:173], v[196:199], v[8:11]
	v_mfma_f32_16x16x32_bf16 v[8:11], v[176:179], v[200:203], v[8:11]
	v_mfma_f32_16x16x32_bf16 v[4:7], v[162:165], v[204:207], v[4:7]
	v_mfma_f32_16x16x32_bf16 v[4:7], v[166:169], v[208:211], v[4:7]
	v_mfma_f32_16x16x32_bf16 v[0:3], v[170:173], v[204:207], v[0:3]
	v_mfma_f32_16x16x32_bf16 v[0:3], v[176:179], v[208:211], v[0:3]
	s_setprio 0
	s_barrier
	s_add_i32 s83, 0, 0x18000
	v_add_u32_e32 v145, s83, v140
	s_add_i32 s84, 0, 0x1c000
	ds_read_b128 v[146:149], v145
	ds_read_b128 v[150:153], v145 offset:1024
	ds_read_b128 v[154:157], v145 offset:2048
	ds_read_b128 v[158:161], v145 offset:3072
	v_add_u32_e32 v145, s84, v140
	ds_read_b128 v[162:165], v145
	ds_read_b128 v[166:169], v145 offset:1024
	ds_read_b128 v[170:173], v145 offset:2048
	ds_read_b128 v[176:179], v145 offset:3072
	s_add_u32 s48, s48, 0x80000
	s_addc_u32 s49, s49, 0
	s_mov_b32 m0, s33
	v_lshl_add_u64 v[220:221], s[48:49], 0, v[134:135]
	ds_read_b128 v[180:183], v143 offset:32768
	ds_read_b128 v[184:187], v143 offset:33792
	ds_read_b128 v[188:191], v143 offset:34816
	ds_read_b128 v[192:195], v143 offset:35840
	ds_read_b128 v[196:199], v143 offset:36864
	ds_read_b128 v[200:203], v143 offset:37888
	ds_read_b128 v[204:207], v143 offset:38912
	ds_read_b128 v[208:211], v143 offset:39936
	global_load_lds_dwordx4 v[220:221], off
	v_lshl_add_u64 v[220:221], s[48:49], 0, v[130:131]
	s_mov_b32 m0, s50
	s_nop 0
	global_load_lds_dwordx4 v[220:221], off
	s_waitcnt vmcnt(8)
	s_waitcnt lgkmcnt(0)
	s_barrier
	s_setprio 1
	s_waitcnt lgkmcnt(0)
	v_mfma_f32_16x16x32_bf16 v[124:127], v[146:149], v[180:183], v[124:127]
	v_mfma_f32_16x16x32_bf16 v[124:127], v[150:153], v[184:187], v[124:127]
	v_mfma_f32_16x16x32_bf16 v[120:123], v[154:157], v[180:183], v[120:123]
	v_mfma_f32_16x16x32_bf16 v[120:123], v[158:161], v[184:187], v[120:123]
	v_mfma_f32_16x16x32_bf16 v[116:119], v[146:149], v[188:191], v[116:119]
	v_mfma_f32_16x16x32_bf16 v[116:119], v[150:153], v[192:195], v[116:119]
	v_mfma_f32_16x16x32_bf16 v[112:115], v[154:157], v[188:191], v[112:115]
	v_mfma_f32_16x16x32_bf16 v[112:115], v[158:161], v[192:195], v[112:115]
	v_mfma_f32_16x16x32_bf16 v[100:103], v[146:149], v[196:199], v[100:103]
	v_mfma_f32_16x16x32_bf16 v[100:103], v[150:153], v[200:203], v[100:103]
	v_mfma_f32_16x16x32_bf16 v[96:99], v[154:157], v[196:199], v[96:99]
	v_mfma_f32_16x16x32_bf16 v[96:99], v[158:161], v[200:203], v[96:99]
	v_mfma_f32_16x16x32_bf16 v[84:87], v[146:149], v[204:207], v[84:87]
	v_mfma_f32_16x16x32_bf16 v[84:87], v[150:153], v[208:211], v[84:87]
	v_mfma_f32_16x16x32_bf16 v[80:83], v[154:157], v[204:207], v[80:83]
	v_mfma_f32_16x16x32_bf16 v[80:83], v[158:161], v[208:211], v[80:83]
	s_setprio 0
	s_setprio 1
	v_mfma_f32_16x16x32_bf16 v[108:111], v[162:165], v[180:183], v[108:111]
	v_mfma_f32_16x16x32_bf16 v[108:111], v[166:169], v[184:187], v[108:111]
	v_mfma_f32_16x16x32_bf16 v[104:107], v[170:173], v[180:183], v[104:107]
	v_mfma_f32_16x16x32_bf16 v[104:107], v[176:179], v[184:187], v[104:107]
	v_mfma_f32_16x16x32_bf16 v[92:95], v[162:165], v[188:191], v[92:95]
	v_mfma_f32_16x16x32_bf16 v[92:95], v[166:169], v[192:195], v[92:95]
	v_mfma_f32_16x16x32_bf16 v[88:91], v[170:173], v[188:191], v[88:91]
	v_mfma_f32_16x16x32_bf16 v[88:91], v[176:179], v[192:195], v[88:91]
	v_mfma_f32_16x16x32_bf16 v[76:79], v[162:165], v[196:199], v[76:79]
	v_mfma_f32_16x16x32_bf16 v[76:79], v[166:169], v[200:203], v[76:79]
	v_mfma_f32_16x16x32_bf16 v[72:75], v[170:173], v[196:199], v[72:75]
	v_mfma_f32_16x16x32_bf16 v[72:75], v[176:179], v[200:203], v[72:75]
	v_mfma_f32_16x16x32_bf16 v[68:71], v[162:165], v[204:207], v[68:71]
	v_mfma_f32_16x16x32_bf16 v[68:71], v[166:169], v[208:211], v[68:71]
	v_mfma_f32_16x16x32_bf16 v[64:67], v[170:173], v[204:207], v[64:67]
	v_mfma_f32_16x16x32_bf16 v[64:67], v[176:179], v[208:211], v[64:67]
	s_setprio 0
	s_barrier
	s_add_i32 s48, s83, s10
	v_lshl_add_u64 v[212:213], v[212:213], 0, s[24:25]
	s_mov_b32 m0, s48
	ds_read_b128 v[180:183], v143 offset:49152
	ds_read_b128 v[184:187], v143 offset:50176
	ds_read_b128 v[188:191], v143 offset:51200
	ds_read_b128 v[192:195], v143 offset:52224
	ds_read_b128 v[196:199], v143 offset:53248
	ds_read_b128 v[200:203], v143 offset:54272
	ds_read_b128 v[204:207], v143 offset:55296
	ds_read_b128 v[208:211], v143 offset:56320
	global_load_lds_dwordx4 v[212:213], off
	s_add_i32 m0, s48, 0x2000
	s_add_u32 s46, s46, 0x80080
	v_lshl_add_u64 v[212:213], v[214:215], 0, s[24:25]
	s_addc_u32 s47, s47, 0
	s_add_i32 s48, s84, s10
	global_load_lds_dwordx4 v[212:213], off
	v_lshl_add_u64 v[212:213], s[46:47], 0, v[132:133]
	s_mov_b32 m0, s48
	s_nop 0
	global_load_lds_dwordx4 v[212:213], off
	v_lshl_add_u64 v[212:213], s[46:47], 0, v[128:129]
	s_add_i32 m0, s48, 0x2000
	s_nop 0
	global_load_lds_dwordx4 v[212:213], off
	v_lshl_add_u64 v[212:213], v[216:217], 0, s[24:25]
	s_mov_b32 m0, s62
	s_nop 0
	global_load_lds_dwordx4 v[212:213], off
	v_lshl_add_u64 v[212:213], v[218:219], 0, s[24:25]
	s_mov_b32 m0, s63
	s_nop 0
	global_load_lds_dwordx4 v[212:213], off
	s_waitcnt vmcnt(8)
	s_waitcnt lgkmcnt(0)
	s_barrier
	s_setprio 1
	s_waitcnt lgkmcnt(0)
	v_mfma_f32_16x16x32_bf16 v[60:63], v[146:149], v[180:183], v[60:63]
	v_mfma_f32_16x16x32_bf16 v[60:63], v[150:153], v[184:187], v[60:63]
	v_mfma_f32_16x16x32_bf16 v[56:59], v[154:157], v[180:183], v[56:59]
	v_mfma_f32_16x16x32_bf16 v[56:59], v[158:161], v[184:187], v[56:59]
	v_mfma_f32_16x16x32_bf16 v[52:55], v[146:149], v[188:191], v[52:55]
	v_mfma_f32_16x16x32_bf16 v[52:55], v[150:153], v[192:195], v[52:55]
	v_mfma_f32_16x16x32_bf16 v[48:51], v[154:157], v[188:191], v[48:51]
	v_mfma_f32_16x16x32_bf16 v[48:51], v[158:161], v[192:195], v[48:51]
	v_mfma_f32_16x16x32_bf16 v[36:39], v[146:149], v[196:199], v[36:39]
	v_mfma_f32_16x16x32_bf16 v[36:39], v[150:153], v[200:203], v[36:39]
	v_mfma_f32_16x16x32_bf16 v[32:35], v[154:157], v[196:199], v[32:35]
	v_mfma_f32_16x16x32_bf16 v[32:35], v[158:161], v[200:203], v[32:35]
	v_mfma_f32_16x16x32_bf16 v[20:23], v[146:149], v[204:207], v[20:23]
	v_mfma_f32_16x16x32_bf16 v[20:23], v[150:153], v[208:211], v[20:23]
	v_mfma_f32_16x16x32_bf16 v[16:19], v[154:157], v[204:207], v[16:19]
	v_mfma_f32_16x16x32_bf16 v[16:19], v[158:161], v[208:211], v[16:19]
	s_setprio 0
	s_setprio 1
	v_mfma_f32_16x16x32_bf16 v[44:47], v[162:165], v[180:183], v[44:47]
	v_mfma_f32_16x16x32_bf16 v[44:47], v[166:169], v[184:187], v[44:47]
	v_mfma_f32_16x16x32_bf16 v[40:43], v[170:173], v[180:183], v[40:43]
	v_mfma_f32_16x16x32_bf16 v[40:43], v[176:179], v[184:187], v[40:43]
	v_mfma_f32_16x16x32_bf16 v[28:31], v[162:165], v[188:191], v[28:31]
	v_mfma_f32_16x16x32_bf16 v[28:31], v[166:169], v[192:195], v[28:31]
	v_mfma_f32_16x16x32_bf16 v[24:27], v[170:173], v[188:191], v[24:27]
	v_mfma_f32_16x16x32_bf16 v[24:27], v[176:179], v[192:195], v[24:27]
	v_mfma_f32_16x16x32_bf16 v[12:15], v[162:165], v[196:199], v[12:15]
	v_mfma_f32_16x16x32_bf16 v[12:15], v[166:169], v[200:203], v[12:15]
	v_mfma_f32_16x16x32_bf16 v[8:11], v[170:173], v[196:199], v[8:11]
	v_mfma_f32_16x16x32_bf16 v[8:11], v[176:179], v[200:203], v[8:11]
	v_mfma_f32_16x16x32_bf16 v[4:7], v[162:165], v[204:207], v[4:7]
	v_mfma_f32_16x16x32_bf16 v[4:7], v[166:169], v[208:211], v[4:7]
	v_mfma_f32_16x16x32_bf16 v[0:3], v[170:173], v[204:207], v[0:3]
	v_mfma_f32_16x16x32_bf16 v[0:3], v[176:179], v[208:211], v[0:3]
	s_setprio 0
	s_barrier
	s_add_i32 s82, s82, 2
	s_add_u32 s44, s44, 0x100
	s_addc_u32 s45, s45, 0
	s_add_u32 s39, s39, 0x100
	s_addc_u32 s81, s81, 0
	s_cmp_gt_u32 s82, 5
	s_cbranch_scc0 .LBB0_414
	s_and_b64 vcc, exec, s[36:37]
	s_cbranch_vccz .LBB0_417
	s_barrier

.LBB0_428:
	ds_read_b128 v[148:151], v143
	ds_read_b128 v[152:155], v143 offset:1024
	ds_read_b128 v[156:159], v143 offset:2048
	ds_read_b128 v[160:163], v143 offset:3072
	ds_read_b128 v[164:167], v144
	ds_read_b128 v[168:171], v144 offset:1024
	ds_read_b128 v[176:179], v144 offset:2048
	ds_read_b128 v[180:183], v144 offset:3072
	s_add_u32 s48, s46, 0xfff80080
	s_addc_u32 s49, s47, -1
	s_cmp_eq_u32 s83, 4
	s_cselect_b32 s51, s77, s49
	s_cselect_b32 s50, s78, s48
	s_cselect_b32 s49, s79, s82
	s_cselect_b32 s48, s80, s81
	v_lshl_add_u64 v[172:173], s[46:47], 0, v[138:139]
	s_add_i32 m0, s15, 0xc000
	ds_read_b128 v[184:187], v145
	ds_read_b128 v[188:191], v145 offset:1024
	ds_read_b128 v[192:195], v145 offset:2048
	ds_read_b128 v[196:199], v145 offset:3072
	ds_read_b128 v[200:203], v145 offset:4096
	ds_read_b128 v[204:207], v145 offset:5120
	ds_read_b128 v[208:211], v145 offset:6144
	ds_read_b128 v[212:215], v145 offset:7168
	global_load_lds_dwordx4 v[172:173], off
	v_lshl_add_u64 v[172:173], s[46:47], 0, v[140:141]
	s_add_i32 m0, s15, 0xe000
	s_nop 0
	global_load_lds_dwordx4 v[172:173], off
	s_waitcnt vmcnt(8)
	s_waitcnt lgkmcnt(0)
	s_barrier
	s_setprio 1
	s_waitcnt lgkmcnt(0)
	v_mfma_f32_16x16x32_bf16 v[124:127], v[148:151], v[184:187], v[124:127]
	v_mfma_f32_16x16x32_bf16 v[124:127], v[152:155], v[188:191], v[124:127]
	v_mfma_f32_16x16x32_bf16 v[120:123], v[156:159], v[184:187], v[120:123]
	v_mfma_f32_16x16x32_bf16 v[120:123], v[160:163], v[188:191], v[120:123]
	v_mfma_f32_16x16x32_bf16 v[116:119], v[148:151], v[192:195], v[116:119]
	v_mfma_f32_16x16x32_bf16 v[116:119], v[152:155], v[196:199], v[116:119]
	v_mfma_f32_16x16x32_bf16 v[112:115], v[156:159], v[192:195], v[112:115]
	v_mfma_f32_16x16x32_bf16 v[112:115], v[160:163], v[196:199], v[112:115]
	v_mfma_f32_16x16x32_bf16 v[100:103], v[148:151], v[200:203], v[100:103]
	v_mfma_f32_16x16x32_bf16 v[100:103], v[152:155], v[204:207], v[100:103]
	v_mfma_f32_16x16x32_bf16 v[96:99], v[156:159], v[200:203], v[96:99]
	v_mfma_f32_16x16x32_bf16 v[96:99], v[160:163], v[204:207], v[96:99]
	v_mfma_f32_16x16x32_bf16 v[84:87], v[148:151], v[208:211], v[84:87]
	v_mfma_f32_16x16x32_bf16 v[84:87], v[152:155], v[212:215], v[84:87]
	v_mfma_f32_16x16x32_bf16 v[80:83], v[156:159], v[208:211], v[80:83]
	v_mfma_f32_16x16x32_bf16 v[80:83], v[160:163], v[212:215], v[80:83]
	s_setprio 0
	s_setprio 1
	v_mfma_f32_16x16x32_bf16 v[108:111], v[164:167], v[184:187], v[108:111]
	v_mfma_f32_16x16x32_bf16 v[108:111], v[168:171], v[188:191], v[108:111]
	v_mfma_f32_16x16x32_bf16 v[104:107], v[176:179], v[184:187], v[104:107]
	v_mfma_f32_16x16x32_bf16 v[104:107], v[180:183], v[188:191], v[104:107]
	v_mfma_f32_16x16x32_bf16 v[92:95], v[164:167], v[192:195], v[92:95]
	v_mfma_f32_16x16x32_bf16 v[92:95], v[168:171], v[196:199], v[92:95]
	v_mfma_f32_16x16x32_bf16 v[88:91], v[176:179], v[192:195], v[88:91]
	v_mfma_f32_16x16x32_bf16 v[88:91], v[180:183], v[196:199], v[88:91]
	v_mfma_f32_16x16x32_bf16 v[76:79], v[164:167], v[200:203], v[76:79]
	v_mfma_f32_16x16x32_bf16 v[76:79], v[168:171], v[204:207], v[76:79]
	v_mfma_f32_16x16x32_bf16 v[72:75], v[176:179], v[200:203], v[72:75]
	v_mfma_f32_16x16x32_bf16 v[72:75], v[180:183], v[204:207], v[72:75]
	v_mfma_f32_16x16x32_bf16 v[68:71], v[164:167], v[208:211], v[68:71]
	v_mfma_f32_16x16x32_bf16 v[68:71], v[168:171], v[212:215], v[68:71]
	v_mfma_f32_16x16x32_bf16 v[64:67], v[176:179], v[208:211], v[64:67]
	v_mfma_f32_16x16x32_bf16 v[64:67], v[180:183], v[212:215], v[64:67]
	s_setprio 0
	s_barrier
	s_add_i32 s84, s68, s10
	v_lshl_add_u64 v[172:173], s[48:49], 0, v[132:133]
	s_mov_b32 m0, s84
	ds_read_b128 v[184:187], v145 offset:16384
	ds_read_b128 v[188:191], v145 offset:17408
	ds_read_b128 v[192:195], v145 offset:18432
	ds_read_b128 v[196:199], v145 offset:19456
	ds_read_b128 v[200:203], v145 offset:20480
	ds_read_b128 v[204:207], v145 offset:21504
	ds_read_b128 v[208:211], v145 offset:22528
	ds_read_b128 v[212:215], v145 offset:23552
	global_load_lds_dwordx4 v[172:173], off
	s_add_i32 m0, s84, 0x2000
	s_add_u32 s84, s48, 0x80000
	v_lshl_add_u64 v[216:217], s[48:49], 0, v[128:129]
	s_addc_u32 s85, s49, 0
	s_add_i32 s86, s69, s10
	global_load_lds_dwordx4 v[216:217], off
	v_lshl_add_u64 v[218:219], s[84:85], 0, v[132:133]
	s_mov_b32 m0, s86
	v_lshl_add_u64 v[220:221], s[50:51], 0, v[130:131]
	global_load_lds_dwordx4 v[218:219], off
	v_lshl_add_u64 v[218:219], s[84:85], 0, v[128:129]
	s_add_i32 m0, s86, 0x2000
	s_nop 0
	global_load_lds_dwordx4 v[218:219], off
	v_lshl_add_u64 v[218:219], s[50:51], 0, v[134:135]
	s_mov_b32 m0, s15
	s_nop 0
	global_load_lds_dwordx4 v[218:219], off
	s_mov_b32 m0, s22
	s_nop 0
	global_load_lds_dwordx4 v[220:221], off
	s_waitcnt vmcnt(8)
	s_waitcnt lgkmcnt(0)
	s_barrier
	s_setprio 1
	s_waitcnt lgkmcnt(0)
	v_mfma_f32_16x16x32_bf16 v[60:63], v[148:151], v[184:187], v[60:63]
	v_mfma_f32_16x16x32_bf16 v[60:63], v[152:155], v[188:191], v[60:63]
	v_mfma_f32_16x16x32_bf16 v[56:59], v[156:159], v[184:187], v[56:59]
	v_mfma_f32_16x16x32_bf16 v[56:59], v[160:163], v[188:191], v[56:59]
	v_mfma_f32_16x16x32_bf16 v[52:55], v[148:151], v[192:195], v[52:55]
	v_mfma_f32_16x16x32_bf16 v[52:55], v[152:155], v[196:199], v[52:55]
	v_mfma_f32_16x16x32_bf16 v[48:51], v[156:159], v[192:195], v[48:51]
	v_mfma_f32_16x16x32_bf16 v[48:51], v[160:163], v[196:199], v[48:51]
	v_mfma_f32_16x16x32_bf16 v[36:39], v[148:151], v[200:203], v[36:39]
	v_mfma_f32_16x16x32_bf16 v[36:39], v[152:155], v[204:207], v[36:39]
	v_mfma_f32_16x16x32_bf16 v[32:35], v[156:159], v[200:203], v[32:35]
	v_mfma_f32_16x16x32_bf16 v[32:35], v[160:163], v[204:207], v[32:35]
	v_mfma_f32_16x16x32_bf16 v[20:23], v[148:151], v[208:211], v[20:23]
	v_mfma_f32_16x16x32_bf16 v[20:23], v[152:155], v[212:215], v[20:23]
	v_mfma_f32_16x16x32_bf16 v[16:19], v[156:159], v[208:211], v[16:19]
	v_mfma_f32_16x16x32_bf16 v[16:19], v[160:163], v[212:215], v[16:19]
	s_setprio 0
	s_setprio 1
	v_mfma_f32_16x16x32_bf16 v[44:47], v[164:167], v[184:187], v[44:47]
	v_mfma_f32_16x16x32_bf16 v[44:47], v[168:171], v[188:191], v[44:47]
	v_mfma_f32_16x16x32_bf16 v[40:43], v[176:179], v[184:187], v[40:43]
	v_mfma_f32_16x16x32_bf16 v[40:43], v[180:183], v[188:191], v[40:43]
	v_mfma_f32_16x16x32_bf16 v[28:31], v[164:167], v[192:195], v[28:31]
	v_mfma_f32_16x16x32_bf16 v[28:31], v[168:171], v[196:199], v[28:31]
	v_mfma_f32_16x16x32_bf16 v[24:27], v[176:179], v[192:195], v[24:27]
	v_mfma_f32_16x16x32_bf16 v[24:27], v[180:183], v[196:199], v[24:27]
	v_mfma_f32_16x16x32_bf16 v[12:15], v[164:167], v[200:203], v[12:15]
	v_mfma_f32_16x16x32_bf16 v[12:15], v[168:171], v[204:207], v[12:15]
	v_mfma_f32_16x16x32_bf16 v[8:11], v[176:179], v[200:203], v[8:11]
	v_mfma_f32_16x16x32_bf16 v[8:11], v[180:183], v[204:207], v[8:11]
	v_mfma_f32_16x16x32_bf16 v[4:7], v[164:167], v[208:211], v[4:7]
	v_mfma_f32_16x16x32_bf16 v[4:7], v[168:171], v[212:215], v[4:7]
	v_mfma_f32_16x16x32_bf16 v[0:3], v[176:179], v[208:211], v[0:3]
	v_mfma_f32_16x16x32_bf16 v[0:3], v[180:183], v[212:215], v[0:3]
	s_setprio 0
	s_barrier
	s_add_i32 s84, 0, 0x18000
	v_add_u32_e32 v136, s84, v142
	s_add_i32 s85, 0, 0x1c000
	ds_read_b128 v[148:151], v136
	ds_read_b128 v[152:155], v136 offset:1024
	ds_read_b128 v[156:159], v136 offset:2048
	ds_read_b128 v[160:163], v136 offset:3072
	v_add_u32_e32 v136, s85, v142
	ds_read_b128 v[164:167], v136
	ds_read_b128 v[168:171], v136 offset:1024
	ds_read_b128 v[176:179], v136 offset:2048
	ds_read_b128 v[180:183], v136 offset:3072
	s_add_u32 s50, s50, 0x80000
	s_addc_u32 s51, s51, 0
	s_mov_b32 m0, s23
	v_lshl_add_u64 v[222:223], s[50:51], 0, v[134:135]
	ds_read_b128 v[184:187], v145 offset:32768
	ds_read_b128 v[188:191], v145 offset:33792
	ds_read_b128 v[192:195], v145 offset:34816
	ds_read_b128 v[196:199], v145 offset:35840
	ds_read_b128 v[200:203], v145 offset:36864
	ds_read_b128 v[204:207], v145 offset:37888
	ds_read_b128 v[208:211], v145 offset:38912
	ds_read_b128 v[212:215], v145 offset:39936
	global_load_lds_dwordx4 v[222:223], off
	v_lshl_add_u64 v[222:223], s[50:51], 0, v[130:131]
	s_mov_b32 m0, s33
	s_nop 0
	global_load_lds_dwordx4 v[222:223], off
	s_waitcnt vmcnt(8)
	s_waitcnt lgkmcnt(0)
	s_barrier
	s_setprio 1
	s_waitcnt lgkmcnt(0)
	v_mfma_f32_16x16x32_bf16 v[124:127], v[148:151], v[184:187], v[124:127]
	v_mfma_f32_16x16x32_bf16 v[124:127], v[152:155], v[188:191], v[124:127]
	v_mfma_f32_16x16x32_bf16 v[120:123], v[156:159], v[184:187], v[120:123]
	v_mfma_f32_16x16x32_bf16 v[120:123], v[160:163], v[188:191], v[120:123]
	v_mfma_f32_16x16x32_bf16 v[116:119], v[148:151], v[192:195], v[116:119]
	v_mfma_f32_16x16x32_bf16 v[116:119], v[152:155], v[196:199], v[116:119]
	v_mfma_f32_16x16x32_bf16 v[112:115], v[156:159], v[192:195], v[112:115]
	v_mfma_f32_16x16x32_bf16 v[112:115], v[160:163], v[196:199], v[112:115]
	v_mfma_f32_16x16x32_bf16 v[100:103], v[148:151], v[200:203], v[100:103]
	v_mfma_f32_16x16x32_bf16 v[100:103], v[152:155], v[204:207], v[100:103]
	v_mfma_f32_16x16x32_bf16 v[96:99], v[156:159], v[200:203], v[96:99]
	v_mfma_f32_16x16x32_bf16 v[96:99], v[160:163], v[204:207], v[96:99]
	v_mfma_f32_16x16x32_bf16 v[84:87], v[148:151], v[208:211], v[84:87]
	v_mfma_f32_16x16x32_bf16 v[84:87], v[152:155], v[212:215], v[84:87]
	v_mfma_f32_16x16x32_bf16 v[80:83], v[156:159], v[208:211], v[80:83]
	v_mfma_f32_16x16x32_bf16 v[80:83], v[160:163], v[212:215], v[80:83]
	s_setprio 0
	s_setprio 1
	v_mfma_f32_16x16x32_bf16 v[108:111], v[164:167], v[184:187], v[108:111]
	v_mfma_f32_16x16x32_bf16 v[108:111], v[168:171], v[188:191], v[108:111]
	v_mfma_f32_16x16x32_bf16 v[104:107], v[176:179], v[184:187], v[104:107]
	v_mfma_f32_16x16x32_bf16 v[104:107], v[180:183], v[188:191], v[104:107]
	v_mfma_f32_16x16x32_bf16 v[92:95], v[164:167], v[192:195], v[92:95]
	v_mfma_f32_16x16x32_bf16 v[92:95], v[168:171], v[196:199], v[92:95]
	v_mfma_f32_16x16x32_bf16 v[88:91], v[176:179], v[192:195], v[88:91]
	v_mfma_f32_16x16x32_bf16 v[88:91], v[180:183], v[196:199], v[88:91]
	v_mfma_f32_16x16x32_bf16 v[76:79], v[164:167], v[200:203], v[76:79]
	v_mfma_f32_16x16x32_bf16 v[76:79], v[168:171], v[204:207], v[76:79]
	v_mfma_f32_16x16x32_bf16 v[72:75], v[176:179], v[200:203], v[72:75]
	v_mfma_f32_16x16x32_bf16 v[72:75], v[180:183], v[204:207], v[72:75]
	v_mfma_f32_16x16x32_bf16 v[68:71], v[164:167], v[208:211], v[68:71]
	v_mfma_f32_16x16x32_bf16 v[68:71], v[168:171], v[212:215], v[68:71]
	v_mfma_f32_16x16x32_bf16 v[64:67], v[176:179], v[208:211], v[64:67]
	v_mfma_f32_16x16x32_bf16 v[64:67], v[180:183], v[212:215], v[64:67]
	s_setprio 0
	s_barrier
	s_add_i32 s50, s84, s10
	v_lshl_add_u64 v[172:173], v[172:173], 0, s[38:39]
	s_mov_b32 m0, s50
	ds_read_b128 v[184:187], v145 offset:49152
	ds_read_b128 v[188:191], v145 offset:50176
	ds_read_b128 v[192:195], v145 offset:51200
	ds_read_b128 v[196:199], v145 offset:52224
	ds_read_b128 v[200:203], v145 offset:53248
	ds_read_b128 v[204:207], v145 offset:54272
	ds_read_b128 v[208:211], v145 offset:55296
	ds_read_b128 v[212:215], v145 offset:56320
	global_load_lds_dwordx4 v[172:173], off
	s_add_i32 m0, s50, 0x2000
	s_add_u32 s48, s48, 0x80080
	v_lshl_add_u64 v[172:173], v[216:217], 0, s[38:39]
	s_addc_u32 s49, s49, 0
	s_add_i32 s50, s85, s10
	global_load_lds_dwordx4 v[172:173], off
	v_lshl_add_u64 v[172:173], s[48:49], 0, v[132:133]
	s_mov_b32 m0, s50
	s_nop 0
	global_load_lds_dwordx4 v[172:173], off
	v_lshl_add_u64 v[172:173], s[48:49], 0, v[128:129]
	s_add_i32 m0, s50, 0x2000
	s_nop 0
	global_load_lds_dwordx4 v[172:173], off
	v_lshl_add_u64 v[172:173], v[218:219], 0, s[38:39]
	s_mov_b32 m0, s64
	s_nop 0
	global_load_lds_dwordx4 v[172:173], off
	v_lshl_add_u64 v[172:173], v[220:221], 0, s[38:39]
	s_mov_b32 m0, s65
	s_nop 0
	global_load_lds_dwordx4 v[172:173], off
	s_waitcnt vmcnt(8)
	s_waitcnt lgkmcnt(0)
	s_barrier
	s_setprio 1
	s_waitcnt lgkmcnt(0)
	v_mfma_f32_16x16x32_bf16 v[60:63], v[148:151], v[184:187], v[60:63]
	v_mfma_f32_16x16x32_bf16 v[60:63], v[152:155], v[188:191], v[60:63]
	v_mfma_f32_16x16x32_bf16 v[56:59], v[156:159], v[184:187], v[56:59]
	v_mfma_f32_16x16x32_bf16 v[56:59], v[160:163], v[188:191], v[56:59]
	v_mfma_f32_16x16x32_bf16 v[52:55], v[148:151], v[192:195], v[52:55]
	v_mfma_f32_16x16x32_bf16 v[52:55], v[152:155], v[196:199], v[52:55]
	v_mfma_f32_16x16x32_bf16 v[48:51], v[156:159], v[192:195], v[48:51]
	v_mfma_f32_16x16x32_bf16 v[48:51], v[160:163], v[196:199], v[48:51]
	v_mfma_f32_16x16x32_bf16 v[36:39], v[148:151], v[200:203], v[36:39]
	v_mfma_f32_16x16x32_bf16 v[36:39], v[152:155], v[204:207], v[36:39]
	v_mfma_f32_16x16x32_bf16 v[32:35], v[156:159], v[200:203], v[32:35]
	v_mfma_f32_16x16x32_bf16 v[32:35], v[160:163], v[204:207], v[32:35]
	v_mfma_f32_16x16x32_bf16 v[20:23], v[148:151], v[208:211], v[20:23]
	v_mfma_f32_16x16x32_bf16 v[20:23], v[152:155], v[212:215], v[20:23]
	v_mfma_f32_16x16x32_bf16 v[16:19], v[156:159], v[208:211], v[16:19]
	v_mfma_f32_16x16x32_bf16 v[16:19], v[160:163], v[212:215], v[16:19]
	s_setprio 0
	s_setprio 1
	v_mfma_f32_16x16x32_bf16 v[44:47], v[164:167], v[184:187], v[44:47]
	v_mfma_f32_16x16x32_bf16 v[44:47], v[168:171], v[188:191], v[44:47]
	v_mfma_f32_16x16x32_bf16 v[40:43], v[176:179], v[184:187], v[40:43]
	v_mfma_f32_16x16x32_bf16 v[40:43], v[180:183], v[188:191], v[40:43]
	v_mfma_f32_16x16x32_bf16 v[28:31], v[164:167], v[192:195], v[28:31]
	v_mfma_f32_16x16x32_bf16 v[28:31], v[168:171], v[196:199], v[28:31]
	v_mfma_f32_16x16x32_bf16 v[24:27], v[176:179], v[192:195], v[24:27]
	v_mfma_f32_16x16x32_bf16 v[24:27], v[180:183], v[196:199], v[24:27]
	v_mfma_f32_16x16x32_bf16 v[12:15], v[164:167], v[200:203], v[12:15]
	v_mfma_f32_16x16x32_bf16 v[12:15], v[168:171], v[204:207], v[12:15]
	v_mfma_f32_16x16x32_bf16 v[8:11], v[176:179], v[200:203], v[8:11]
	v_mfma_f32_16x16x32_bf16 v[8:11], v[180:183], v[204:207], v[8:11]
	v_mfma_f32_16x16x32_bf16 v[4:7], v[164:167], v[208:211], v[4:7]
	v_mfma_f32_16x16x32_bf16 v[4:7], v[168:171], v[212:215], v[4:7]
	v_mfma_f32_16x16x32_bf16 v[0:3], v[176:179], v[208:211], v[0:3]
	v_mfma_f32_16x16x32_bf16 v[0:3], v[180:183], v[212:215], v[0:3]
	s_setprio 0
	s_barrier
	s_add_i32 s83, s83, 2
	s_add_u32 s46, s46, 0x100
	s_addc_u32 s47, s47, 0
	s_add_u32 s81, s81, 0x100
	s_addc_u32 s82, s82, 0
	s_cmp_gt_u32 s83, 5
	s_cbranch_scc0 .LBB0_428
	s_and_b64 vcc, exec, s[40:41]
	s_cbranch_vccz .LBB0_431
	s_barrier

.LBB0_502:
	ds_read_b128 v[128:131], v192
	ds_read_b128 v[132:135], v192 offset:1024
	ds_read_b128 v[136:139], v192 offset:2048
	ds_read_b128 v[140:143], v192 offset:3072
	ds_read_b128 v[144:147], v193
	ds_read_b128 v[148:151], v193 offset:1024
	ds_read_b128 v[168:171], v193 offset:2048
	ds_read_b128 v[196:199], v193 offset:3072
	s_add_u32 s62, s60, 0xfff80080
	s_addc_u32 s63, s61, -1
	s_cmp_eq_u32 s76, 28
	s_cselect_b32 s65, s27, s63
	s_cselect_b32 s64, s45, s62
	s_cselect_b32 s63, s43, s75
	s_cselect_b32 s62, s51, s74
	v_lshl_add_u64 v[172:173], s[60:61], 0, v[160:161]
	s_add_i32 m0, s1, 0xc000
	ds_read_b128 v[200:203], v194
	ds_read_b128 v[204:207], v194 offset:1024
	ds_read_b128 v[208:211], v194 offset:2048
	ds_read_b128 v[212:215], v194 offset:3072
	ds_read_b128 v[216:219], v194 offset:4096
	ds_read_b128 v[220:223], v194 offset:5120
	ds_read_b128 v[224:227], v194 offset:6144
	ds_read_b128 v[228:231], v194 offset:7168
	global_load_lds_dwordx4 v[172:173], off
	v_lshl_add_u64 v[172:173], s[60:61], 0, v[162:163]
	s_add_i32 m0, s1, 0xe000
	s_nop 0
	global_load_lds_dwordx4 v[172:173], off
	s_waitcnt vmcnt(8)
	s_waitcnt lgkmcnt(0)
	s_barrier
	s_setprio 1
	s_waitcnt lgkmcnt(0)
	v_mfma_f32_16x16x32_bf16 v[124:127], v[128:131], v[200:203], v[124:127]
	v_mfma_f32_16x16x32_bf16 v[124:127], v[132:135], v[204:207], v[124:127]
	v_mfma_f32_16x16x32_bf16 v[120:123], v[136:139], v[200:203], v[120:123]
	v_mfma_f32_16x16x32_bf16 v[120:123], v[140:143], v[204:207], v[120:123]
	v_mfma_f32_16x16x32_bf16 v[108:111], v[128:131], v[208:211], v[108:111]
	v_mfma_f32_16x16x32_bf16 v[108:111], v[132:135], v[212:215], v[108:111]
	v_mfma_f32_16x16x32_bf16 v[104:107], v[136:139], v[208:211], v[104:107]
	v_mfma_f32_16x16x32_bf16 v[104:107], v[140:143], v[212:215], v[104:107]
	v_mfma_f32_16x16x32_bf16 v[92:95], v[128:131], v[216:219], v[92:95]
	v_mfma_f32_16x16x32_bf16 v[92:95], v[132:135], v[220:223], v[92:95]
	v_mfma_f32_16x16x32_bf16 v[88:91], v[136:139], v[216:219], v[88:91]
	v_mfma_f32_16x16x32_bf16 v[88:91], v[140:143], v[220:223], v[88:91]
	v_mfma_f32_16x16x32_bf16 v[76:79], v[128:131], v[224:227], v[76:79]
	v_mfma_f32_16x16x32_bf16 v[76:79], v[132:135], v[228:231], v[76:79]
	v_mfma_f32_16x16x32_bf16 v[72:75], v[136:139], v[224:227], v[72:75]
	v_mfma_f32_16x16x32_bf16 v[72:75], v[140:143], v[228:231], v[72:75]
	s_setprio 0
	s_setprio 1
	v_mfma_f32_16x16x32_bf16 v[116:119], v[144:147], v[200:203], v[116:119]
	v_mfma_f32_16x16x32_bf16 v[116:119], v[148:151], v[204:207], v[116:119]
	v_mfma_f32_16x16x32_bf16 v[112:115], v[168:171], v[200:203], v[112:115]
	v_mfma_f32_16x16x32_bf16 v[112:115], v[196:199], v[204:207], v[112:115]
	v_mfma_f32_16x16x32_bf16 v[100:103], v[144:147], v[208:211], v[100:103]
	v_mfma_f32_16x16x32_bf16 v[100:103], v[148:151], v[212:215], v[100:103]
	v_mfma_f32_16x16x32_bf16 v[96:99], v[168:171], v[208:211], v[96:99]
	v_mfma_f32_16x16x32_bf16 v[96:99], v[196:199], v[212:215], v[96:99]
	v_mfma_f32_16x16x32_bf16 v[84:87], v[144:147], v[216:219], v[84:87]
	v_mfma_f32_16x16x32_bf16 v[84:87], v[148:151], v[220:223], v[84:87]
	v_mfma_f32_16x16x32_bf16 v[80:83], v[168:171], v[216:219], v[80:83]
	v_mfma_f32_16x16x32_bf16 v[80:83], v[196:199], v[220:223], v[80:83]
	v_mfma_f32_16x16x32_bf16 v[68:71], v[144:147], v[224:227], v[68:71]
	v_mfma_f32_16x16x32_bf16 v[68:71], v[148:151], v[228:231], v[68:71]
	v_mfma_f32_16x16x32_bf16 v[64:67], v[168:171], v[224:227], v[64:67]
	v_mfma_f32_16x16x32_bf16 v[64:67], v[196:199], v[228:231], v[64:67]
	s_setprio 0
	s_barrier
	s_add_i32 s77, s69, s0
	v_lshl_add_u64 v[172:173], s[62:63], 0, v[154:155]
	s_mov_b32 m0, s77
	ds_read_b128 v[200:203], v194 offset:16384
	ds_read_b128 v[204:207], v194 offset:17408
	ds_read_b128 v[208:211], v194 offset:18432
	ds_read_b128 v[212:215], v194 offset:19456
	ds_read_b128 v[216:219], v194 offset:20480
	ds_read_b128 v[220:223], v194 offset:21504
	ds_read_b128 v[224:227], v194 offset:22528
	ds_read_b128 v[228:231], v194 offset:23552
	global_load_lds_dwordx4 v[172:173], off
	s_add_i32 m0, s77, 0x2000
	s_add_u32 s78, s62, 0x80000
	v_lshl_add_u64 v[232:233], s[62:63], 0, v[158:159]
	s_addc_u32 s79, s63, 0
	s_add_i32 s77, s73, s0
	global_load_lds_dwordx4 v[232:233], off
	v_lshl_add_u64 v[234:235], s[78:79], 0, v[154:155]
	s_mov_b32 m0, s77
	v_lshl_add_u64 v[236:237], s[64:65], 0, v[156:157]
	global_load_lds_dwordx4 v[234:235], off
	v_lshl_add_u64 v[234:235], s[78:79], 0, v[158:159]
	s_add_i32 m0, s77, 0x2000
	s_nop 0
	global_load_lds_dwordx4 v[234:235], off
	v_lshl_add_u64 v[234:235], s[64:65], 0, v[152:153]
	s_mov_b32 m0, s1
	s_nop 0
	global_load_lds_dwordx4 v[234:235], off
	s_mov_b32 m0, s10
	s_nop 0
	global_load_lds_dwordx4 v[236:237], off
	s_waitcnt vmcnt(8)
	s_waitcnt lgkmcnt(0)
	s_barrier
	s_setprio 1
	s_waitcnt lgkmcnt(0)
	v_mfma_f32_16x16x32_bf16 v[60:63], v[128:131], v[200:203], v[60:63]
	v_mfma_f32_16x16x32_bf16 v[60:63], v[132:135], v[204:207], v[60:63]
	v_mfma_f32_16x16x32_bf16 v[56:59], v[136:139], v[200:203], v[56:59]
	v_mfma_f32_16x16x32_bf16 v[56:59], v[140:143], v[204:207], v[56:59]
	v_mfma_f32_16x16x32_bf16 v[44:47], v[128:131], v[208:211], v[44:47]
	v_mfma_f32_16x16x32_bf16 v[44:47], v[132:135], v[212:215], v[44:47]
	v_mfma_f32_16x16x32_bf16 v[40:43], v[136:139], v[208:211], v[40:43]
	v_mfma_f32_16x16x32_bf16 v[40:43], v[140:143], v[212:215], v[40:43]
	v_mfma_f32_16x16x32_bf16 v[28:31], v[128:131], v[216:219], v[28:31]
	v_mfma_f32_16x16x32_bf16 v[28:31], v[132:135], v[220:223], v[28:31]
	v_mfma_f32_16x16x32_bf16 v[24:27], v[136:139], v[216:219], v[24:27]
	v_mfma_f32_16x16x32_bf16 v[24:27], v[140:143], v[220:223], v[24:27]
	v_mfma_f32_16x16x32_bf16 v[12:15], v[128:131], v[224:227], v[12:15]
	v_mfma_f32_16x16x32_bf16 v[12:15], v[132:135], v[228:231], v[12:15]
	v_mfma_f32_16x16x32_bf16 v[8:11], v[136:139], v[224:227], v[8:11]
	v_mfma_f32_16x16x32_bf16 v[8:11], v[140:143], v[228:231], v[8:11]
	s_setprio 0
	s_setprio 1
	v_mfma_f32_16x16x32_bf16 v[52:55], v[144:147], v[200:203], v[52:55]
	v_mfma_f32_16x16x32_bf16 v[52:55], v[148:151], v[204:207], v[52:55]
	v_mfma_f32_16x16x32_bf16 v[48:51], v[168:171], v[200:203], v[48:51]
	v_mfma_f32_16x16x32_bf16 v[48:51], v[196:199], v[204:207], v[48:51]
	v_mfma_f32_16x16x32_bf16 v[36:39], v[144:147], v[208:211], v[36:39]
	v_mfma_f32_16x16x32_bf16 v[36:39], v[148:151], v[212:215], v[36:39]
	v_mfma_f32_16x16x32_bf16 v[32:35], v[168:171], v[208:211], v[32:35]
	v_mfma_f32_16x16x32_bf16 v[32:35], v[196:199], v[212:215], v[32:35]
	v_mfma_f32_16x16x32_bf16 v[20:23], v[144:147], v[216:219], v[20:23]
	v_mfma_f32_16x16x32_bf16 v[20:23], v[148:151], v[220:223], v[20:23]
	v_mfma_f32_16x16x32_bf16 v[16:19], v[168:171], v[216:219], v[16:19]
	v_mfma_f32_16x16x32_bf16 v[16:19], v[196:199], v[220:223], v[16:19]
	v_mfma_f32_16x16x32_bf16 v[4:7], v[144:147], v[224:227], v[4:7]
	v_mfma_f32_16x16x32_bf16 v[4:7], v[148:151], v[228:231], v[4:7]
	v_mfma_f32_16x16x32_bf16 v[0:3], v[168:171], v[224:227], v[0:3]
	v_mfma_f32_16x16x32_bf16 v[0:3], v[196:199], v[228:231], v[0:3]
	s_setprio 0
	s_barrier
	s_add_i32 s77, 0, 0x18000
	s_add_i32 s78, 0, 0x1c000
	v_add_u32_e32 v140, s77, v177
	v_add_u32_e32 v196, s78, v177
	ds_read_b128 v[128:131], v140
	ds_read_b128 v[132:135], v140 offset:1024
	ds_read_b128 v[136:139], v140 offset:2048
	ds_read_b128 v[140:143], v140 offset:3072
	ds_read_b128 v[144:147], v196
	ds_read_b128 v[148:151], v196 offset:1024
	ds_read_b128 v[168:171], v196 offset:2048
	ds_read_b128 v[196:199], v196 offset:3072
	s_add_u32 s64, s64, 0x80000
	s_addc_u32 s65, s65, 0
	s_mov_b32 m0, s11
	v_lshl_add_u64 v[238:239], s[64:65], 0, v[152:153]
	ds_read_b128 v[200:203], v194 offset:32768
	ds_read_b128 v[204:207], v194 offset:33792
	ds_read_b128 v[208:211], v194 offset:34816
	ds_read_b128 v[212:215], v194 offset:35840
	ds_read_b128 v[216:219], v194 offset:36864
	ds_read_b128 v[220:223], v194 offset:37888
	ds_read_b128 v[224:227], v194 offset:38912
	ds_read_b128 v[228:231], v194 offset:39936
	global_load_lds_dwordx4 v[238:239], off
	v_lshl_add_u64 v[238:239], s[64:65], 0, v[156:157]
	s_mov_b32 m0, s14
	s_nop 0
	global_load_lds_dwordx4 v[238:239], off
	s_waitcnt vmcnt(8)
	s_waitcnt lgkmcnt(0)
	s_barrier
	s_setprio 1
	s_waitcnt lgkmcnt(0)
	v_mfma_f32_16x16x32_bf16 v[124:127], v[128:131], v[200:203], v[124:127]
	v_mfma_f32_16x16x32_bf16 v[124:127], v[132:135], v[204:207], v[124:127]
	v_mfma_f32_16x16x32_bf16 v[120:123], v[136:139], v[200:203], v[120:123]
	v_mfma_f32_16x16x32_bf16 v[120:123], v[140:143], v[204:207], v[120:123]
	v_mfma_f32_16x16x32_bf16 v[108:111], v[128:131], v[208:211], v[108:111]
	v_mfma_f32_16x16x32_bf16 v[108:111], v[132:135], v[212:215], v[108:111]
	v_mfma_f32_16x16x32_bf16 v[104:107], v[136:139], v[208:211], v[104:107]
	v_mfma_f32_16x16x32_bf16 v[104:107], v[140:143], v[212:215], v[104:107]
	v_mfma_f32_16x16x32_bf16 v[92:95], v[128:131], v[216:219], v[92:95]
	v_mfma_f32_16x16x32_bf16 v[92:95], v[132:135], v[220:223], v[92:95]
	v_mfma_f32_16x16x32_bf16 v[88:91], v[136:139], v[216:219], v[88:91]
	v_mfma_f32_16x16x32_bf16 v[88:91], v[140:143], v[220:223], v[88:91]
	v_mfma_f32_16x16x32_bf16 v[76:79], v[128:131], v[224:227], v[76:79]
	v_mfma_f32_16x16x32_bf16 v[76:79], v[132:135], v[228:231], v[76:79]
	v_mfma_f32_16x16x32_bf16 v[72:75], v[136:139], v[224:227], v[72:75]
	v_mfma_f32_16x16x32_bf16 v[72:75], v[140:143], v[228:231], v[72:75]
	s_setprio 0
	s_setprio 1
	v_mfma_f32_16x16x32_bf16 v[116:119], v[144:147], v[200:203], v[116:119]
	v_mfma_f32_16x16x32_bf16 v[116:119], v[148:151], v[204:207], v[116:119]
	v_mfma_f32_16x16x32_bf16 v[112:115], v[168:171], v[200:203], v[112:115]
	v_mfma_f32_16x16x32_bf16 v[112:115], v[196:199], v[204:207], v[112:115]
	v_mfma_f32_16x16x32_bf16 v[100:103], v[144:147], v[208:211], v[100:103]
	v_mfma_f32_16x16x32_bf16 v[100:103], v[148:151], v[212:215], v[100:103]
	v_mfma_f32_16x16x32_bf16 v[96:99], v[168:171], v[208:211], v[96:99]
	v_mfma_f32_16x16x32_bf16 v[96:99], v[196:199], v[212:215], v[96:99]
	v_mfma_f32_16x16x32_bf16 v[84:87], v[144:147], v[216:219], v[84:87]
	v_mfma_f32_16x16x32_bf16 v[84:87], v[148:151], v[220:223], v[84:87]
	v_mfma_f32_16x16x32_bf16 v[80:83], v[168:171], v[216:219], v[80:83]
	v_mfma_f32_16x16x32_bf16 v[80:83], v[196:199], v[220:223], v[80:83]
	v_mfma_f32_16x16x32_bf16 v[68:71], v[144:147], v[224:227], v[68:71]
	v_mfma_f32_16x16x32_bf16 v[68:71], v[148:151], v[228:231], v[68:71]
	v_mfma_f32_16x16x32_bf16 v[64:67], v[168:171], v[224:227], v[64:67]
	v_mfma_f32_16x16x32_bf16 v[64:67], v[196:199], v[228:231], v[64:67]
	s_setprio 0
	s_barrier
	s_add_i32 s64, s77, s0
	v_lshl_add_u64 v[172:173], v[172:173], 0, s[38:39]
	s_mov_b32 m0, s64
	ds_read_b128 v[200:203], v194 offset:49152
	ds_read_b128 v[204:207], v194 offset:50176
	ds_read_b128 v[208:211], v194 offset:51200
	ds_read_b128 v[212:215], v194 offset:52224
	ds_read_b128 v[216:219], v194 offset:53248
	ds_read_b128 v[220:223], v194 offset:54272
	ds_read_b128 v[224:227], v194 offset:55296
	ds_read_b128 v[228:231], v194 offset:56320
	global_load_lds_dwordx4 v[172:173], off
	s_add_i32 m0, s64, 0x2000
	s_add_u32 s62, s62, 0x80080
	v_lshl_add_u64 v[172:173], v[232:233], 0, s[38:39]
	s_addc_u32 s63, s63, 0
	s_add_i32 s64, s78, s0
	global_load_lds_dwordx4 v[172:173], off
	v_lshl_add_u64 v[172:173], s[62:63], 0, v[154:155]
	s_mov_b32 m0, s64
	s_nop 0
	global_load_lds_dwordx4 v[172:173], off
	v_lshl_add_u64 v[172:173], s[62:63], 0, v[158:159]
	s_add_i32 m0, s64, 0x2000
	s_nop 0
	global_load_lds_dwordx4 v[172:173], off
	v_lshl_add_u64 v[172:173], v[234:235], 0, s[38:39]
	s_mov_b32 m0, s33
	s_nop 0
	global_load_lds_dwordx4 v[172:173], off
	v_lshl_add_u64 v[172:173], v[236:237], 0, s[38:39]
	s_mov_b32 m0, s68
	s_nop 0
	global_load_lds_dwordx4 v[172:173], off
	s_waitcnt vmcnt(8)
	s_waitcnt lgkmcnt(0)
	s_barrier
	s_setprio 1
	s_waitcnt lgkmcnt(0)
	v_mfma_f32_16x16x32_bf16 v[60:63], v[128:131], v[200:203], v[60:63]
	v_mfma_f32_16x16x32_bf16 v[60:63], v[132:135], v[204:207], v[60:63]
	v_mfma_f32_16x16x32_bf16 v[56:59], v[136:139], v[200:203], v[56:59]
	v_mfma_f32_16x16x32_bf16 v[56:59], v[140:143], v[204:207], v[56:59]
	v_mfma_f32_16x16x32_bf16 v[44:47], v[128:131], v[208:211], v[44:47]
	v_mfma_f32_16x16x32_bf16 v[44:47], v[132:135], v[212:215], v[44:47]
	v_mfma_f32_16x16x32_bf16 v[40:43], v[136:139], v[208:211], v[40:43]
	v_mfma_f32_16x16x32_bf16 v[40:43], v[140:143], v[212:215], v[40:43]
	v_mfma_f32_16x16x32_bf16 v[28:31], v[128:131], v[216:219], v[28:31]
	v_mfma_f32_16x16x32_bf16 v[28:31], v[132:135], v[220:223], v[28:31]
	v_mfma_f32_16x16x32_bf16 v[24:27], v[136:139], v[216:219], v[24:27]
	v_mfma_f32_16x16x32_bf16 v[24:27], v[140:143], v[220:223], v[24:27]
	v_mfma_f32_16x16x32_bf16 v[12:15], v[128:131], v[224:227], v[12:15]
	v_mfma_f32_16x16x32_bf16 v[12:15], v[132:135], v[228:231], v[12:15]
	v_mfma_f32_16x16x32_bf16 v[8:11], v[136:139], v[224:227], v[8:11]
	v_mfma_f32_16x16x32_bf16 v[8:11], v[140:143], v[228:231], v[8:11]
	s_setprio 0
	s_setprio 1
	v_mfma_f32_16x16x32_bf16 v[52:55], v[144:147], v[200:203], v[52:55]
	v_mfma_f32_16x16x32_bf16 v[52:55], v[148:151], v[204:207], v[52:55]
	v_mfma_f32_16x16x32_bf16 v[48:51], v[168:171], v[200:203], v[48:51]
	v_mfma_f32_16x16x32_bf16 v[48:51], v[196:199], v[204:207], v[48:51]
	v_mfma_f32_16x16x32_bf16 v[36:39], v[144:147], v[208:211], v[36:39]
	v_mfma_f32_16x16x32_bf16 v[36:39], v[148:151], v[212:215], v[36:39]
	v_mfma_f32_16x16x32_bf16 v[32:35], v[168:171], v[208:211], v[32:35]
	v_mfma_f32_16x16x32_bf16 v[32:35], v[196:199], v[212:215], v[32:35]
	v_mfma_f32_16x16x32_bf16 v[20:23], v[144:147], v[216:219], v[20:23]
	v_mfma_f32_16x16x32_bf16 v[20:23], v[148:151], v[220:223], v[20:23]
	v_mfma_f32_16x16x32_bf16 v[16:19], v[168:171], v[216:219], v[16:19]
	v_mfma_f32_16x16x32_bf16 v[16:19], v[196:199], v[220:223], v[16:19]
	v_mfma_f32_16x16x32_bf16 v[4:7], v[144:147], v[224:227], v[4:7]
	v_mfma_f32_16x16x32_bf16 v[4:7], v[148:151], v[228:231], v[4:7]
	v_mfma_f32_16x16x32_bf16 v[0:3], v[168:171], v[224:227], v[0:3]
	v_mfma_f32_16x16x32_bf16 v[0:3], v[196:199], v[228:231], v[0:3]
	s_setprio 0
	s_barrier
	s_add_i32 s76, s76, 2
	s_add_u32 s60, s60, 0x100
	s_addc_u32 s61, s61, 0
	s_add_u32 s74, s74, 0x100
	s_addc_u32 s75, s75, 0
	s_cmp_gt_u32 s76, 29
	s_cbranch_scc0 .LBB0_502
	s_and_b64 vcc, exec, s[40:41]
	s_cbranch_vccz .LBB0_505
	s_barrier

.LBB0_596:
	ds_read_b128 v[142:145], v159
	ds_read_b128 v[146:149], v159 offset:1024
	ds_read_b128 v[150:153], v159 offset:2048
	ds_read_b128 v[154:157], v159 offset:3072
	ds_read_b128 v[166:169], v160
	ds_read_b128 v[170:173], v160 offset:1024
	ds_read_b128 v[176:179], v160 offset:2048
	ds_read_b128 v[180:183], v160 offset:3072
	s_add_u32 s50, s48, 0xfff80080
	s_addc_u32 s51, s49, -1
	s_cmp_eq_u32 s76, 28
	s_cselect_b32 s61, s39, s51
	s_cselect_b32 s60, s47, s50
	s_cselect_b32 s51, s72, s75
	s_cselect_b32 s50, s73, s74
	v_lshl_add_u64 v[216:217], s[48:49], 0, v[138:139]
	s_add_i32 m0, s1, 0xc000
	ds_read_b128 v[184:187], v161
	ds_read_b128 v[188:191], v161 offset:1024
	ds_read_b128 v[192:195], v161 offset:2048
	ds_read_b128 v[196:199], v161 offset:3072
	ds_read_b128 v[200:203], v161 offset:4096
	ds_read_b128 v[204:207], v161 offset:5120
	ds_read_b128 v[208:211], v161 offset:6144
	ds_read_b128 v[212:215], v161 offset:7168
	global_load_lds_dwordx4 v[216:217], off
	v_lshl_add_u64 v[216:217], s[48:49], 0, v[140:141]
	s_add_i32 m0, s1, 0xe000
	s_nop 0
	global_load_lds_dwordx4 v[216:217], off
	s_waitcnt vmcnt(8)
	s_waitcnt lgkmcnt(0)
	s_barrier
	s_setprio 1
	s_waitcnt lgkmcnt(0)
	v_mfma_f32_16x16x32_bf16 v[124:127], v[142:145], v[184:187], v[124:127]
	v_mfma_f32_16x16x32_bf16 v[124:127], v[146:149], v[188:191], v[124:127]
	v_mfma_f32_16x16x32_bf16 v[120:123], v[150:153], v[184:187], v[120:123]
	v_mfma_f32_16x16x32_bf16 v[120:123], v[154:157], v[188:191], v[120:123]
	v_mfma_f32_16x16x32_bf16 v[108:111], v[142:145], v[192:195], v[108:111]
	v_mfma_f32_16x16x32_bf16 v[108:111], v[146:149], v[196:199], v[108:111]
	v_mfma_f32_16x16x32_bf16 v[104:107], v[150:153], v[192:195], v[104:107]
	v_mfma_f32_16x16x32_bf16 v[104:107], v[154:157], v[196:199], v[104:107]
	v_mfma_f32_16x16x32_bf16 v[92:95], v[142:145], v[200:203], v[92:95]
	v_mfma_f32_16x16x32_bf16 v[92:95], v[146:149], v[204:207], v[92:95]
	v_mfma_f32_16x16x32_bf16 v[88:91], v[150:153], v[200:203], v[88:91]
	v_mfma_f32_16x16x32_bf16 v[88:91], v[154:157], v[204:207], v[88:91]
	v_mfma_f32_16x16x32_bf16 v[76:79], v[142:145], v[208:211], v[76:79]
	v_mfma_f32_16x16x32_bf16 v[76:79], v[146:149], v[212:215], v[76:79]
	v_mfma_f32_16x16x32_bf16 v[72:75], v[150:153], v[208:211], v[72:75]
	v_mfma_f32_16x16x32_bf16 v[72:75], v[154:157], v[212:215], v[72:75]
	s_setprio 0
	s_setprio 1
	v_mfma_f32_16x16x32_bf16 v[116:119], v[166:169], v[184:187], v[116:119]
	v_mfma_f32_16x16x32_bf16 v[116:119], v[170:173], v[188:191], v[116:119]
	v_mfma_f32_16x16x32_bf16 v[112:115], v[176:179], v[184:187], v[112:115]
	v_mfma_f32_16x16x32_bf16 v[112:115], v[180:183], v[188:191], v[112:115]
	v_mfma_f32_16x16x32_bf16 v[100:103], v[166:169], v[192:195], v[100:103]
	v_mfma_f32_16x16x32_bf16 v[100:103], v[170:173], v[196:199], v[100:103]
	v_mfma_f32_16x16x32_bf16 v[96:99], v[176:179], v[192:195], v[96:99]
	v_mfma_f32_16x16x32_bf16 v[96:99], v[180:183], v[196:199], v[96:99]
	v_mfma_f32_16x16x32_bf16 v[84:87], v[166:169], v[200:203], v[84:87]
	v_mfma_f32_16x16x32_bf16 v[84:87], v[170:173], v[204:207], v[84:87]
	v_mfma_f32_16x16x32_bf16 v[80:83], v[176:179], v[200:203], v[80:83]
	v_mfma_f32_16x16x32_bf16 v[80:83], v[180:183], v[204:207], v[80:83]
	v_mfma_f32_16x16x32_bf16 v[68:71], v[166:169], v[208:211], v[68:71]
	v_mfma_f32_16x16x32_bf16 v[68:71], v[170:173], v[212:215], v[68:71]
	v_mfma_f32_16x16x32_bf16 v[64:67], v[176:179], v[208:211], v[64:67]
	v_mfma_f32_16x16x32_bf16 v[64:67], v[180:183], v[212:215], v[64:67]
	s_setprio 0
	s_barrier
	s_add_i32 s77, s64, s0
	v_lshl_add_u64 v[216:217], s[50:51], 0, v[130:131]
	s_mov_b32 m0, s77
	ds_read_b128 v[184:187], v161 offset:16384
	ds_read_b128 v[188:191], v161 offset:17408
	ds_read_b128 v[192:195], v161 offset:18432
	ds_read_b128 v[196:199], v161 offset:19456
	ds_read_b128 v[200:203], v161 offset:20480
	ds_read_b128 v[204:207], v161 offset:21504
	ds_read_b128 v[208:211], v161 offset:22528
	ds_read_b128 v[212:215], v161 offset:23552
	global_load_lds_dwordx4 v[216:217], off
	s_add_i32 m0, s77, 0x2000
	s_add_u32 s78, s50, 0x80000
	v_lshl_add_u64 v[218:219], s[50:51], 0, v[134:135]
	s_addc_u32 s79, s51, 0
	s_add_i32 s77, s65, s0
	global_load_lds_dwordx4 v[218:219], off
	v_lshl_add_u64 v[220:221], s[78:79], 0, v[130:131]
	s_mov_b32 m0, s77
	v_lshl_add_u64 v[222:223], s[60:61], 0, v[132:133]
	global_load_lds_dwordx4 v[220:221], off
	v_lshl_add_u64 v[220:221], s[78:79], 0, v[134:135]
	s_add_i32 m0, s77, 0x2000
	s_nop 0
	global_load_lds_dwordx4 v[220:221], off
	v_lshl_add_u64 v[220:221], s[60:61], 0, v[128:129]
	s_mov_b32 m0, s1
	s_nop 0
	global_load_lds_dwordx4 v[220:221], off
	s_mov_b32 m0, s10
	s_nop 0
	global_load_lds_dwordx4 v[222:223], off
	s_waitcnt vmcnt(8)
	s_waitcnt lgkmcnt(0)
	s_barrier
	s_setprio 1
	s_waitcnt lgkmcnt(0)
	v_mfma_f32_16x16x32_bf16 v[60:63], v[142:145], v[184:187], v[60:63]
	v_mfma_f32_16x16x32_bf16 v[60:63], v[146:149], v[188:191], v[60:63]
	v_mfma_f32_16x16x32_bf16 v[56:59], v[150:153], v[184:187], v[56:59]
	v_mfma_f32_16x16x32_bf16 v[56:59], v[154:157], v[188:191], v[56:59]
	v_mfma_f32_16x16x32_bf16 v[44:47], v[142:145], v[192:195], v[44:47]
	v_mfma_f32_16x16x32_bf16 v[44:47], v[146:149], v[196:199], v[44:47]
	v_mfma_f32_16x16x32_bf16 v[40:43], v[150:153], v[192:195], v[40:43]
	v_mfma_f32_16x16x32_bf16 v[40:43], v[154:157], v[196:199], v[40:43]
	v_mfma_f32_16x16x32_bf16 v[28:31], v[142:145], v[200:203], v[28:31]
	v_mfma_f32_16x16x32_bf16 v[28:31], v[146:149], v[204:207], v[28:31]
	v_mfma_f32_16x16x32_bf16 v[24:27], v[150:153], v[200:203], v[24:27]
	v_mfma_f32_16x16x32_bf16 v[24:27], v[154:157], v[204:207], v[24:27]
	v_mfma_f32_16x16x32_bf16 v[12:15], v[142:145], v[208:211], v[12:15]
	v_mfma_f32_16x16x32_bf16 v[12:15], v[146:149], v[212:215], v[12:15]
	v_mfma_f32_16x16x32_bf16 v[8:11], v[150:153], v[208:211], v[8:11]
	v_mfma_f32_16x16x32_bf16 v[8:11], v[154:157], v[212:215], v[8:11]
	s_setprio 0
	s_setprio 1
	v_mfma_f32_16x16x32_bf16 v[52:55], v[166:169], v[184:187], v[52:55]
	v_mfma_f32_16x16x32_bf16 v[52:55], v[170:173], v[188:191], v[52:55]
	v_mfma_f32_16x16x32_bf16 v[48:51], v[176:179], v[184:187], v[48:51]
	v_mfma_f32_16x16x32_bf16 v[48:51], v[180:183], v[188:191], v[48:51]
	v_mfma_f32_16x16x32_bf16 v[36:39], v[166:169], v[192:195], v[36:39]
	v_mfma_f32_16x16x32_bf16 v[36:39], v[170:173], v[196:199], v[36:39]
	v_mfma_f32_16x16x32_bf16 v[32:35], v[176:179], v[192:195], v[32:35]
	v_mfma_f32_16x16x32_bf16 v[32:35], v[180:183], v[196:199], v[32:35]
	v_mfma_f32_16x16x32_bf16 v[20:23], v[166:169], v[200:203], v[20:23]
	v_mfma_f32_16x16x32_bf16 v[20:23], v[170:173], v[204:207], v[20:23]
	v_mfma_f32_16x16x32_bf16 v[16:19], v[176:179], v[200:203], v[16:19]
	v_mfma_f32_16x16x32_bf16 v[16:19], v[180:183], v[204:207], v[16:19]
	v_mfma_f32_16x16x32_bf16 v[4:7], v[166:169], v[208:211], v[4:7]
	v_mfma_f32_16x16x32_bf16 v[4:7], v[170:173], v[212:215], v[4:7]
	v_mfma_f32_16x16x32_bf16 v[0:3], v[176:179], v[208:211], v[0:3]
	v_mfma_f32_16x16x32_bf16 v[0:3], v[180:183], v[212:215], v[0:3]
	s_setprio 0
	s_barrier
	s_add_i32 s77, 0, 0x18000
	v_add_u32_e32 v136, s77, v158
	s_add_i32 s78, 0, 0x1c000
	ds_read_b128 v[142:145], v136
	ds_read_b128 v[146:149], v136 offset:1024
	ds_read_b128 v[150:153], v136 offset:2048
	ds_read_b128 v[154:157], v136 offset:3072
	v_add_u32_e32 v136, s78, v158
	ds_read_b128 v[166:169], v136
	ds_read_b128 v[170:173], v136 offset:1024
	ds_read_b128 v[176:179], v136 offset:2048
	ds_read_b128 v[180:183], v136 offset:3072
	s_add_u32 s60, s60, 0x80000
	s_addc_u32 s61, s61, 0
	s_mov_b32 m0, s11
	v_lshl_add_u64 v[224:225], s[60:61], 0, v[128:129]
	ds_read_b128 v[184:187], v161 offset:32768
	ds_read_b128 v[188:191], v161 offset:33792
	ds_read_b128 v[192:195], v161 offset:34816
	ds_read_b128 v[196:199], v161 offset:35840
	ds_read_b128 v[200:203], v161 offset:36864
	ds_read_b128 v[204:207], v161 offset:37888
	ds_read_b128 v[208:211], v161 offset:38912
	ds_read_b128 v[212:215], v161 offset:39936
	global_load_lds_dwordx4 v[224:225], off
	v_lshl_add_u64 v[224:225], s[60:61], 0, v[132:133]
	s_mov_b32 m0, s14
	s_nop 0
	global_load_lds_dwordx4 v[224:225], off
	s_waitcnt vmcnt(8)
	s_waitcnt lgkmcnt(0)
	s_barrier
	s_setprio 1
	s_waitcnt lgkmcnt(0)
	v_mfma_f32_16x16x32_bf16 v[124:127], v[142:145], v[184:187], v[124:127]
	v_mfma_f32_16x16x32_bf16 v[124:127], v[146:149], v[188:191], v[124:127]
	v_mfma_f32_16x16x32_bf16 v[120:123], v[150:153], v[184:187], v[120:123]
	v_mfma_f32_16x16x32_bf16 v[120:123], v[154:157], v[188:191], v[120:123]
	v_mfma_f32_16x16x32_bf16 v[108:111], v[142:145], v[192:195], v[108:111]
	v_mfma_f32_16x16x32_bf16 v[108:111], v[146:149], v[196:199], v[108:111]
	v_mfma_f32_16x16x32_bf16 v[104:107], v[150:153], v[192:195], v[104:107]
	v_mfma_f32_16x16x32_bf16 v[104:107], v[154:157], v[196:199], v[104:107]
	v_mfma_f32_16x16x32_bf16 v[92:95], v[142:145], v[200:203], v[92:95]
	v_mfma_f32_16x16x32_bf16 v[92:95], v[146:149], v[204:207], v[92:95]
	v_mfma_f32_16x16x32_bf16 v[88:91], v[150:153], v[200:203], v[88:91]
	v_mfma_f32_16x16x32_bf16 v[88:91], v[154:157], v[204:207], v[88:91]
	v_mfma_f32_16x16x32_bf16 v[76:79], v[142:145], v[208:211], v[76:79]
	v_mfma_f32_16x16x32_bf16 v[76:79], v[146:149], v[212:215], v[76:79]
	v_mfma_f32_16x16x32_bf16 v[72:75], v[150:153], v[208:211], v[72:75]
	v_mfma_f32_16x16x32_bf16 v[72:75], v[154:157], v[212:215], v[72:75]
	s_setprio 0
	s_setprio 1
	v_mfma_f32_16x16x32_bf16 v[116:119], v[166:169], v[184:187], v[116:119]
	v_mfma_f32_16x16x32_bf16 v[116:119], v[170:173], v[188:191], v[116:119]
	v_mfma_f32_16x16x32_bf16 v[112:115], v[176:179], v[184:187], v[112:115]
	v_mfma_f32_16x16x32_bf16 v[112:115], v[180:183], v[188:191], v[112:115]
	v_mfma_f32_16x16x32_bf16 v[100:103], v[166:169], v[192:195], v[100:103]
	v_mfma_f32_16x16x32_bf16 v[100:103], v[170:173], v[196:199], v[100:103]
	v_mfma_f32_16x16x32_bf16 v[96:99], v[176:179], v[192:195], v[96:99]
	v_mfma_f32_16x16x32_bf16 v[96:99], v[180:183], v[196:199], v[96:99]
	v_mfma_f32_16x16x32_bf16 v[84:87], v[166:169], v[200:203], v[84:87]
	v_mfma_f32_16x16x32_bf16 v[84:87], v[170:173], v[204:207], v[84:87]
	v_mfma_f32_16x16x32_bf16 v[80:83], v[176:179], v[200:203], v[80:83]
	v_mfma_f32_16x16x32_bf16 v[80:83], v[180:183], v[204:207], v[80:83]
	v_mfma_f32_16x16x32_bf16 v[68:71], v[166:169], v[208:211], v[68:71]
	v_mfma_f32_16x16x32_bf16 v[68:71], v[170:173], v[212:215], v[68:71]
	v_mfma_f32_16x16x32_bf16 v[64:67], v[176:179], v[208:211], v[64:67]
	v_mfma_f32_16x16x32_bf16 v[64:67], v[180:183], v[212:215], v[64:67]
	s_setprio 0
	s_barrier
	s_add_i32 s60, s77, s0
	v_lshl_add_u64 v[216:217], v[216:217], 0, s[34:35]
	s_mov_b32 m0, s60
	ds_read_b128 v[184:187], v161 offset:49152
	ds_read_b128 v[188:191], v161 offset:50176
	ds_read_b128 v[192:195], v161 offset:51200
	ds_read_b128 v[196:199], v161 offset:52224
	ds_read_b128 v[200:203], v161 offset:53248
	ds_read_b128 v[204:207], v161 offset:54272
	ds_read_b128 v[208:211], v161 offset:55296
	ds_read_b128 v[212:215], v161 offset:56320
	global_load_lds_dwordx4 v[216:217], off
	s_add_i32 m0, s60, 0x2000
	s_add_u32 s50, s50, 0x80080
	v_lshl_add_u64 v[216:217], v[218:219], 0, s[34:35]
	s_addc_u32 s51, s51, 0
	s_add_i32 s60, s78, s0
	global_load_lds_dwordx4 v[216:217], off
	v_lshl_add_u64 v[216:217], s[50:51], 0, v[130:131]
	s_mov_b32 m0, s60
	s_nop 0
	global_load_lds_dwordx4 v[216:217], off
	v_lshl_add_u64 v[216:217], s[50:51], 0, v[134:135]
	s_add_i32 m0, s60, 0x2000
	s_nop 0
	global_load_lds_dwordx4 v[216:217], off
	v_lshl_add_u64 v[216:217], v[220:221], 0, s[34:35]
	s_mov_b32 m0, s15
	s_nop 0
	global_load_lds_dwordx4 v[216:217], off
	v_lshl_add_u64 v[216:217], v[222:223], 0, s[34:35]
	s_mov_b32 m0, s33
	s_nop 0
	global_load_lds_dwordx4 v[216:217], off
	s_waitcnt vmcnt(8)
	s_waitcnt lgkmcnt(0)
	s_barrier
	s_setprio 1
	s_waitcnt lgkmcnt(0)
	v_mfma_f32_16x16x32_bf16 v[60:63], v[142:145], v[184:187], v[60:63]
	v_mfma_f32_16x16x32_bf16 v[60:63], v[146:149], v[188:191], v[60:63]
	v_mfma_f32_16x16x32_bf16 v[56:59], v[150:153], v[184:187], v[56:59]
	v_mfma_f32_16x16x32_bf16 v[56:59], v[154:157], v[188:191], v[56:59]
	v_mfma_f32_16x16x32_bf16 v[44:47], v[142:145], v[192:195], v[44:47]
	v_mfma_f32_16x16x32_bf16 v[44:47], v[146:149], v[196:199], v[44:47]
	v_mfma_f32_16x16x32_bf16 v[40:43], v[150:153], v[192:195], v[40:43]
	v_mfma_f32_16x16x32_bf16 v[40:43], v[154:157], v[196:199], v[40:43]
	v_mfma_f32_16x16x32_bf16 v[28:31], v[142:145], v[200:203], v[28:31]
	v_mfma_f32_16x16x32_bf16 v[28:31], v[146:149], v[204:207], v[28:31]
	v_mfma_f32_16x16x32_bf16 v[24:27], v[150:153], v[200:203], v[24:27]
	v_mfma_f32_16x16x32_bf16 v[24:27], v[154:157], v[204:207], v[24:27]
	v_mfma_f32_16x16x32_bf16 v[12:15], v[142:145], v[208:211], v[12:15]
	v_mfma_f32_16x16x32_bf16 v[12:15], v[146:149], v[212:215], v[12:15]
	v_mfma_f32_16x16x32_bf16 v[8:11], v[150:153], v[208:211], v[8:11]
	v_mfma_f32_16x16x32_bf16 v[8:11], v[154:157], v[212:215], v[8:11]
	s_setprio 0
	s_setprio 1
	v_mfma_f32_16x16x32_bf16 v[52:55], v[166:169], v[184:187], v[52:55]
	v_mfma_f32_16x16x32_bf16 v[52:55], v[170:173], v[188:191], v[52:55]
	v_mfma_f32_16x16x32_bf16 v[48:51], v[176:179], v[184:187], v[48:51]
	v_mfma_f32_16x16x32_bf16 v[48:51], v[180:183], v[188:191], v[48:51]
	v_mfma_f32_16x16x32_bf16 v[36:39], v[166:169], v[192:195], v[36:39]
	v_mfma_f32_16x16x32_bf16 v[36:39], v[170:173], v[196:199], v[36:39]
	v_mfma_f32_16x16x32_bf16 v[32:35], v[176:179], v[192:195], v[32:35]
	v_mfma_f32_16x16x32_bf16 v[32:35], v[180:183], v[196:199], v[32:35]
	v_mfma_f32_16x16x32_bf16 v[20:23], v[166:169], v[200:203], v[20:23]
	v_mfma_f32_16x16x32_bf16 v[20:23], v[170:173], v[204:207], v[20:23]
	v_mfma_f32_16x16x32_bf16 v[16:19], v[176:179], v[200:203], v[16:19]
	v_mfma_f32_16x16x32_bf16 v[16:19], v[180:183], v[204:207], v[16:19]
	v_mfma_f32_16x16x32_bf16 v[4:7], v[166:169], v[208:211], v[4:7]
	v_mfma_f32_16x16x32_bf16 v[4:7], v[170:173], v[212:215], v[4:7]
	v_mfma_f32_16x16x32_bf16 v[0:3], v[176:179], v[208:211], v[0:3]
	v_mfma_f32_16x16x32_bf16 v[0:3], v[180:183], v[212:215], v[0:3]
	s_setprio 0
	s_barrier
	s_add_i32 s76, s76, 2
	s_add_u32 s48, s48, 0x100
	s_addc_u32 s49, s49, 0
	s_add_u32 s74, s74, 0x100
	s_addc_u32 s75, s75, 0
	s_cmp_gt_u32 s76, 29
	s_cbranch_scc0 .LBB0_596
	s_and_b64 vcc, exec, s[36:37]
	s_cbranch_vccz .LBB0_599
	s_barrier

.LBB0_707:
	ds_read_b128 v[128:131], v188
	ds_read_b128 v[132:135], v188 offset:1024
	ds_read_b128 v[136:139], v188 offset:2048
	ds_read_b128 v[140:143], v188 offset:3072
	ds_read_b128 v[144:147], v189
	ds_read_b128 v[148:151], v189 offset:1024
	ds_read_b128 v[164:167], v189 offset:2048
	ds_read_b128 v[192:195], v189 offset:3072
	s_add_u32 s60, s50, 0xfffc0080
	s_addc_u32 s61, s51, -1
	s_cmp_eq_u32 s73, 12
	s_cselect_b32 s63, s27, s61
	s_cselect_b32 s62, s41, s60
	s_cselect_b32 s61, s49, s72
	s_cselect_b32 s60, s70, s71
	v_lshl_add_u64 v[168:169], s[50:51], 0, v[160:161]
	s_add_i32 m0, s1, 0xc000
	ds_read_b128 v[196:199], v190
	ds_read_b128 v[200:203], v190 offset:1024
	ds_read_b128 v[204:207], v190 offset:2048
	ds_read_b128 v[208:211], v190 offset:3072
	ds_read_b128 v[212:215], v190 offset:4096
	ds_read_b128 v[216:219], v190 offset:5120
	ds_read_b128 v[220:223], v190 offset:6144
	ds_read_b128 v[224:227], v190 offset:7168
	global_load_lds_dwordx4 v[168:169], off
	v_lshl_add_u64 v[168:169], s[50:51], 0, v[162:163]
	s_add_i32 m0, s1, 0xe000
	s_nop 0
	global_load_lds_dwordx4 v[168:169], off
	s_waitcnt vmcnt(8)
	s_waitcnt lgkmcnt(0)
	s_barrier
	s_setprio 1
	s_waitcnt lgkmcnt(0)
	v_mfma_f32_16x16x32_bf16 v[124:127], v[128:131], v[196:199], v[124:127]
	v_mfma_f32_16x16x32_bf16 v[124:127], v[132:135], v[200:203], v[124:127]
	v_mfma_f32_16x16x32_bf16 v[120:123], v[136:139], v[196:199], v[120:123]
	v_mfma_f32_16x16x32_bf16 v[120:123], v[140:143], v[200:203], v[120:123]
	v_mfma_f32_16x16x32_bf16 v[108:111], v[128:131], v[204:207], v[108:111]
	v_mfma_f32_16x16x32_bf16 v[108:111], v[132:135], v[208:211], v[108:111]
	v_mfma_f32_16x16x32_bf16 v[104:107], v[136:139], v[204:207], v[104:107]
	v_mfma_f32_16x16x32_bf16 v[104:107], v[140:143], v[208:211], v[104:107]
	v_mfma_f32_16x16x32_bf16 v[92:95], v[128:131], v[212:215], v[92:95]
	v_mfma_f32_16x16x32_bf16 v[92:95], v[132:135], v[216:219], v[92:95]
	v_mfma_f32_16x16x32_bf16 v[88:91], v[136:139], v[212:215], v[88:91]
	v_mfma_f32_16x16x32_bf16 v[88:91], v[140:143], v[216:219], v[88:91]
	v_mfma_f32_16x16x32_bf16 v[76:79], v[128:131], v[220:223], v[76:79]
	v_mfma_f32_16x16x32_bf16 v[76:79], v[132:135], v[224:227], v[76:79]
	v_mfma_f32_16x16x32_bf16 v[72:75], v[136:139], v[220:223], v[72:75]
	v_mfma_f32_16x16x32_bf16 v[72:75], v[140:143], v[224:227], v[72:75]
	s_setprio 0
	s_setprio 1
	v_mfma_f32_16x16x32_bf16 v[116:119], v[144:147], v[196:199], v[116:119]
	v_mfma_f32_16x16x32_bf16 v[116:119], v[148:151], v[200:203], v[116:119]
	v_mfma_f32_16x16x32_bf16 v[112:115], v[164:167], v[196:199], v[112:115]
	v_mfma_f32_16x16x32_bf16 v[112:115], v[192:195], v[200:203], v[112:115]
	v_mfma_f32_16x16x32_bf16 v[100:103], v[144:147], v[204:207], v[100:103]
	v_mfma_f32_16x16x32_bf16 v[100:103], v[148:151], v[208:211], v[100:103]
	v_mfma_f32_16x16x32_bf16 v[96:99], v[164:167], v[204:207], v[96:99]
	v_mfma_f32_16x16x32_bf16 v[96:99], v[192:195], v[208:211], v[96:99]
	v_mfma_f32_16x16x32_bf16 v[84:87], v[144:147], v[212:215], v[84:87]
	v_mfma_f32_16x16x32_bf16 v[84:87], v[148:151], v[216:219], v[84:87]
	v_mfma_f32_16x16x32_bf16 v[80:83], v[164:167], v[212:215], v[80:83]
	v_mfma_f32_16x16x32_bf16 v[80:83], v[192:195], v[216:219], v[80:83]
	v_mfma_f32_16x16x32_bf16 v[68:71], v[144:147], v[220:223], v[68:71]
	v_mfma_f32_16x16x32_bf16 v[68:71], v[148:151], v[224:227], v[68:71]
	v_mfma_f32_16x16x32_bf16 v[64:67], v[164:167], v[220:223], v[64:67]
	v_mfma_f32_16x16x32_bf16 v[64:67], v[192:195], v[224:227], v[64:67]
	s_setprio 0
	s_barrier
	s_add_i32 s74, s66, s0
	v_lshl_add_u64 v[168:169], s[60:61], 0, v[154:155]
	s_mov_b32 m0, s74
	ds_read_b128 v[196:199], v190 offset:16384
	ds_read_b128 v[200:203], v190 offset:17408
	ds_read_b128 v[204:207], v190 offset:18432
	ds_read_b128 v[208:211], v190 offset:19456
	ds_read_b128 v[212:215], v190 offset:20480
	ds_read_b128 v[216:219], v190 offset:21504
	ds_read_b128 v[220:223], v190 offset:22528
	ds_read_b128 v[224:227], v190 offset:23552
	global_load_lds_dwordx4 v[168:169], off
	s_add_i32 m0, s74, 0x2000
	s_add_u32 s74, s60, 0x40000
	v_lshl_add_u64 v[228:229], s[60:61], 0, v[158:159]
	s_addc_u32 s75, s61, 0
	s_add_i32 s76, s67, s0
	global_load_lds_dwordx4 v[228:229], off
	v_lshl_add_u64 v[230:231], s[74:75], 0, v[154:155]
	s_mov_b32 m0, s76
	v_lshl_add_u64 v[232:233], s[62:63], 0, v[156:157]
	global_load_lds_dwordx4 v[230:231], off
	v_lshl_add_u64 v[230:231], s[74:75], 0, v[158:159]
	s_add_i32 m0, s76, 0x2000
	s_nop 0
	global_load_lds_dwordx4 v[230:231], off
	v_lshl_add_u64 v[230:231], s[62:63], 0, v[152:153]
	s_mov_b32 m0, s1
	s_nop 0
	global_load_lds_dwordx4 v[230:231], off
	s_mov_b32 m0, s10
	s_nop 0
	global_load_lds_dwordx4 v[232:233], off
	s_waitcnt vmcnt(8)
	s_waitcnt lgkmcnt(0)
	s_barrier
	s_setprio 1
	s_waitcnt lgkmcnt(0)
	v_mfma_f32_16x16x32_bf16 v[60:63], v[128:131], v[196:199], v[60:63]
	v_mfma_f32_16x16x32_bf16 v[60:63], v[132:135], v[200:203], v[60:63]
	v_mfma_f32_16x16x32_bf16 v[56:59], v[136:139], v[196:199], v[56:59]
	v_mfma_f32_16x16x32_bf16 v[56:59], v[140:143], v[200:203], v[56:59]
	v_mfma_f32_16x16x32_bf16 v[44:47], v[128:131], v[204:207], v[44:47]
	v_mfma_f32_16x16x32_bf16 v[44:47], v[132:135], v[208:211], v[44:47]
	v_mfma_f32_16x16x32_bf16 v[40:43], v[136:139], v[204:207], v[40:43]
	v_mfma_f32_16x16x32_bf16 v[40:43], v[140:143], v[208:211], v[40:43]
	v_mfma_f32_16x16x32_bf16 v[28:31], v[128:131], v[212:215], v[28:31]
	v_mfma_f32_16x16x32_bf16 v[28:31], v[132:135], v[216:219], v[28:31]
	v_mfma_f32_16x16x32_bf16 v[24:27], v[136:139], v[212:215], v[24:27]
	v_mfma_f32_16x16x32_bf16 v[24:27], v[140:143], v[216:219], v[24:27]
	v_mfma_f32_16x16x32_bf16 v[12:15], v[128:131], v[220:223], v[12:15]
	v_mfma_f32_16x16x32_bf16 v[12:15], v[132:135], v[224:227], v[12:15]
	v_mfma_f32_16x16x32_bf16 v[8:11], v[136:139], v[220:223], v[8:11]
	v_mfma_f32_16x16x32_bf16 v[8:11], v[140:143], v[224:227], v[8:11]
	s_setprio 0
	s_setprio 1
	v_mfma_f32_16x16x32_bf16 v[52:55], v[144:147], v[196:199], v[52:55]
	v_mfma_f32_16x16x32_bf16 v[52:55], v[148:151], v[200:203], v[52:55]
	v_mfma_f32_16x16x32_bf16 v[48:51], v[164:167], v[196:199], v[48:51]
	v_mfma_f32_16x16x32_bf16 v[48:51], v[192:195], v[200:203], v[48:51]
	v_mfma_f32_16x16x32_bf16 v[36:39], v[144:147], v[204:207], v[36:39]
	v_mfma_f32_16x16x32_bf16 v[36:39], v[148:151], v[208:211], v[36:39]
	v_mfma_f32_16x16x32_bf16 v[32:35], v[164:167], v[204:207], v[32:35]
	v_mfma_f32_16x16x32_bf16 v[32:35], v[192:195], v[208:211], v[32:35]
	v_mfma_f32_16x16x32_bf16 v[20:23], v[144:147], v[212:215], v[20:23]
	v_mfma_f32_16x16x32_bf16 v[20:23], v[148:151], v[216:219], v[20:23]
	v_mfma_f32_16x16x32_bf16 v[16:19], v[164:167], v[212:215], v[16:19]
	v_mfma_f32_16x16x32_bf16 v[16:19], v[192:195], v[216:219], v[16:19]
	v_mfma_f32_16x16x32_bf16 v[4:7], v[144:147], v[220:223], v[4:7]
	v_mfma_f32_16x16x32_bf16 v[4:7], v[148:151], v[224:227], v[4:7]
	v_mfma_f32_16x16x32_bf16 v[0:3], v[164:167], v[220:223], v[0:3]
	v_mfma_f32_16x16x32_bf16 v[0:3], v[192:195], v[224:227], v[0:3]
	s_setprio 0
	s_barrier
	s_add_i32 s74, 0, 0x18000
	s_add_i32 s75, 0, 0x1c000
	v_add_u32_e32 v140, s74, v171
	v_add_u32_e32 v192, s75, v171
	ds_read_b128 v[128:131], v140
	ds_read_b128 v[132:135], v140 offset:1024
	ds_read_b128 v[136:139], v140 offset:2048
	ds_read_b128 v[140:143], v140 offset:3072
	ds_read_b128 v[144:147], v192
	ds_read_b128 v[148:151], v192 offset:1024
	ds_read_b128 v[164:167], v192 offset:2048
	ds_read_b128 v[192:195], v192 offset:3072
	s_add_u32 s62, s62, 0x40000
	s_addc_u32 s63, s63, 0
	s_mov_b32 m0, s11
	v_lshl_add_u64 v[234:235], s[62:63], 0, v[152:153]
	ds_read_b128 v[196:199], v190 offset:32768
	ds_read_b128 v[200:203], v190 offset:33792
	ds_read_b128 v[204:207], v190 offset:34816
	ds_read_b128 v[208:211], v190 offset:35840
	ds_read_b128 v[212:215], v190 offset:36864
	ds_read_b128 v[216:219], v190 offset:37888
	ds_read_b128 v[220:223], v190 offset:38912
	ds_read_b128 v[224:227], v190 offset:39936
	global_load_lds_dwordx4 v[234:235], off
	v_lshl_add_u64 v[234:235], s[62:63], 0, v[156:157]
	s_mov_b32 m0, s14
	s_nop 0
	global_load_lds_dwordx4 v[234:235], off
	s_waitcnt vmcnt(8)
	s_waitcnt lgkmcnt(0)
	s_barrier
	s_setprio 1
	s_waitcnt lgkmcnt(0)
	v_mfma_f32_16x16x32_bf16 v[124:127], v[128:131], v[196:199], v[124:127]
	v_mfma_f32_16x16x32_bf16 v[124:127], v[132:135], v[200:203], v[124:127]
	v_mfma_f32_16x16x32_bf16 v[120:123], v[136:139], v[196:199], v[120:123]
	v_mfma_f32_16x16x32_bf16 v[120:123], v[140:143], v[200:203], v[120:123]
	v_mfma_f32_16x16x32_bf16 v[108:111], v[128:131], v[204:207], v[108:111]
	v_mfma_f32_16x16x32_bf16 v[108:111], v[132:135], v[208:211], v[108:111]
	v_mfma_f32_16x16x32_bf16 v[104:107], v[136:139], v[204:207], v[104:107]
	v_mfma_f32_16x16x32_bf16 v[104:107], v[140:143], v[208:211], v[104:107]
	v_mfma_f32_16x16x32_bf16 v[92:95], v[128:131], v[212:215], v[92:95]
	v_mfma_f32_16x16x32_bf16 v[92:95], v[132:135], v[216:219], v[92:95]
	v_mfma_f32_16x16x32_bf16 v[88:91], v[136:139], v[212:215], v[88:91]
	v_mfma_f32_16x16x32_bf16 v[88:91], v[140:143], v[216:219], v[88:91]
	v_mfma_f32_16x16x32_bf16 v[76:79], v[128:131], v[220:223], v[76:79]
	v_mfma_f32_16x16x32_bf16 v[76:79], v[132:135], v[224:227], v[76:79]
	v_mfma_f32_16x16x32_bf16 v[72:75], v[136:139], v[220:223], v[72:75]
	v_mfma_f32_16x16x32_bf16 v[72:75], v[140:143], v[224:227], v[72:75]
	s_setprio 0
	s_setprio 1
	v_mfma_f32_16x16x32_bf16 v[116:119], v[144:147], v[196:199], v[116:119]
	v_mfma_f32_16x16x32_bf16 v[116:119], v[148:151], v[200:203], v[116:119]
	v_mfma_f32_16x16x32_bf16 v[112:115], v[164:167], v[196:199], v[112:115]
	v_mfma_f32_16x16x32_bf16 v[112:115], v[192:195], v[200:203], v[112:115]
	v_mfma_f32_16x16x32_bf16 v[100:103], v[144:147], v[204:207], v[100:103]
	v_mfma_f32_16x16x32_bf16 v[100:103], v[148:151], v[208:211], v[100:103]
	v_mfma_f32_16x16x32_bf16 v[96:99], v[164:167], v[204:207], v[96:99]
	v_mfma_f32_16x16x32_bf16 v[96:99], v[192:195], v[208:211], v[96:99]
	v_mfma_f32_16x16x32_bf16 v[84:87], v[144:147], v[212:215], v[84:87]
	v_mfma_f32_16x16x32_bf16 v[84:87], v[148:151], v[216:219], v[84:87]
	v_mfma_f32_16x16x32_bf16 v[80:83], v[164:167], v[212:215], v[80:83]
	v_mfma_f32_16x16x32_bf16 v[80:83], v[192:195], v[216:219], v[80:83]
	v_mfma_f32_16x16x32_bf16 v[68:71], v[144:147], v[220:223], v[68:71]
	v_mfma_f32_16x16x32_bf16 v[68:71], v[148:151], v[224:227], v[68:71]
	v_mfma_f32_16x16x32_bf16 v[64:67], v[164:167], v[220:223], v[64:67]
	v_mfma_f32_16x16x32_bf16 v[64:67], v[192:195], v[224:227], v[64:67]
	s_setprio 0
	s_barrier
	s_add_i32 s62, s74, s0
	v_lshl_add_u64 v[168:169], v[168:169], 0, s[36:37]
	s_mov_b32 m0, s62
	ds_read_b128 v[196:199], v190 offset:49152
	ds_read_b128 v[200:203], v190 offset:50176
	ds_read_b128 v[204:207], v190 offset:51200
	ds_read_b128 v[208:211], v190 offset:52224
	ds_read_b128 v[212:215], v190 offset:53248
	ds_read_b128 v[216:219], v190 offset:54272
	ds_read_b128 v[220:223], v190 offset:55296
	ds_read_b128 v[224:227], v190 offset:56320
	global_load_lds_dwordx4 v[168:169], off
	s_add_i32 m0, s62, 0x2000
	s_add_u32 s60, s60, 0x40080
	v_lshl_add_u64 v[168:169], v[228:229], 0, s[36:37]
	s_addc_u32 s61, s61, 0
	s_add_i32 s62, s75, s0
	global_load_lds_dwordx4 v[168:169], off
	v_lshl_add_u64 v[168:169], s[60:61], 0, v[154:155]
	s_mov_b32 m0, s62
	s_nop 0
	global_load_lds_dwordx4 v[168:169], off
	v_lshl_add_u64 v[168:169], s[60:61], 0, v[158:159]
	s_add_i32 m0, s62, 0x2000
	s_nop 0
	global_load_lds_dwordx4 v[168:169], off
	v_lshl_add_u64 v[168:169], v[230:231], 0, s[36:37]
	s_mov_b32 m0, s15
	s_nop 0
	global_load_lds_dwordx4 v[168:169], off
	v_lshl_add_u64 v[168:169], v[232:233], 0, s[36:37]
	s_mov_b32 m0, s33
	s_nop 0
	global_load_lds_dwordx4 v[168:169], off
	s_waitcnt vmcnt(8)
	s_waitcnt lgkmcnt(0)
	s_barrier
	s_setprio 1
	s_waitcnt lgkmcnt(0)
	v_mfma_f32_16x16x32_bf16 v[60:63], v[128:131], v[196:199], v[60:63]
	v_mfma_f32_16x16x32_bf16 v[60:63], v[132:135], v[200:203], v[60:63]
	v_mfma_f32_16x16x32_bf16 v[56:59], v[136:139], v[196:199], v[56:59]
	v_mfma_f32_16x16x32_bf16 v[56:59], v[140:143], v[200:203], v[56:59]
	v_mfma_f32_16x16x32_bf16 v[44:47], v[128:131], v[204:207], v[44:47]
	v_mfma_f32_16x16x32_bf16 v[44:47], v[132:135], v[208:211], v[44:47]
	v_mfma_f32_16x16x32_bf16 v[40:43], v[136:139], v[204:207], v[40:43]
	v_mfma_f32_16x16x32_bf16 v[40:43], v[140:143], v[208:211], v[40:43]
	v_mfma_f32_16x16x32_bf16 v[28:31], v[128:131], v[212:215], v[28:31]
	v_mfma_f32_16x16x32_bf16 v[28:31], v[132:135], v[216:219], v[28:31]
	v_mfma_f32_16x16x32_bf16 v[24:27], v[136:139], v[212:215], v[24:27]
	v_mfma_f32_16x16x32_bf16 v[24:27], v[140:143], v[216:219], v[24:27]
	v_mfma_f32_16x16x32_bf16 v[12:15], v[128:131], v[220:223], v[12:15]
	v_mfma_f32_16x16x32_bf16 v[12:15], v[132:135], v[224:227], v[12:15]
	v_mfma_f32_16x16x32_bf16 v[8:11], v[136:139], v[220:223], v[8:11]
	v_mfma_f32_16x16x32_bf16 v[8:11], v[140:143], v[224:227], v[8:11]
	s_setprio 0
	s_setprio 1
	v_mfma_f32_16x16x32_bf16 v[52:55], v[144:147], v[196:199], v[52:55]
	v_mfma_f32_16x16x32_bf16 v[52:55], v[148:151], v[200:203], v[52:55]
	v_mfma_f32_16x16x32_bf16 v[48:51], v[164:167], v[196:199], v[48:51]
	v_mfma_f32_16x16x32_bf16 v[48:51], v[192:195], v[200:203], v[48:51]
	v_mfma_f32_16x16x32_bf16 v[36:39], v[144:147], v[204:207], v[36:39]
	v_mfma_f32_16x16x32_bf16 v[36:39], v[148:151], v[208:211], v[36:39]
	v_mfma_f32_16x16x32_bf16 v[32:35], v[164:167], v[204:207], v[32:35]
	v_mfma_f32_16x16x32_bf16 v[32:35], v[192:195], v[208:211], v[32:35]
	v_mfma_f32_16x16x32_bf16 v[20:23], v[144:147], v[212:215], v[20:23]
	v_mfma_f32_16x16x32_bf16 v[20:23], v[148:151], v[216:219], v[20:23]
	v_mfma_f32_16x16x32_bf16 v[16:19], v[164:167], v[212:215], v[16:19]
	v_mfma_f32_16x16x32_bf16 v[16:19], v[192:195], v[216:219], v[16:19]
	v_mfma_f32_16x16x32_bf16 v[4:7], v[144:147], v[220:223], v[4:7]
	v_mfma_f32_16x16x32_bf16 v[4:7], v[148:151], v[224:227], v[4:7]
	v_mfma_f32_16x16x32_bf16 v[0:3], v[164:167], v[220:223], v[0:3]
	v_mfma_f32_16x16x32_bf16 v[0:3], v[192:195], v[224:227], v[0:3]
	s_setprio 0
	s_barrier
	s_add_i32 s73, s73, 2
	s_add_u32 s50, s50, 0x100
	s_addc_u32 s51, s51, 0
	s_add_u32 s71, s71, 0x100
	s_addc_u32 s72, s72, 0
	s_cmp_gt_u32 s73, 13
	s_cbranch_scc0 .LBB0_707
	s_and_b64 vcc, exec, s[38:39]
	s_cbranch_vccz .LBB0_710
	s_barrier

.LBB0_787:
	s_lshl_b32 s18, s18, 5
	s_and_b32 s34, s18, 0x60
	s_mov_b64 s[18:19], 0x80
	s_add_i32 m0, s10, 0x18000
	v_lshl_add_u64 v[6:7], v[6:7], 0, s[18:19]
	s_lshl_b32 s25, s24, 13
	s_lshl_b32 s35, s34, 7
	s_waitcnt vmcnt(2)
	s_barrier
	global_load_lds_dwordx4 v[6:7], off
	v_lshl_add_u64 v[4:5], v[4:5], 0, s[18:19]
	s_add_i32 m0, s10, 0x1a000
	s_add_i32 s41, s10, 0x8000
	s_add_i32 s48, s10, 0xa000
	global_load_lds_dwordx4 v[4:5], off
	v_lshl_add_u64 v[0:1], v[0:1], 0, s[18:19]
	s_mov_b32 m0, s41
	s_add_u32 s26, s44, 0x80080
	global_load_lds_dwordx4 v[0:1], off
	v_lshl_add_u64 v[0:1], v[2:3], 0, s[18:19]
	s_mov_b32 m0, s48
	s_addc_u32 s27, s45, 0
	global_load_lds_dwordx4 v[0:1], off
	s_add_i32 m0, s10, 0x1c000
	v_lshl_add_u64 v[0:1], s[26:27], 0, v[132:133]
	global_load_lds_dwordx4 v[0:1], off
	v_lshl_add_u64 v[0:1], s[26:27], 0, v[128:129]
	s_add_i32 m0, s10, 0x1e000
	s_cmpk_lt_u32 s5, 0x100
	global_load_lds_dwordx4 v[0:1], off
	v_lshrrev_b32_e32 v1, 1, v9
	v_and_b32_e32 v1, 24, v1
	v_and_b32_e32 v0, 15, v9
	v_lshlrev_b32_e32 v2, 1, v1
	v_lshl_or_b32 v150, s24, 6, v0
	v_lshl_or_b32 v0, v0, 6, v2
	v_lshlrev_b32_e32 v2, 2, v9
	v_and_b32_e32 v2, 32, v2
	v_bitop3_b32 v3, v0, s25, v2 bitop3:0xde
	v_bitop3_b32 v151, v0, s35, v2 bitop3:0xde
	v_lshlrev_b32_e32 v0, 15, v13
	v_and_b32_e32 v0, 0xffff0000, v0
	v_or_b32_e32 v152, s34, v1
	v_lshl_add_u32 v0, v12, 12, v0
	v_and_b32_e32 v1, 1, v13
	v_lshl_or_b32 v0, v1, 6, v0
	v_lshl_add_u32 v136, v14, 1, v0
	v_lshlrev_b32_e32 v0, 15, v8
	v_and_b32_e32 v0, 0xffff0000, v0
	s_waitcnt vmcnt(6)
	v_lshl_add_u32 v0, v10, 12, v0
	v_and_b32_e32 v1, 1, v8
	s_cselect_b64 s[24:25], -1, 0
	v_lshl_or_b32 v0, v1, 6, v0
	s_add_i32 s49, 0, 0x10000
	s_add_i32 s50, 0, 0x14000
	s_sext_i32_i8 s60, s4
	v_mov_b32_e32 v137, v133
	v_lshl_add_u32 v138, v11, 1, v0
	v_mov_b32_e32 v139, v133
	v_mov_b64_e32 v[140:141], 0xb00
	v_mov_b64_e32 v[142:143], 0xaff
	v_add_u32_e32 v153, s49, v151
	v_add_u32_e32 v154, s50, v151
	v_add_u32_e32 v155, 0, v3
	v_mov_b32_e32 v156, 0x358637bd
	s_movk_i32 s51, 0x2c00
	s_mov_b32 s69, -1
	s_barrier
	s_branch .LBB0_790

.LBB0_793:
	ds_read_b128 v[144:147], v153
	ds_read_b128 v[158:161], v153 offset:1024
	ds_read_b128 v[162:165], v153 offset:2048
	ds_read_b128 v[166:169], v153 offset:3072
	ds_read_b128 v[170:173], v154
	ds_read_b128 v[176:179], v154 offset:1024
	ds_read_b128 v[180:183], v154 offset:2048
	ds_read_b128 v[184:187], v154 offset:3072
	s_add_u32 s44, s42, 0xfff80080
	s_addc_u32 s45, s43, -1
	s_cmp_eq_u32 s65, 28
	s_cselect_b32 s47, s35, s45
	s_cselect_b32 s46, s61, s44
	s_cselect_b32 s45, s27, s64
	s_cselect_b32 s44, s62, s63
	s_add_u32 s100, s46, 0x80
	s_addc_u32 s101, s47, 0
	s_add_i32 m0, s10, 0xc000
	ds_read_b128 v[188:191], v155
	ds_read_b128 v[192:195], v155 offset:1024
	ds_read_b128 v[196:199], v155 offset:2048
	ds_read_b128 v[200:203], v155 offset:3072
	ds_read_b128 v[204:207], v155 offset:4096
	ds_read_b128 v[208:211], v155 offset:5120
	ds_read_b128 v[212:215], v155 offset:6144
	ds_read_b128 v[216:219], v155 offset:7168
	global_load_lds_dwordx4 v136, s[42:43]
	s_add_i32 m0, s10, 0xe000
	s_nop 0
	global_load_lds_dwordx4 v138, s[42:43]
	s_waitcnt vmcnt(8)
	s_waitcnt lgkmcnt(0)
	s_setprio 1
	s_waitcnt lgkmcnt(0)
	v_mfma_f32_16x16x32_bf16 v[124:127], v[144:147], v[188:191], v[124:127]
	v_mfma_f32_16x16x32_bf16 v[124:127], v[158:161], v[192:195], v[124:127]
	v_mfma_f32_16x16x32_bf16 v[120:123], v[162:165], v[188:191], v[120:123]
	v_mfma_f32_16x16x32_bf16 v[120:123], v[166:169], v[192:195], v[120:123]
	v_mfma_f32_16x16x32_bf16 v[108:111], v[144:147], v[196:199], v[108:111]
	v_mfma_f32_16x16x32_bf16 v[108:111], v[158:161], v[200:203], v[108:111]
	v_mfma_f32_16x16x32_bf16 v[104:107], v[162:165], v[196:199], v[104:107]
	v_mfma_f32_16x16x32_bf16 v[104:107], v[166:169], v[200:203], v[104:107]
	v_mfma_f32_16x16x32_bf16 v[92:95], v[144:147], v[204:207], v[92:95]
	v_mfma_f32_16x16x32_bf16 v[92:95], v[158:161], v[208:211], v[92:95]
	v_mfma_f32_16x16x32_bf16 v[88:91], v[162:165], v[204:207], v[88:91]
	v_mfma_f32_16x16x32_bf16 v[88:91], v[166:169], v[208:211], v[88:91]
	v_mfma_f32_16x16x32_bf16 v[76:79], v[144:147], v[212:215], v[76:79]
	v_mfma_f32_16x16x32_bf16 v[76:79], v[158:161], v[216:219], v[76:79]
	v_mfma_f32_16x16x32_bf16 v[72:75], v[162:165], v[212:215], v[72:75]
	v_mfma_f32_16x16x32_bf16 v[72:75], v[166:169], v[216:219], v[72:75]
	s_setprio 0
	s_setprio 1
	v_mfma_f32_16x16x32_bf16 v[116:119], v[170:173], v[188:191], v[116:119]
	v_mfma_f32_16x16x32_bf16 v[116:119], v[176:179], v[192:195], v[116:119]
	v_mfma_f32_16x16x32_bf16 v[112:115], v[180:183], v[188:191], v[112:115]
	v_mfma_f32_16x16x32_bf16 v[112:115], v[184:187], v[192:195], v[112:115]
	v_mfma_f32_16x16x32_bf16 v[100:103], v[170:173], v[196:199], v[100:103]
	v_mfma_f32_16x16x32_bf16 v[100:103], v[176:179], v[200:203], v[100:103]
	v_mfma_f32_16x16x32_bf16 v[96:99], v[180:183], v[196:199], v[96:99]
	v_mfma_f32_16x16x32_bf16 v[96:99], v[184:187], v[200:203], v[96:99]
	v_mfma_f32_16x16x32_bf16 v[84:87], v[170:173], v[204:207], v[84:87]
	v_mfma_f32_16x16x32_bf16 v[84:87], v[176:179], v[208:211], v[84:87]
	v_mfma_f32_16x16x32_bf16 v[80:83], v[180:183], v[204:207], v[80:83]
	v_mfma_f32_16x16x32_bf16 v[80:83], v[184:187], v[208:211], v[80:83]
	v_mfma_f32_16x16x32_bf16 v[68:71], v[170:173], v[212:215], v[68:71]
	v_mfma_f32_16x16x32_bf16 v[68:71], v[176:179], v[216:219], v[68:71]
	v_mfma_f32_16x16x32_bf16 v[64:67], v[180:183], v[212:215], v[64:67]
	v_mfma_f32_16x16x32_bf16 v[64:67], v[184:187], v[216:219], v[64:67]
	s_setprio 0
	s_barrier
	s_add_i32 s66, s49, s0
	s_mov_b32 m0, s66
	ds_read_b128 v[188:191], v155 offset:16384
	ds_read_b128 v[192:195], v155 offset:17408
	ds_read_b128 v[196:199], v155 offset:18432
	ds_read_b128 v[200:203], v155 offset:19456
	ds_read_b128 v[204:207], v155 offset:20480
	ds_read_b128 v[208:211], v155 offset:21504
	ds_read_b128 v[212:215], v155 offset:22528
	ds_read_b128 v[216:219], v155 offset:23552
	global_load_lds_dwordx4 v132, s[44:45]
	s_add_i32 m0, s66, 0x2000
	s_add_u32 s66, s44, 0x80000
	s_addc_u32 s67, s45, 0
	s_add_i32 s68, s50, s0
	global_load_lds_dwordx4 v128, s[44:45]
	s_mov_b32 m0, s68
	s_nop 0
	global_load_lds_dwordx4 v132, s[66:67]
	s_add_i32 m0, s68, 0x2000
	s_nop 0
	global_load_lds_dwordx4 v128, s[66:67]
	s_mov_b32 m0, s10
	s_nop 0
	global_load_lds_dwordx4 v134, s[46:47]
	s_mov_b32 m0, s11
	s_nop 0
	global_load_lds_dwordx4 v130, s[46:47]
	s_waitcnt vmcnt(8)
	s_waitcnt lgkmcnt(0)
	s_setprio 1
	s_waitcnt lgkmcnt(0)
	v_mfma_f32_16x16x32_bf16 v[60:63], v[144:147], v[188:191], v[60:63]
	v_mfma_f32_16x16x32_bf16 v[60:63], v[158:161], v[192:195], v[60:63]
	v_mfma_f32_16x16x32_bf16 v[56:59], v[162:165], v[188:191], v[56:59]
	v_mfma_f32_16x16x32_bf16 v[56:59], v[166:169], v[192:195], v[56:59]
	v_mfma_f32_16x16x32_bf16 v[44:47], v[144:147], v[196:199], v[44:47]
	v_mfma_f32_16x16x32_bf16 v[44:47], v[158:161], v[200:203], v[44:47]
	v_mfma_f32_16x16x32_bf16 v[40:43], v[162:165], v[196:199], v[40:43]
	v_mfma_f32_16x16x32_bf16 v[40:43], v[166:169], v[200:203], v[40:43]
	v_mfma_f32_16x16x32_bf16 v[28:31], v[144:147], v[204:207], v[28:31]
	v_mfma_f32_16x16x32_bf16 v[28:31], v[158:161], v[208:211], v[28:31]
	v_mfma_f32_16x16x32_bf16 v[24:27], v[162:165], v[204:207], v[24:27]
	v_mfma_f32_16x16x32_bf16 v[24:27], v[166:169], v[208:211], v[24:27]
	v_mfma_f32_16x16x32_bf16 v[12:15], v[144:147], v[212:215], v[12:15]
	v_mfma_f32_16x16x32_bf16 v[12:15], v[158:161], v[216:219], v[12:15]
	v_mfma_f32_16x16x32_bf16 v[8:11], v[162:165], v[212:215], v[8:11]
	v_mfma_f32_16x16x32_bf16 v[8:11], v[166:169], v[216:219], v[8:11]
	s_setprio 0
	s_setprio 1
	v_mfma_f32_16x16x32_bf16 v[52:55], v[170:173], v[188:191], v[52:55]
	v_mfma_f32_16x16x32_bf16 v[52:55], v[176:179], v[192:195], v[52:55]
	v_mfma_f32_16x16x32_bf16 v[48:51], v[180:183], v[188:191], v[48:51]
	v_mfma_f32_16x16x32_bf16 v[48:51], v[184:187], v[192:195], v[48:51]
	v_mfma_f32_16x16x32_bf16 v[36:39], v[170:173], v[196:199], v[36:39]
	v_mfma_f32_16x16x32_bf16 v[36:39], v[176:179], v[200:203], v[36:39]
	v_mfma_f32_16x16x32_bf16 v[32:35], v[180:183], v[196:199], v[32:35]
	v_mfma_f32_16x16x32_bf16 v[32:35], v[184:187], v[200:203], v[32:35]
	v_mfma_f32_16x16x32_bf16 v[20:23], v[170:173], v[204:207], v[20:23]
	v_mfma_f32_16x16x32_bf16 v[20:23], v[176:179], v[208:211], v[20:23]
	v_mfma_f32_16x16x32_bf16 v[16:19], v[180:183], v[204:207], v[16:19]
	v_mfma_f32_16x16x32_bf16 v[16:19], v[184:187], v[208:211], v[16:19]
	v_mfma_f32_16x16x32_bf16 v[4:7], v[170:173], v[212:215], v[4:7]
	v_mfma_f32_16x16x32_bf16 v[4:7], v[176:179], v[216:219], v[4:7]
	v_mfma_f32_16x16x32_bf16 v[0:3], v[180:183], v[212:215], v[0:3]
	v_mfma_f32_16x16x32_bf16 v[0:3], v[184:187], v[216:219], v[0:3]
	s_setprio 0
	s_barrier
	s_add_i32 s66, 0, 0x18000
	v_add_u32_e32 v157, s66, v151
	s_add_i32 s67, 0, 0x1c000
	ds_read_b128 v[144:147], v157
	ds_read_b128 v[158:161], v157 offset:1024
	ds_read_b128 v[162:165], v157 offset:2048
	ds_read_b128 v[166:169], v157 offset:3072
	v_add_u32_e32 v157, s67, v151
	ds_read_b128 v[170:173], v157
	ds_read_b128 v[176:179], v157 offset:1024
	ds_read_b128 v[180:183], v157 offset:2048
	ds_read_b128 v[184:187], v157 offset:3072
	s_add_u32 s46, s46, 0x80000
	s_addc_u32 s47, s47, 0
	s_mov_b32 m0, s14
	ds_read_b128 v[188:191], v155 offset:32768
	ds_read_b128 v[192:195], v155 offset:33792
	ds_read_b128 v[196:199], v155 offset:34816
	ds_read_b128 v[200:203], v155 offset:35840
	ds_read_b128 v[204:207], v155 offset:36864
	ds_read_b128 v[208:211], v155 offset:37888
	ds_read_b128 v[212:215], v155 offset:38912
	ds_read_b128 v[216:219], v155 offset:39936
	global_load_lds_dwordx4 v134, s[46:47]
	s_mov_b32 m0, s15
	s_nop 0
	global_load_lds_dwordx4 v130, s[46:47]
	s_waitcnt vmcnt(8)
	s_waitcnt lgkmcnt(0)
	s_setprio 1
	s_waitcnt lgkmcnt(0)
	v_mfma_f32_16x16x32_bf16 v[124:127], v[144:147], v[188:191], v[124:127]
	v_mfma_f32_16x16x32_bf16 v[124:127], v[158:161], v[192:195], v[124:127]
	v_mfma_f32_16x16x32_bf16 v[120:123], v[162:165], v[188:191], v[120:123]
	v_mfma_f32_16x16x32_bf16 v[120:123], v[166:169], v[192:195], v[120:123]
	v_mfma_f32_16x16x32_bf16 v[108:111], v[144:147], v[196:199], v[108:111]
	v_mfma_f32_16x16x32_bf16 v[108:111], v[158:161], v[200:203], v[108:111]
	v_mfma_f32_16x16x32_bf16 v[104:107], v[162:165], v[196:199], v[104:107]
	v_mfma_f32_16x16x32_bf16 v[104:107], v[166:169], v[200:203], v[104:107]
	v_mfma_f32_16x16x32_bf16 v[92:95], v[144:147], v[204:207], v[92:95]
	v_mfma_f32_16x16x32_bf16 v[92:95], v[158:161], v[208:211], v[92:95]
	v_mfma_f32_16x16x32_bf16 v[88:91], v[162:165], v[204:207], v[88:91]
	v_mfma_f32_16x16x32_bf16 v[88:91], v[166:169], v[208:211], v[88:91]
	v_mfma_f32_16x16x32_bf16 v[76:79], v[144:147], v[212:215], v[76:79]
	v_mfma_f32_16x16x32_bf16 v[76:79], v[158:161], v[216:219], v[76:79]
	v_mfma_f32_16x16x32_bf16 v[72:75], v[162:165], v[212:215], v[72:75]
	v_mfma_f32_16x16x32_bf16 v[72:75], v[166:169], v[216:219], v[72:75]
	s_setprio 0
	s_setprio 1
	v_mfma_f32_16x16x32_bf16 v[116:119], v[170:173], v[188:191], v[116:119]
	v_mfma_f32_16x16x32_bf16 v[116:119], v[176:179], v[192:195], v[116:119]
	v_mfma_f32_16x16x32_bf16 v[112:115], v[180:183], v[188:191], v[112:115]
	v_mfma_f32_16x16x32_bf16 v[112:115], v[184:187], v[192:195], v[112:115]
	v_mfma_f32_16x16x32_bf16 v[100:103], v[170:173], v[196:199], v[100:103]
	v_mfma_f32_16x16x32_bf16 v[100:103], v[176:179], v[200:203], v[100:103]
	v_mfma_f32_16x16x32_bf16 v[96:99], v[180:183], v[196:199], v[96:99]
	v_mfma_f32_16x16x32_bf16 v[96:99], v[184:187], v[200:203], v[96:99]
	v_mfma_f32_16x16x32_bf16 v[84:87], v[170:173], v[204:207], v[84:87]
	v_mfma_f32_16x16x32_bf16 v[84:87], v[176:179], v[208:211], v[84:87]
	v_mfma_f32_16x16x32_bf16 v[80:83], v[180:183], v[204:207], v[80:83]
	v_mfma_f32_16x16x32_bf16 v[80:83], v[184:187], v[208:211], v[80:83]
	v_mfma_f32_16x16x32_bf16 v[68:71], v[170:173], v[212:215], v[68:71]
	v_mfma_f32_16x16x32_bf16 v[68:71], v[176:179], v[216:219], v[68:71]
	v_mfma_f32_16x16x32_bf16 v[64:67], v[180:183], v[212:215], v[64:67]
	v_mfma_f32_16x16x32_bf16 v[64:67], v[184:187], v[216:219], v[64:67]
	s_setprio 0
	s_barrier
	s_add_i32 s46, s66, s0
	s_add_u32 s98, s44, 0x80
	s_addc_u32 s99, s45, 0
	s_mov_b32 m0, s46
	ds_read_b128 v[188:191], v155 offset:49152
	ds_read_b128 v[192:195], v155 offset:50176
	ds_read_b128 v[196:199], v155 offset:51200
	ds_read_b128 v[200:203], v155 offset:52224
	ds_read_b128 v[204:207], v155 offset:53248
	ds_read_b128 v[208:211], v155 offset:54272
	ds_read_b128 v[212:215], v155 offset:55296
	ds_read_b128 v[216:219], v155 offset:56320
	global_load_lds_dwordx4 v132, s[98:99]
	s_add_i32 m0, s46, 0x2000
	s_add_u32 s44, s44, 0x80080
	s_addc_u32 s45, s45, 0
	s_add_i32 s46, s67, s0
	global_load_lds_dwordx4 v128, s[98:99]
	s_mov_b32 m0, s46
	s_nop 0
	global_load_lds_dwordx4 v132, s[44:45]
	s_add_i32 m0, s46, 0x2000
	s_nop 0
	global_load_lds_dwordx4 v128, s[44:45]
	s_mov_b32 m0, s41
	s_nop 0
	global_load_lds_dwordx4 v134, s[100:101]
	s_mov_b32 m0, s48
	s_nop 0
	global_load_lds_dwordx4 v130, s[100:101]
	s_waitcnt vmcnt(8)
	s_waitcnt lgkmcnt(0)
	s_setprio 1
	s_waitcnt lgkmcnt(0)
	v_mfma_f32_16x16x32_bf16 v[60:63], v[144:147], v[188:191], v[60:63]
	v_mfma_f32_16x16x32_bf16 v[60:63], v[158:161], v[192:195], v[60:63]
	v_mfma_f32_16x16x32_bf16 v[56:59], v[162:165], v[188:191], v[56:59]
	v_mfma_f32_16x16x32_bf16 v[56:59], v[166:169], v[192:195], v[56:59]
	v_mfma_f32_16x16x32_bf16 v[44:47], v[144:147], v[196:199], v[44:47]
	v_mfma_f32_16x16x32_bf16 v[44:47], v[158:161], v[200:203], v[44:47]
	v_mfma_f32_16x16x32_bf16 v[40:43], v[162:165], v[196:199], v[40:43]
	v_mfma_f32_16x16x32_bf16 v[40:43], v[166:169], v[200:203], v[40:43]
	v_mfma_f32_16x16x32_bf16 v[28:31], v[144:147], v[204:207], v[28:31]
	v_mfma_f32_16x16x32_bf16 v[28:31], v[158:161], v[208:211], v[28:31]
	v_mfma_f32_16x16x32_bf16 v[24:27], v[162:165], v[204:207], v[24:27]
	v_mfma_f32_16x16x32_bf16 v[24:27], v[166:169], v[208:211], v[24:27]
	v_mfma_f32_16x16x32_bf16 v[12:15], v[144:147], v[212:215], v[12:15]
	v_mfma_f32_16x16x32_bf16 v[12:15], v[158:161], v[216:219], v[12:15]
	v_mfma_f32_16x16x32_bf16 v[8:11], v[162:165], v[212:215], v[8:11]
	v_mfma_f32_16x16x32_bf16 v[8:11], v[166:169], v[216:219], v[8:11]
	s_setprio 0
	s_setprio 1
	v_mfma_f32_16x16x32_bf16 v[52:55], v[170:173], v[188:191], v[52:55]
	v_mfma_f32_16x16x32_bf16 v[52:55], v[176:179], v[192:195], v[52:55]
	v_mfma_f32_16x16x32_bf16 v[48:51], v[180:183], v[188:191], v[48:51]
	v_mfma_f32_16x16x32_bf16 v[48:51], v[184:187], v[192:195], v[48:51]
	v_mfma_f32_16x16x32_bf16 v[36:39], v[170:173], v[196:199], v[36:39]
	v_mfma_f32_16x16x32_bf16 v[36:39], v[176:179], v[200:203], v[36:39]
	v_mfma_f32_16x16x32_bf16 v[32:35], v[180:183], v[196:199], v[32:35]
	v_mfma_f32_16x16x32_bf16 v[32:35], v[184:187], v[200:203], v[32:35]
	v_mfma_f32_16x16x32_bf16 v[20:23], v[170:173], v[204:207], v[20:23]
	v_mfma_f32_16x16x32_bf16 v[20:23], v[176:179], v[208:211], v[20:23]
	v_mfma_f32_16x16x32_bf16 v[16:19], v[180:183], v[204:207], v[16:19]
	v_mfma_f32_16x16x32_bf16 v[16:19], v[184:187], v[208:211], v[16:19]
	v_mfma_f32_16x16x32_bf16 v[4:7], v[170:173], v[212:215], v[4:7]
	v_mfma_f32_16x16x32_bf16 v[4:7], v[176:179], v[216:219], v[4:7]
	v_mfma_f32_16x16x32_bf16 v[0:3], v[180:183], v[212:215], v[0:3]
	v_mfma_f32_16x16x32_bf16 v[0:3], v[184:187], v[216:219], v[0:3]
	s_setprio 0
	s_barrier
	s_add_i32 s65, s65, 2
	s_add_u32 s42, s42, 0x100
	s_addc_u32 s43, s43, 0
	s_add_u32 s63, s63, 0x100
	s_addc_u32 s64, s64, 0
	s_cmp_gt_u32 s65, 29
	s_cbranch_scc0 .LBB0_793
	s_branch .Lp7_kloop_done

.Lp7_kloop_done:
.LBB0_796:
	s_andn2_b64 vcc, exec, s[4:5]
	s_mov_b64 s[4:5], -1
	v_lshl_add_u32 v148, s40, 8, v150
	v_lshl_or_b32 v146, s60, 7, v152
	v_mov_b64_e32 v[144:145], s[12:13]
	v_ashrrev_i32_e32 v147, 31, v146
	s_cmp_eq_u32 s40, s69
	s_cbranch_scc1 .Lp7_epi_cached
	s_mov_b32 s69, s40
	v_add_u32_e32 v160, 64, v148
	v_ashrrev_i32_e32 v161, 31, v160
	v_lshlrev_b64 v[158:159], 5, v[160:161]
	v_lshl_add_u64 v[158:159], s[22:23], 0, v[158:159]
	global_load_dwordx4 v[176:179], v[158:159], off offset:-2048
	global_load_dwordx4 v[180:183], v[158:159], off offset:-2032
	global_load_dwordx4 v[184:187], v[158:159], off offset:-1536
	global_load_dwordx4 v[188:191], v[158:159], off offset:-1520
	global_load_dwordx4 v[192:195], v[158:159], off offset:-1024
	global_load_dwordx4 v[196:199], v[158:159], off offset:-1008
	global_load_dwordx4 v[200:203], v[158:159], off offset:-512
	global_load_dwordx4 v[204:207], v[158:159], off offset:-496
	global_load_dwordx4 v[208:211], v[158:159], off offset:2048
	global_load_dwordx4 v[212:215], v[158:159], off offset:2064
	global_load_dwordx4 v[216:219], v[158:159], off offset:2560
	global_load_dwordx4 v[220:223], v[158:159], off offset:2576
	global_load_dwordx4 v[224:227], v[158:159], off offset:3072
	global_load_dwordx4 v[228:231], v[158:159], off offset:3088
	global_load_dwordx4 v[232:235], v[158:159], off offset:3584
	global_load_dwordx4 v[236:239], v[158:159], off offset:3600
	s_waitcnt vmcnt(14)
	v_add_f32_e32 v176, v176, v177
	v_add_f32_e32 v178, v178, v179
	v_add_f32_e32 v180, v180, v181
	v_add_f32_e32 v182, v182, v183
	v_add_f32_e32 v176, v176, v178
	v_add_f32_e32 v180, v180, v182
	v_add_f32_e32 v176, v176, v180
	v_fmamk_f32 v241, v176, 0x3a000000, v156
	s_waitcnt vmcnt(12)
	v_add_f32_e32 v184, v184, v185
	v_add_f32_e32 v186, v186, v187
	v_add_f32_e32 v188, v188, v189
	v_add_f32_e32 v190, v190, v191
	v_add_f32_e32 v184, v184, v186
	v_add_f32_e32 v188, v188, v190
	v_add_f32_e32 v184, v184, v188
	v_fmamk_f32 v242, v184, 0x3a000000, v156
	s_waitcnt vmcnt(10)
	v_add_f32_e32 v192, v192, v193
	v_add_f32_e32 v194, v194, v195
	v_add_f32_e32 v196, v196, v197
	v_add_f32_e32 v198, v198, v199
	v_add_f32_e32 v192, v192, v194
	v_add_f32_e32 v196, v196, v198
	v_add_f32_e32 v192, v192, v196
	v_fmamk_f32 v243, v192, 0x3a000000, v156
	s_waitcnt vmcnt(8)
	v_add_f32_e32 v200, v200, v201
	v_add_f32_e32 v202, v202, v203
	v_add_f32_e32 v204, v204, v205
	v_add_f32_e32 v206, v206, v207
	v_add_f32_e32 v200, v200, v202
	v_add_f32_e32 v204, v204, v206
	v_add_f32_e32 v200, v200, v204
	v_fmamk_f32 v244, v200, 0x3a000000, v156
	s_waitcnt vmcnt(6)
	v_add_f32_e32 v208, v208, v209
	v_add_f32_e32 v210, v210, v211
	v_add_f32_e32 v212, v212, v213
	v_add_f32_e32 v214, v214, v215
	v_add_f32_e32 v208, v208, v210
	v_add_f32_e32 v212, v212, v214
	v_add_f32_e32 v208, v208, v212
	v_fmamk_f32 v245, v208, 0x3a000000, v156
	s_waitcnt vmcnt(4)
	v_add_f32_e32 v216, v216, v217
	v_add_f32_e32 v218, v218, v219
	v_add_f32_e32 v220, v220, v221
	v_add_f32_e32 v222, v222, v223
	v_add_f32_e32 v216, v216, v218
	v_add_f32_e32 v220, v220, v222
	v_add_f32_e32 v216, v216, v220
	v_fmamk_f32 v246, v216, 0x3a000000, v156
	s_waitcnt vmcnt(2)
	v_add_f32_e32 v224, v224, v225
	v_add_f32_e32 v226, v226, v227
	v_add_f32_e32 v228, v228, v229
	v_add_f32_e32 v230, v230, v231
	v_add_f32_e32 v224, v224, v226
	v_add_f32_e32 v228, v228, v230
	v_add_f32_e32 v224, v224, v228
	v_fmamk_f32 v247, v224, 0x3a000000, v156
	s_waitcnt vmcnt(0)
	v_add_f32_e32 v232, v232, v233
	v_add_f32_e32 v234, v234, v235
	v_add_f32_e32 v236, v236, v237
	v_add_f32_e32 v238, v238, v239
	v_add_f32_e32 v232, v232, v234
	v_add_f32_e32 v236, v236, v238
	v_add_f32_e32 v232, v232, v236
	v_fmamk_f32 v248, v232, 0x3a000000, v156
.Lp7_epi_cached:
	v_mad_i64_i32 v[160:161], s[42:43], v148, s51, v[144:145]
	v_lshlrev_b64 v[146:147], 1, v[146:147]
	s_mov_b32 s66, 0x2c000
	s_mov_b32 s67, 0
	v_lshl_add_u64 v[160:161], v[160:161], 0, v[146:147]
	v_rsq_f32_e32 v176, v241
	v_pk_mul_f32 v[116:117], v[124:125], v[116:117]
	v_pk_mul_f32 v[118:119], v[126:127], v[118:119]
	v_pk_mul_f32 v[112:113], v[120:121], v[112:113]
	v_pk_mul_f32 v[114:115], v[122:123], v[114:115]
	v_mul_f32_e32 v177, 0xbfb8aa3b, v176
	v_mul_f32_e32 v162, v177, v124
	v_mul_f32_e32 v163, v177, v125
	v_mul_f32_e32 v164, v177, v126
	v_mul_f32_e32 v165, v177, v127
	v_mul_f32_e32 v166, v177, v120
	v_mul_f32_e32 v167, v177, v121
	v_mul_f32_e32 v168, v177, v122
	v_mul_f32_e32 v169, v177, v123
	v_exp_f32_e32 v162, v162
	v_exp_f32_e32 v163, v163
	v_exp_f32_e32 v164, v164
	v_exp_f32_e32 v165, v165
	v_exp_f32_e32 v166, v166
	v_exp_f32_e32 v167, v167
	v_exp_f32_e32 v168, v168
	v_exp_f32_e32 v169, v169
	v_fma_f32 v162, v162, v241, v241
	v_fma_f32 v163, v163, v241, v241
	v_fma_f32 v164, v164, v241, v241
	v_fma_f32 v165, v165, v241, v241
	v_fma_f32 v166, v166, v241, v241
	v_fma_f32 v167, v167, v241, v241
	v_fma_f32 v168, v168, v241, v241
	v_fma_f32 v169, v169, v241, v241
	v_rcp_f32_e32 v162, v162
	v_rcp_f32_e32 v163, v163
	v_rcp_f32_e32 v164, v164
	v_rcp_f32_e32 v165, v165
	v_rcp_f32_e32 v166, v166
	v_rcp_f32_e32 v167, v167
	v_rcp_f32_e32 v168, v168
	v_rcp_f32_e32 v169, v169
	v_pk_mul_f32 v[116:117], v[116:117], v[162:163]
	v_pk_mul_f32 v[118:119], v[118:119], v[164:165]
	v_pk_mul_f32 v[112:113], v[112:113], v[166:167]
	v_pk_mul_f32 v[114:115], v[114:115], v[168:169]
	v_cvt_pk_bf16_f32 v170, v116, v117
	v_cvt_pk_bf16_f32 v171, v118, v119
	v_cvt_pk_bf16_f32 v172, v112, v113
	v_cvt_pk_bf16_f32 v173, v114, v115
	global_store_dwordx4 v[160:161], v[170:173], off
	v_lshl_add_u64 v[160:161], v[160:161], 0, s[66:67]
	v_rsq_f32_e32 v176, v242
	v_pk_mul_f32 v[100:101], v[108:109], v[100:101]
	v_pk_mul_f32 v[102:103], v[110:111], v[102:103]
	v_pk_mul_f32 v[96:97], v[104:105], v[96:97]
	v_pk_mul_f32 v[98:99], v[106:107], v[98:99]
	v_mul_f32_e32 v177, 0xbfb8aa3b, v176
	v_mul_f32_e32 v162, v177, v108
	v_mul_f32_e32 v163, v177, v109
	v_mul_f32_e32 v164, v177, v110
	v_mul_f32_e32 v165, v177, v111
	v_mul_f32_e32 v166, v177, v104
	v_mul_f32_e32 v167, v177, v105
	v_mul_f32_e32 v168, v177, v106
	v_mul_f32_e32 v169, v177, v107
	v_exp_f32_e32 v162, v162
	v_exp_f32_e32 v163, v163
	v_exp_f32_e32 v164, v164
	v_exp_f32_e32 v165, v165
	v_exp_f32_e32 v166, v166
	v_exp_f32_e32 v167, v167
	v_exp_f32_e32 v168, v168
	v_exp_f32_e32 v169, v169
	v_fma_f32 v162, v162, v242, v242
	v_fma_f32 v163, v163, v242, v242
	v_fma_f32 v164, v164, v242, v242
	v_fma_f32 v165, v165, v242, v242
	v_fma_f32 v166, v166, v242, v242
	v_fma_f32 v167, v167, v242, v242
	v_fma_f32 v168, v168, v242, v242
	v_fma_f32 v169, v169, v242, v242
	v_rcp_f32_e32 v162, v162
	v_rcp_f32_e32 v163, v163
	v_rcp_f32_e32 v164, v164
	v_rcp_f32_e32 v165, v165
	v_rcp_f32_e32 v166, v166
	v_rcp_f32_e32 v167, v167
	v_rcp_f32_e32 v168, v168
	v_rcp_f32_e32 v169, v169
	v_pk_mul_f32 v[100:101], v[100:101], v[162:163]
	v_pk_mul_f32 v[102:103], v[102:103], v[164:165]
	v_pk_mul_f32 v[96:97], v[96:97], v[166:167]
	v_pk_mul_f32 v[98:99], v[98:99], v[168:169]
	v_cvt_pk_bf16_f32 v170, v100, v101
	v_cvt_pk_bf16_f32 v171, v102, v103
	v_cvt_pk_bf16_f32 v172, v96, v97
	v_cvt_pk_bf16_f32 v173, v98, v99
	global_store_dwordx4 v[160:161], v[170:173], off
	v_lshl_add_u64 v[160:161], v[160:161], 0, s[66:67]
	v_rsq_f32_e32 v176, v243
	v_pk_mul_f32 v[84:85], v[92:93], v[84:85]
	v_pk_mul_f32 v[86:87], v[94:95], v[86:87]
	v_pk_mul_f32 v[80:81], v[88:89], v[80:81]
	v_pk_mul_f32 v[82:83], v[90:91], v[82:83]
	v_mul_f32_e32 v177, 0xbfb8aa3b, v176
	v_mul_f32_e32 v162, v177, v92
	v_mul_f32_e32 v163, v177, v93
	v_mul_f32_e32 v164, v177, v94
	v_mul_f32_e32 v165, v177, v95
	v_mul_f32_e32 v166, v177, v88
	v_mul_f32_e32 v167, v177, v89
	v_mul_f32_e32 v168, v177, v90
	v_mul_f32_e32 v169, v177, v91
	v_exp_f32_e32 v162, v162
	v_exp_f32_e32 v163, v163
	v_exp_f32_e32 v164, v164
	v_exp_f32_e32 v165, v165
	v_exp_f32_e32 v166, v166
	v_exp_f32_e32 v167, v167
	v_exp_f32_e32 v168, v168
	v_exp_f32_e32 v169, v169
	v_fma_f32 v162, v162, v243, v243
	v_fma_f32 v163, v163, v243, v243
	v_fma_f32 v164, v164, v243, v243
	v_fma_f32 v165, v165, v243, v243
	v_fma_f32 v166, v166, v243, v243
	v_fma_f32 v167, v167, v243, v243
	v_fma_f32 v168, v168, v243, v243
	v_fma_f32 v169, v169, v243, v243
	v_rcp_f32_e32 v162, v162
	v_rcp_f32_e32 v163, v163
	v_rcp_f32_e32 v164, v164
	v_rcp_f32_e32 v165, v165
	v_rcp_f32_e32 v166, v166
	v_rcp_f32_e32 v167, v167
	v_rcp_f32_e32 v168, v168
	v_rcp_f32_e32 v169, v169
	v_pk_mul_f32 v[84:85], v[84:85], v[162:163]
	v_pk_mul_f32 v[86:87], v[86:87], v[164:165]
	v_pk_mul_f32 v[80:81], v[80:81], v[166:167]
	v_pk_mul_f32 v[82:83], v[82:83], v[168:169]
	v_cvt_pk_bf16_f32 v170, v84, v85
	v_cvt_pk_bf16_f32 v171, v86, v87
	v_cvt_pk_bf16_f32 v172, v80, v81
	v_cvt_pk_bf16_f32 v173, v82, v83
	global_store_dwordx4 v[160:161], v[170:173], off
	v_lshl_add_u64 v[160:161], v[160:161], 0, s[66:67]
	v_rsq_f32_e32 v176, v244
	v_pk_mul_f32 v[68:69], v[76:77], v[68:69]
	v_pk_mul_f32 v[70:71], v[78:79], v[70:71]
	v_pk_mul_f32 v[64:65], v[72:73], v[64:65]
	v_pk_mul_f32 v[66:67], v[74:75], v[66:67]
	v_mul_f32_e32 v177, 0xbfb8aa3b, v176
	v_mul_f32_e32 v162, v177, v76
	v_mul_f32_e32 v163, v177, v77
	v_mul_f32_e32 v164, v177, v78
	v_mul_f32_e32 v165, v177, v79
	v_mul_f32_e32 v166, v177, v72
	v_mul_f32_e32 v167, v177, v73
	v_mul_f32_e32 v168, v177, v74
	v_mul_f32_e32 v169, v177, v75
	v_exp_f32_e32 v162, v162
	v_exp_f32_e32 v163, v163
	v_exp_f32_e32 v164, v164
	v_exp_f32_e32 v165, v165
	v_exp_f32_e32 v166, v166
	v_exp_f32_e32 v167, v167
	v_exp_f32_e32 v168, v168
	v_exp_f32_e32 v169, v169
	v_fma_f32 v162, v162, v244, v244
	v_fma_f32 v163, v163, v244, v244
	v_fma_f32 v164, v164, v244, v244
	v_fma_f32 v165, v165, v244, v244
	v_fma_f32 v166, v166, v244, v244
	v_fma_f32 v167, v167, v244, v244
	v_fma_f32 v168, v168, v244, v244
	v_fma_f32 v169, v169, v244, v244
	v_rcp_f32_e32 v162, v162
	v_rcp_f32_e32 v163, v163
	v_rcp_f32_e32 v164, v164
	v_rcp_f32_e32 v165, v165
	v_rcp_f32_e32 v166, v166
	v_rcp_f32_e32 v167, v167
	v_rcp_f32_e32 v168, v168
	v_rcp_f32_e32 v169, v169
	v_pk_mul_f32 v[68:69], v[68:69], v[162:163]
	v_pk_mul_f32 v[70:71], v[70:71], v[164:165]
	v_pk_mul_f32 v[64:65], v[64:65], v[166:167]
	v_pk_mul_f32 v[66:67], v[66:67], v[168:169]
	v_cvt_pk_bf16_f32 v170, v68, v69
	v_cvt_pk_bf16_f32 v171, v70, v71
	v_cvt_pk_bf16_f32 v172, v64, v65
	v_cvt_pk_bf16_f32 v173, v66, v67
	global_store_dwordx4 v[160:161], v[170:173], off
	s_mov_b32 s66, 0xdc000
	v_lshl_add_u64 v[160:161], v[160:161], 0, s[66:67]
	v_rsq_f32_e32 v176, v245
	v_pk_mul_f32 v[52:53], v[60:61], v[52:53]
	v_pk_mul_f32 v[54:55], v[62:63], v[54:55]
	v_pk_mul_f32 v[48:49], v[56:57], v[48:49]
	v_pk_mul_f32 v[50:51], v[58:59], v[50:51]
	v_mul_f32_e32 v177, 0xbfb8aa3b, v176
	v_mul_f32_e32 v162, v177, v60
	v_mul_f32_e32 v163, v177, v61
	v_mul_f32_e32 v164, v177, v62
	v_mul_f32_e32 v165, v177, v63
	v_mul_f32_e32 v166, v177, v56
	v_mul_f32_e32 v167, v177, v57
	v_mul_f32_e32 v168, v177, v58
	v_mul_f32_e32 v169, v177, v59
	v_exp_f32_e32 v162, v162
	v_exp_f32_e32 v163, v163
	v_exp_f32_e32 v164, v164
	v_exp_f32_e32 v165, v165
	v_exp_f32_e32 v166, v166
	v_exp_f32_e32 v167, v167
	v_exp_f32_e32 v168, v168
	v_exp_f32_e32 v169, v169
	v_fma_f32 v162, v162, v245, v245
	v_fma_f32 v163, v163, v245, v245
	v_fma_f32 v164, v164, v245, v245
	v_fma_f32 v165, v165, v245, v245
	v_fma_f32 v166, v166, v245, v245
	v_fma_f32 v167, v167, v245, v245
	v_fma_f32 v168, v168, v245, v245
	v_fma_f32 v169, v169, v245, v245
	v_rcp_f32_e32 v162, v162
	v_rcp_f32_e32 v163, v163
	v_rcp_f32_e32 v164, v164
	v_rcp_f32_e32 v165, v165
	v_rcp_f32_e32 v166, v166
	v_rcp_f32_e32 v167, v167
	v_rcp_f32_e32 v168, v168
	v_rcp_f32_e32 v169, v169
	v_pk_mul_f32 v[52:53], v[52:53], v[162:163]
	v_pk_mul_f32 v[54:55], v[54:55], v[164:165]
	v_pk_mul_f32 v[48:49], v[48:49], v[166:167]
	v_pk_mul_f32 v[50:51], v[50:51], v[168:169]
	v_cvt_pk_bf16_f32 v170, v52, v53
	v_cvt_pk_bf16_f32 v171, v54, v55
	v_cvt_pk_bf16_f32 v172, v48, v49
	v_cvt_pk_bf16_f32 v173, v50, v51
	global_store_dwordx4 v[160:161], v[170:173], off
	s_mov_b32 s66, 0x2c000
	v_lshl_add_u64 v[160:161], v[160:161], 0, s[66:67]
	v_rsq_f32_e32 v176, v246
	v_pk_mul_f32 v[36:37], v[44:45], v[36:37]
	v_pk_mul_f32 v[38:39], v[46:47], v[38:39]
	v_pk_mul_f32 v[32:33], v[40:41], v[32:33]
	v_pk_mul_f32 v[34:35], v[42:43], v[34:35]
	v_mul_f32_e32 v177, 0xbfb8aa3b, v176
	v_mul_f32_e32 v162, v177, v44
	v_mul_f32_e32 v163, v177, v45
	v_mul_f32_e32 v164, v177, v46
	v_mul_f32_e32 v165, v177, v47
	v_mul_f32_e32 v166, v177, v40
	v_mul_f32_e32 v167, v177, v41
	v_mul_f32_e32 v168, v177, v42
	v_mul_f32_e32 v169, v177, v43
	v_exp_f32_e32 v162, v162
	v_exp_f32_e32 v163, v163
	v_exp_f32_e32 v164, v164
	v_exp_f32_e32 v165, v165
	v_exp_f32_e32 v166, v166
	v_exp_f32_e32 v167, v167
	v_exp_f32_e32 v168, v168
	v_exp_f32_e32 v169, v169
	v_fma_f32 v162, v162, v246, v246
	v_fma_f32 v163, v163, v246, v246
	v_fma_f32 v164, v164, v246, v246
	v_fma_f32 v165, v165, v246, v246
	v_fma_f32 v166, v166, v246, v246
	v_fma_f32 v167, v167, v246, v246
	v_fma_f32 v168, v168, v246, v246
	v_fma_f32 v169, v169, v246, v246
	v_rcp_f32_e32 v162, v162
	v_rcp_f32_e32 v163, v163
	v_rcp_f32_e32 v164, v164
	v_rcp_f32_e32 v165, v165
	v_rcp_f32_e32 v166, v166
	v_rcp_f32_e32 v167, v167
	v_rcp_f32_e32 v168, v168
	v_rcp_f32_e32 v169, v169
	v_pk_mul_f32 v[36:37], v[36:37], v[162:163]
	v_pk_mul_f32 v[38:39], v[38:39], v[164:165]
	v_pk_mul_f32 v[32:33], v[32:33], v[166:167]
	v_pk_mul_f32 v[34:35], v[34:35], v[168:169]
	v_cvt_pk_bf16_f32 v170, v36, v37
	v_cvt_pk_bf16_f32 v171, v38, v39
	v_cvt_pk_bf16_f32 v172, v32, v33
	v_cvt_pk_bf16_f32 v173, v34, v35
	global_store_dwordx4 v[160:161], v[170:173], off
	v_lshl_add_u64 v[160:161], v[160:161], 0, s[66:67]
	v_rsq_f32_e32 v176, v247
	v_pk_mul_f32 v[20:21], v[28:29], v[20:21]
	v_pk_mul_f32 v[22:23], v[30:31], v[22:23]
	v_pk_mul_f32 v[16:17], v[24:25], v[16:17]
	v_pk_mul_f32 v[18:19], v[26:27], v[18:19]
	v_mul_f32_e32 v177, 0xbfb8aa3b, v176
	v_mul_f32_e32 v162, v177, v28
	v_mul_f32_e32 v163, v177, v29
	v_mul_f32_e32 v164, v177, v30
	v_mul_f32_e32 v165, v177, v31
	v_mul_f32_e32 v166, v177, v24
	v_mul_f32_e32 v167, v177, v25
	v_mul_f32_e32 v168, v177, v26
	v_mul_f32_e32 v169, v177, v27
	v_exp_f32_e32 v162, v162
	v_exp_f32_e32 v163, v163
	v_exp_f32_e32 v164, v164
	v_exp_f32_e32 v165, v165
	v_exp_f32_e32 v166, v166
	v_exp_f32_e32 v167, v167
	v_exp_f32_e32 v168, v168
	v_exp_f32_e32 v169, v169
	v_fma_f32 v162, v162, v247, v247
	v_fma_f32 v163, v163, v247, v247
	v_fma_f32 v164, v164, v247, v247
	v_fma_f32 v165, v165, v247, v247
	v_fma_f32 v166, v166, v247, v247
	v_fma_f32 v167, v167, v247, v247
	v_fma_f32 v168, v168, v247, v247
	v_fma_f32 v169, v169, v247, v247
	v_rcp_f32_e32 v162, v162
	v_rcp_f32_e32 v163, v163
	v_rcp_f32_e32 v164, v164
	v_rcp_f32_e32 v165, v165
	v_rcp_f32_e32 v166, v166
	v_rcp_f32_e32 v167, v167
	v_rcp_f32_e32 v168, v168
	v_rcp_f32_e32 v169, v169
	v_pk_mul_f32 v[20:21], v[20:21], v[162:163]
	v_pk_mul_f32 v[22:23], v[22:23], v[164:165]
	v_pk_mul_f32 v[16:17], v[16:17], v[166:167]
	v_pk_mul_f32 v[18:19], v[18:19], v[168:169]
	v_cvt_pk_bf16_f32 v170, v20, v21
	v_cvt_pk_bf16_f32 v171, v22, v23
	v_cvt_pk_bf16_f32 v172, v16, v17
	v_cvt_pk_bf16_f32 v173, v18, v19
	global_store_dwordx4 v[160:161], v[170:173], off
	v_lshl_add_u64 v[160:161], v[160:161], 0, s[66:67]
	v_rsq_f32_e32 v176, v248
	v_pk_mul_f32 v[4:5], v[12:13], v[4:5]
	v_pk_mul_f32 v[6:7], v[14:15], v[6:7]
	v_pk_mul_f32 v[0:1], v[8:9], v[0:1]
	v_pk_mul_f32 v[2:3], v[10:11], v[2:3]
	v_mul_f32_e32 v177, 0xbfb8aa3b, v176
	v_mul_f32_e32 v162, v177, v12
	v_mul_f32_e32 v163, v177, v13
	v_mul_f32_e32 v164, v177, v14
	v_mul_f32_e32 v165, v177, v15
	v_mul_f32_e32 v166, v177, v8
	v_mul_f32_e32 v167, v177, v9
	v_mul_f32_e32 v168, v177, v10
	v_mul_f32_e32 v169, v177, v11
	v_exp_f32_e32 v162, v162
	v_exp_f32_e32 v163, v163
	v_exp_f32_e32 v164, v164
	v_exp_f32_e32 v165, v165
	v_exp_f32_e32 v166, v166
	v_exp_f32_e32 v167, v167
	v_exp_f32_e32 v168, v168
	v_exp_f32_e32 v169, v169
	v_fma_f32 v162, v162, v248, v248
	v_fma_f32 v163, v163, v248, v248
	v_fma_f32 v164, v164, v248, v248
	v_fma_f32 v165, v165, v248, v248
	v_fma_f32 v166, v166, v248, v248
	v_fma_f32 v167, v167, v248, v248
	v_fma_f32 v168, v168, v248, v248
	v_fma_f32 v169, v169, v248, v248
	v_rcp_f32_e32 v162, v162
	v_rcp_f32_e32 v163, v163
	v_rcp_f32_e32 v164, v164
	v_rcp_f32_e32 v165, v165
	v_rcp_f32_e32 v166, v166
	v_rcp_f32_e32 v167, v167
	v_rcp_f32_e32 v168, v168
	v_rcp_f32_e32 v169, v169
	v_pk_mul_f32 v[4:5], v[4:5], v[162:163]
	v_pk_mul_f32 v[6:7], v[6:7], v[164:165]
	v_pk_mul_f32 v[0:1], v[0:1], v[166:167]
	v_pk_mul_f32 v[2:3], v[2:3], v[168:169]
	v_cvt_pk_bf16_f32 v170, v4, v5
	v_cvt_pk_bf16_f32 v171, v6, v7
	v_cvt_pk_bf16_f32 v172, v0, v1
	v_cvt_pk_bf16_f32 v173, v2, v3
	global_store_dwordx4 v[160:161], v[170:173], off
	s_cbranch_vccnz .LBB0_789
	s_branch .LBB0_788

.LBB0_873:
	ds_read_b128 v[128:131], v192
	ds_read_b128 v[132:135], v192 offset:1024
	ds_read_b128 v[136:139], v192 offset:2048
	ds_read_b128 v[140:143], v192 offset:3072
	ds_read_b128 v[144:147], v193
	ds_read_b128 v[148:151], v193 offset:1024
	ds_read_b128 v[168:171], v193 offset:2048
	ds_read_b128 v[196:199], v193 offset:3072
	s_add_u32 s34, s26, 0x100
	s_addc_u32 s35, s27, 0
	s_cmpk_eq_i32 s51, 0x54
	s_cselect_b32 s39, s1, s35
	s_cselect_b32 s38, s0, s34
	s_cselect_b32 s37, s25, s50
	s_cselect_b32 s36, s24, s49
	v_lshl_add_u64 v[172:173], s[26:27], 0, v[160:161]
	s_add_i32 m0, s11, 0xc000
	ds_read_b128 v[200:203], v194
	ds_read_b128 v[204:207], v194 offset:1024
	ds_read_b128 v[208:211], v194 offset:2048
	ds_read_b128 v[212:215], v194 offset:3072
	ds_read_b128 v[216:219], v194 offset:4096
	ds_read_b128 v[220:223], v194 offset:5120
	ds_read_b128 v[224:227], v194 offset:6144
	ds_read_b128 v[228:231], v194 offset:7168
	global_load_lds_dwordx4 v[172:173], off
	v_lshl_add_u64 v[172:173], s[26:27], 0, v[162:163]
	s_add_i32 m0, s11, 0xe000
	s_nop 0
	global_load_lds_dwordx4 v[172:173], off
	s_waitcnt vmcnt(8)
	s_waitcnt lgkmcnt(0)
	s_barrier
	s_setprio 1
	s_waitcnt lgkmcnt(0)
	v_mfma_f32_16x16x32_bf16 v[124:127], v[128:131], v[200:203], v[124:127]
	v_mfma_f32_16x16x32_bf16 v[124:127], v[132:135], v[204:207], v[124:127]
	v_mfma_f32_16x16x32_bf16 v[120:123], v[136:139], v[200:203], v[120:123]
	v_mfma_f32_16x16x32_bf16 v[120:123], v[140:143], v[204:207], v[120:123]
	v_mfma_f32_16x16x32_bf16 v[108:111], v[128:131], v[208:211], v[108:111]
	v_mfma_f32_16x16x32_bf16 v[108:111], v[132:135], v[212:215], v[108:111]
	v_mfma_f32_16x16x32_bf16 v[104:107], v[136:139], v[208:211], v[104:107]
	v_mfma_f32_16x16x32_bf16 v[104:107], v[140:143], v[212:215], v[104:107]
	v_mfma_f32_16x16x32_bf16 v[92:95], v[128:131], v[216:219], v[92:95]
	v_mfma_f32_16x16x32_bf16 v[92:95], v[132:135], v[220:223], v[92:95]
	v_mfma_f32_16x16x32_bf16 v[88:91], v[136:139], v[216:219], v[88:91]
	v_mfma_f32_16x16x32_bf16 v[88:91], v[140:143], v[220:223], v[88:91]
	v_mfma_f32_16x16x32_bf16 v[76:79], v[128:131], v[224:227], v[76:79]
	v_mfma_f32_16x16x32_bf16 v[76:79], v[132:135], v[228:231], v[76:79]
	v_mfma_f32_16x16x32_bf16 v[72:75], v[136:139], v[224:227], v[72:75]
	v_mfma_f32_16x16x32_bf16 v[72:75], v[140:143], v[228:231], v[72:75]
	s_setprio 0
	s_setprio 1
	v_mfma_f32_16x16x32_bf16 v[116:119], v[144:147], v[200:203], v[116:119]
	v_mfma_f32_16x16x32_bf16 v[116:119], v[148:151], v[204:207], v[116:119]
	v_mfma_f32_16x16x32_bf16 v[112:115], v[168:171], v[200:203], v[112:115]
	v_mfma_f32_16x16x32_bf16 v[112:115], v[196:199], v[204:207], v[112:115]
	v_mfma_f32_16x16x32_bf16 v[100:103], v[144:147], v[208:211], v[100:103]
	v_mfma_f32_16x16x32_bf16 v[100:103], v[148:151], v[212:215], v[100:103]
	v_mfma_f32_16x16x32_bf16 v[96:99], v[168:171], v[208:211], v[96:99]
	v_mfma_f32_16x16x32_bf16 v[96:99], v[196:199], v[212:215], v[96:99]
	v_mfma_f32_16x16x32_bf16 v[84:87], v[144:147], v[216:219], v[84:87]
	v_mfma_f32_16x16x32_bf16 v[84:87], v[148:151], v[220:223], v[84:87]
	v_mfma_f32_16x16x32_bf16 v[80:83], v[168:171], v[216:219], v[80:83]
	v_mfma_f32_16x16x32_bf16 v[80:83], v[196:199], v[220:223], v[80:83]
	v_mfma_f32_16x16x32_bf16 v[68:71], v[144:147], v[224:227], v[68:71]
	v_mfma_f32_16x16x32_bf16 v[68:71], v[148:151], v[228:231], v[68:71]
	v_mfma_f32_16x16x32_bf16 v[64:67], v[168:171], v[224:227], v[64:67]
	v_mfma_f32_16x16x32_bf16 v[64:67], v[196:199], v[228:231], v[64:67]
	s_setprio 0
	s_barrier
	s_add_i32 s26, s45, s10
	v_lshl_add_u64 v[172:173], s[36:37], 0, v[154:155]
	s_mov_b32 m0, s26
	ds_read_b128 v[200:203], v194 offset:16384
	ds_read_b128 v[204:207], v194 offset:17408
	ds_read_b128 v[208:211], v194 offset:18432
	ds_read_b128 v[212:215], v194 offset:19456
	ds_read_b128 v[216:219], v194 offset:20480
	ds_read_b128 v[220:223], v194 offset:21504
	ds_read_b128 v[224:227], v194 offset:22528
	ds_read_b128 v[228:231], v194 offset:23552
	global_load_lds_dwordx4 v[172:173], off
	s_add_i32 m0, s26, 0x2000
	s_add_u32 s26, s36, 0x160000
	v_lshl_add_u64 v[232:233], s[36:37], 0, v[158:159]
	s_addc_u32 s27, s37, 0
	s_add_i32 s60, s46, s10
	global_load_lds_dwordx4 v[232:233], off
	v_lshl_add_u64 v[234:235], s[26:27], 0, v[154:155]
	s_mov_b32 m0, s60
	v_lshl_add_u64 v[236:237], s[38:39], 0, v[156:157]
	global_load_lds_dwordx4 v[234:235], off
	v_lshl_add_u64 v[234:235], s[26:27], 0, v[158:159]
	s_add_i32 m0, s60, 0x2000
	s_nop 0
	global_load_lds_dwordx4 v[234:235], off
	v_lshl_add_u64 v[234:235], s[38:39], 0, v[152:153]
	s_mov_b32 m0, s11
	s_nop 0
	global_load_lds_dwordx4 v[234:235], off
	s_mov_b32 m0, s33
	s_nop 0
	global_load_lds_dwordx4 v[236:237], off
	s_waitcnt vmcnt(8)
	s_waitcnt lgkmcnt(0)
	s_barrier
	s_setprio 1
	s_waitcnt lgkmcnt(0)
	v_mfma_f32_16x16x32_bf16 v[60:63], v[128:131], v[200:203], v[60:63]
	v_mfma_f32_16x16x32_bf16 v[60:63], v[132:135], v[204:207], v[60:63]
	v_mfma_f32_16x16x32_bf16 v[56:59], v[136:139], v[200:203], v[56:59]
	v_mfma_f32_16x16x32_bf16 v[56:59], v[140:143], v[204:207], v[56:59]
	v_mfma_f32_16x16x32_bf16 v[44:47], v[128:131], v[208:211], v[44:47]
	v_mfma_f32_16x16x32_bf16 v[44:47], v[132:135], v[212:215], v[44:47]
	v_mfma_f32_16x16x32_bf16 v[40:43], v[136:139], v[208:211], v[40:43]
	v_mfma_f32_16x16x32_bf16 v[40:43], v[140:143], v[212:215], v[40:43]
	v_mfma_f32_16x16x32_bf16 v[28:31], v[128:131], v[216:219], v[28:31]
	v_mfma_f32_16x16x32_bf16 v[28:31], v[132:135], v[220:223], v[28:31]
	v_mfma_f32_16x16x32_bf16 v[24:27], v[136:139], v[216:219], v[24:27]
	v_mfma_f32_16x16x32_bf16 v[24:27], v[140:143], v[220:223], v[24:27]
	v_mfma_f32_16x16x32_bf16 v[12:15], v[128:131], v[224:227], v[12:15]
	v_mfma_f32_16x16x32_bf16 v[12:15], v[132:135], v[228:231], v[12:15]
	v_mfma_f32_16x16x32_bf16 v[8:11], v[136:139], v[224:227], v[8:11]
	v_mfma_f32_16x16x32_bf16 v[8:11], v[140:143], v[228:231], v[8:11]
	s_setprio 0
	s_setprio 1
	v_mfma_f32_16x16x32_bf16 v[52:55], v[144:147], v[200:203], v[52:55]
	v_mfma_f32_16x16x32_bf16 v[52:55], v[148:151], v[204:207], v[52:55]
	v_mfma_f32_16x16x32_bf16 v[48:51], v[168:171], v[200:203], v[48:51]
	v_mfma_f32_16x16x32_bf16 v[48:51], v[196:199], v[204:207], v[48:51]
	v_mfma_f32_16x16x32_bf16 v[36:39], v[144:147], v[208:211], v[36:39]
	v_mfma_f32_16x16x32_bf16 v[36:39], v[148:151], v[212:215], v[36:39]
	v_mfma_f32_16x16x32_bf16 v[32:35], v[168:171], v[208:211], v[32:35]
	v_mfma_f32_16x16x32_bf16 v[32:35], v[196:199], v[212:215], v[32:35]
	v_mfma_f32_16x16x32_bf16 v[20:23], v[144:147], v[216:219], v[20:23]
	v_mfma_f32_16x16x32_bf16 v[20:23], v[148:151], v[220:223], v[20:23]
	v_mfma_f32_16x16x32_bf16 v[16:19], v[168:171], v[216:219], v[16:19]
	v_mfma_f32_16x16x32_bf16 v[16:19], v[196:199], v[220:223], v[16:19]
	v_mfma_f32_16x16x32_bf16 v[4:7], v[144:147], v[224:227], v[4:7]
	v_mfma_f32_16x16x32_bf16 v[4:7], v[148:151], v[228:231], v[4:7]
	v_mfma_f32_16x16x32_bf16 v[0:3], v[168:171], v[224:227], v[0:3]
	v_mfma_f32_16x16x32_bf16 v[0:3], v[196:199], v[228:231], v[0:3]
	s_setprio 0
	s_barrier
	s_add_i32 s60, 0, 0x18000
	s_add_i32 s61, 0, 0x1c000
	v_add_u32_e32 v140, s60, v177
	v_add_u32_e32 v196, s61, v177
	ds_read_b128 v[128:131], v140
	ds_read_b128 v[132:135], v140 offset:1024
	ds_read_b128 v[136:139], v140 offset:2048
	ds_read_b128 v[140:143], v140 offset:3072
	ds_read_b128 v[144:147], v196
	ds_read_b128 v[148:151], v196 offset:1024
	ds_read_b128 v[168:171], v196 offset:2048
	ds_read_b128 v[196:199], v196 offset:3072
	s_add_u32 s26, s38, 0x160000
	s_addc_u32 s27, s39, 0
	s_mov_b32 m0, s40
	v_lshl_add_u64 v[238:239], s[26:27], 0, v[152:153]
	ds_read_b128 v[200:203], v194 offset:32768
	ds_read_b128 v[204:207], v194 offset:33792
	ds_read_b128 v[208:211], v194 offset:34816
	ds_read_b128 v[212:215], v194 offset:35840
	ds_read_b128 v[216:219], v194 offset:36864
	ds_read_b128 v[220:223], v194 offset:37888
	ds_read_b128 v[224:227], v194 offset:38912
	ds_read_b128 v[228:231], v194 offset:39936
	global_load_lds_dwordx4 v[238:239], off
	v_lshl_add_u64 v[238:239], s[26:27], 0, v[156:157]
	s_mov_b32 m0, s41
	s_nop 0
	global_load_lds_dwordx4 v[238:239], off
	s_waitcnt vmcnt(8)
	s_waitcnt lgkmcnt(0)
	s_barrier
	s_setprio 1
	s_waitcnt lgkmcnt(0)
	v_mfma_f32_16x16x32_bf16 v[124:127], v[128:131], v[200:203], v[124:127]
	v_mfma_f32_16x16x32_bf16 v[124:127], v[132:135], v[204:207], v[124:127]
	v_mfma_f32_16x16x32_bf16 v[120:123], v[136:139], v[200:203], v[120:123]
	v_mfma_f32_16x16x32_bf16 v[120:123], v[140:143], v[204:207], v[120:123]
	v_mfma_f32_16x16x32_bf16 v[108:111], v[128:131], v[208:211], v[108:111]
	v_mfma_f32_16x16x32_bf16 v[108:111], v[132:135], v[212:215], v[108:111]
	v_mfma_f32_16x16x32_bf16 v[104:107], v[136:139], v[208:211], v[104:107]
	v_mfma_f32_16x16x32_bf16 v[104:107], v[140:143], v[212:215], v[104:107]
	v_mfma_f32_16x16x32_bf16 v[92:95], v[128:131], v[216:219], v[92:95]
	v_mfma_f32_16x16x32_bf16 v[92:95], v[132:135], v[220:223], v[92:95]
	v_mfma_f32_16x16x32_bf16 v[88:91], v[136:139], v[216:219], v[88:91]
	v_mfma_f32_16x16x32_bf16 v[88:91], v[140:143], v[220:223], v[88:91]
	v_mfma_f32_16x16x32_bf16 v[76:79], v[128:131], v[224:227], v[76:79]
	v_mfma_f32_16x16x32_bf16 v[76:79], v[132:135], v[228:231], v[76:79]
	v_mfma_f32_16x16x32_bf16 v[72:75], v[136:139], v[224:227], v[72:75]
	v_mfma_f32_16x16x32_bf16 v[72:75], v[140:143], v[228:231], v[72:75]
	s_setprio 0
	s_setprio 1
	v_mfma_f32_16x16x32_bf16 v[116:119], v[144:147], v[200:203], v[116:119]
	v_mfma_f32_16x16x32_bf16 v[116:119], v[148:151], v[204:207], v[116:119]
	v_mfma_f32_16x16x32_bf16 v[112:115], v[168:171], v[200:203], v[112:115]
	v_mfma_f32_16x16x32_bf16 v[112:115], v[196:199], v[204:207], v[112:115]
	v_mfma_f32_16x16x32_bf16 v[100:103], v[144:147], v[208:211], v[100:103]
	v_mfma_f32_16x16x32_bf16 v[100:103], v[148:151], v[212:215], v[100:103]
	v_mfma_f32_16x16x32_bf16 v[96:99], v[168:171], v[208:211], v[96:99]
	v_mfma_f32_16x16x32_bf16 v[96:99], v[196:199], v[212:215], v[96:99]
	v_mfma_f32_16x16x32_bf16 v[84:87], v[144:147], v[216:219], v[84:87]
	v_mfma_f32_16x16x32_bf16 v[84:87], v[148:151], v[220:223], v[84:87]
	v_mfma_f32_16x16x32_bf16 v[80:83], v[168:171], v[216:219], v[80:83]
	v_mfma_f32_16x16x32_bf16 v[80:83], v[196:199], v[220:223], v[80:83]
	v_mfma_f32_16x16x32_bf16 v[68:71], v[144:147], v[224:227], v[68:71]
	v_mfma_f32_16x16x32_bf16 v[68:71], v[148:151], v[228:231], v[68:71]
	v_mfma_f32_16x16x32_bf16 v[64:67], v[168:171], v[224:227], v[64:67]
	v_mfma_f32_16x16x32_bf16 v[64:67], v[196:199], v[228:231], v[64:67]
	s_setprio 0
	s_barrier
	s_add_i32 s26, s60, s10
	v_lshl_add_u64 v[172:173], v[172:173], 0, s[20:21]
	s_mov_b32 m0, s26
	ds_read_b128 v[200:203], v194 offset:49152
	ds_read_b128 v[204:207], v194 offset:50176
	ds_read_b128 v[208:211], v194 offset:51200
	ds_read_b128 v[212:215], v194 offset:52224
	ds_read_b128 v[216:219], v194 offset:53248
	ds_read_b128 v[220:223], v194 offset:54272
	ds_read_b128 v[224:227], v194 offset:55296
	ds_read_b128 v[228:231], v194 offset:56320
	global_load_lds_dwordx4 v[172:173], off
	s_add_i32 m0, s26, 0x2000
	s_add_u32 s26, s36, 0x160080
	v_lshl_add_u64 v[172:173], v[232:233], 0, s[20:21]
	s_addc_u32 s27, s37, 0
	s_add_i32 s36, s61, s10
	global_load_lds_dwordx4 v[172:173], off
	v_lshl_add_u64 v[172:173], s[26:27], 0, v[154:155]
	s_mov_b32 m0, s36
	s_nop 0
	global_load_lds_dwordx4 v[172:173], off
	v_lshl_add_u64 v[172:173], s[26:27], 0, v[158:159]
	s_add_i32 m0, s36, 0x2000
	s_nop 0
	global_load_lds_dwordx4 v[172:173], off
	v_lshl_add_u64 v[172:173], v[234:235], 0, s[20:21]
	s_mov_b32 m0, s43
	s_nop 0
	global_load_lds_dwordx4 v[172:173], off
	v_lshl_add_u64 v[172:173], v[236:237], 0, s[20:21]
	s_mov_b32 m0, s44
	s_nop 0
	global_load_lds_dwordx4 v[172:173], off
	s_waitcnt vmcnt(8)
	s_waitcnt lgkmcnt(0)
	s_barrier
	s_setprio 1
	s_waitcnt lgkmcnt(0)
	v_mfma_f32_16x16x32_bf16 v[60:63], v[128:131], v[200:203], v[60:63]
	v_mfma_f32_16x16x32_bf16 v[60:63], v[132:135], v[204:207], v[60:63]
	v_mfma_f32_16x16x32_bf16 v[56:59], v[136:139], v[200:203], v[56:59]
	v_mfma_f32_16x16x32_bf16 v[56:59], v[140:143], v[204:207], v[56:59]
	v_mfma_f32_16x16x32_bf16 v[44:47], v[128:131], v[208:211], v[44:47]
	v_mfma_f32_16x16x32_bf16 v[44:47], v[132:135], v[212:215], v[44:47]
	v_mfma_f32_16x16x32_bf16 v[40:43], v[136:139], v[208:211], v[40:43]
	v_mfma_f32_16x16x32_bf16 v[40:43], v[140:143], v[212:215], v[40:43]
	v_mfma_f32_16x16x32_bf16 v[28:31], v[128:131], v[216:219], v[28:31]
	v_mfma_f32_16x16x32_bf16 v[28:31], v[132:135], v[220:223], v[28:31]
	v_mfma_f32_16x16x32_bf16 v[24:27], v[136:139], v[216:219], v[24:27]
	v_mfma_f32_16x16x32_bf16 v[24:27], v[140:143], v[220:223], v[24:27]
	v_mfma_f32_16x16x32_bf16 v[12:15], v[128:131], v[224:227], v[12:15]
	v_mfma_f32_16x16x32_bf16 v[12:15], v[132:135], v[228:231], v[12:15]
	v_mfma_f32_16x16x32_bf16 v[8:11], v[136:139], v[224:227], v[8:11]
	v_mfma_f32_16x16x32_bf16 v[8:11], v[140:143], v[228:231], v[8:11]
	s_setprio 0
	s_setprio 1
	v_mfma_f32_16x16x32_bf16 v[52:55], v[144:147], v[200:203], v[52:55]
	v_mfma_f32_16x16x32_bf16 v[52:55], v[148:151], v[204:207], v[52:55]
	v_mfma_f32_16x16x32_bf16 v[48:51], v[168:171], v[200:203], v[48:51]
	v_mfma_f32_16x16x32_bf16 v[48:51], v[196:199], v[204:207], v[48:51]
	v_mfma_f32_16x16x32_bf16 v[36:39], v[144:147], v[208:211], v[36:39]
	v_mfma_f32_16x16x32_bf16 v[36:39], v[148:151], v[212:215], v[36:39]
	v_mfma_f32_16x16x32_bf16 v[32:35], v[168:171], v[208:211], v[32:35]
	v_mfma_f32_16x16x32_bf16 v[32:35], v[196:199], v[212:215], v[32:35]
	v_mfma_f32_16x16x32_bf16 v[20:23], v[144:147], v[216:219], v[20:23]
	v_mfma_f32_16x16x32_bf16 v[20:23], v[148:151], v[220:223], v[20:23]
	v_mfma_f32_16x16x32_bf16 v[16:19], v[168:171], v[216:219], v[16:19]
	v_mfma_f32_16x16x32_bf16 v[16:19], v[196:199], v[220:223], v[16:19]
	v_mfma_f32_16x16x32_bf16 v[4:7], v[144:147], v[224:227], v[4:7]
	v_mfma_f32_16x16x32_bf16 v[4:7], v[148:151], v[228:231], v[4:7]
	v_mfma_f32_16x16x32_bf16 v[0:3], v[168:171], v[224:227], v[0:3]
	v_mfma_f32_16x16x32_bf16 v[0:3], v[196:199], v[228:231], v[0:3]
	s_setprio 0
	s_barrier
	s_add_i32 s51, s51, 2
	s_add_u32 s49, s49, 0x100
	s_addc_u32 s50, s50, 0
	s_cmpk_gt_u32 s51, 0x55
	s_mov_b64 s[26:27], s[34:35]
	s_cbranch_scc0 .LBB0_873
	s_and_b64 vcc, exec, s[22:23]
	s_cbranch_vccz .LBB0_876
	s_barrier

.LBB0_975:
	ds_read_b128 v[132:135], v179
	ds_read_b128 v[136:139], v179 offset:1024
	ds_read_b128 v[140:143], v179 offset:2048
	ds_read_b128 v[144:147], v179 offset:3072
	ds_read_b128 v[148:151], v180
	ds_read_b128 v[166:169], v180 offset:1024
	ds_read_b128 v[170:173], v180 offset:2048
	ds_read_b128 v[174:177], v180 offset:3072
	s_add_u32 s22, s20, 0x100
	s_addc_u32 s23, s21, 0
	s_add_u32 s24, s62, s20
	s_addc_u32 s25, s63, s21
	s_cmpk_eq_i32 s64, 0x54
	s_cselect_b32 s26, s16, s24
	s_cselect_b32 s24, 0, s22
	s_cselect_b32 s27, s17, s25
	s_cselect_b32 s25, 0, s23
	s_add_u32 s24, s2, s24
	s_addc_u32 s25, s3, s25
	s_mov_b32 m0, s57
	v_lshl_add_u64 v[218:219], v[128:129], 0, s[20:21]
	ds_read_b128 v[186:189], v181
	ds_read_b128 v[190:193], v181 offset:1024
	ds_read_b128 v[194:197], v181 offset:2048
	ds_read_b128 v[198:201], v181 offset:3072
	ds_read_b128 v[202:205], v181 offset:4096
	ds_read_b128 v[206:209], v181 offset:5120
	ds_read_b128 v[210:213], v181 offset:6144
	ds_read_b128 v[214:217], v181 offset:7168
	global_load_lds_dwordx4 v[218:219], off
	v_lshl_add_u64 v[218:219], v[130:131], 0, s[20:21]
	s_mov_b32 m0, s58
	s_nop 0
	global_load_lds_dwordx4 v[218:219], off
	s_waitcnt vmcnt(8)
	s_waitcnt lgkmcnt(0)
	s_barrier
	s_setprio 1
	s_waitcnt lgkmcnt(0)
	v_mfma_f32_16x16x32_bf16 v[124:127], v[132:135], v[186:189], v[124:127]
	v_mfma_f32_16x16x32_bf16 v[124:127], v[136:139], v[190:193], v[124:127]
	v_mfma_f32_16x16x32_bf16 v[120:123], v[140:143], v[186:189], v[120:123]
	v_mfma_f32_16x16x32_bf16 v[120:123], v[144:147], v[190:193], v[120:123]
	v_mfma_f32_16x16x32_bf16 v[108:111], v[132:135], v[194:197], v[108:111]
	v_mfma_f32_16x16x32_bf16 v[108:111], v[136:139], v[198:201], v[108:111]
	v_mfma_f32_16x16x32_bf16 v[104:107], v[140:143], v[194:197], v[104:107]
	v_mfma_f32_16x16x32_bf16 v[104:107], v[144:147], v[198:201], v[104:107]
	v_mfma_f32_16x16x32_bf16 v[92:95], v[132:135], v[202:205], v[92:95]
	v_mfma_f32_16x16x32_bf16 v[92:95], v[136:139], v[206:209], v[92:95]
	v_mfma_f32_16x16x32_bf16 v[88:91], v[140:143], v[202:205], v[88:91]
	v_mfma_f32_16x16x32_bf16 v[88:91], v[144:147], v[206:209], v[88:91]
	v_mfma_f32_16x16x32_bf16 v[76:79], v[132:135], v[210:213], v[76:79]
	v_mfma_f32_16x16x32_bf16 v[76:79], v[136:139], v[214:217], v[76:79]
	v_mfma_f32_16x16x32_bf16 v[72:75], v[140:143], v[210:213], v[72:75]
	v_mfma_f32_16x16x32_bf16 v[72:75], v[144:147], v[214:217], v[72:75]
	s_setprio 0
	s_setprio 1
	v_mfma_f32_16x16x32_bf16 v[116:119], v[148:151], v[186:189], v[116:119]
	v_mfma_f32_16x16x32_bf16 v[116:119], v[166:169], v[190:193], v[116:119]
	v_mfma_f32_16x16x32_bf16 v[112:115], v[170:173], v[186:189], v[112:115]
	v_mfma_f32_16x16x32_bf16 v[112:115], v[174:177], v[190:193], v[112:115]
	v_mfma_f32_16x16x32_bf16 v[100:103], v[148:151], v[194:197], v[100:103]
	v_mfma_f32_16x16x32_bf16 v[100:103], v[166:169], v[198:201], v[100:103]
	v_mfma_f32_16x16x32_bf16 v[96:99], v[170:173], v[194:197], v[96:99]
	v_mfma_f32_16x16x32_bf16 v[96:99], v[174:177], v[198:201], v[96:99]
	v_mfma_f32_16x16x32_bf16 v[84:87], v[148:151], v[202:205], v[84:87]
	v_mfma_f32_16x16x32_bf16 v[84:87], v[166:169], v[206:209], v[84:87]
	v_mfma_f32_16x16x32_bf16 v[80:83], v[170:173], v[202:205], v[80:83]
	v_mfma_f32_16x16x32_bf16 v[80:83], v[174:177], v[206:209], v[80:83]
	v_mfma_f32_16x16x32_bf16 v[68:71], v[148:151], v[210:213], v[68:71]
	v_mfma_f32_16x16x32_bf16 v[68:71], v[166:169], v[214:217], v[68:71]
	v_mfma_f32_16x16x32_bf16 v[64:67], v[170:173], v[210:213], v[64:67]
	v_mfma_f32_16x16x32_bf16 v[64:67], v[174:177], v[214:217], v[64:67]
	s_setprio 0
	s_barrier
	s_mov_b32 m0, s59
	v_lshl_add_u64 v[218:219], s[24:25], 0, v[154:155]
	ds_read_b128 v[186:189], v181 offset:16384
	ds_read_b128 v[190:193], v181 offset:17408
	ds_read_b128 v[194:197], v181 offset:18432
	ds_read_b128 v[198:201], v181 offset:19456
	ds_read_b128 v[202:205], v181 offset:20480
	ds_read_b128 v[206:209], v181 offset:21504
	ds_read_b128 v[210:213], v181 offset:22528
	ds_read_b128 v[214:217], v181 offset:23552
	global_load_lds_dwordx4 v[218:219], off
	s_add_i32 m0, s59, 0x2000
	s_add_u32 s20, s24, 0x160000
	v_lshl_add_u64 v[220:221], s[24:25], 0, v[158:159]
	s_addc_u32 s21, s25, 0
	s_add_i32 s65, s56, s31
	global_load_lds_dwordx4 v[220:221], off
	v_lshl_add_u64 v[222:223], s[20:21], 0, v[154:155]
	s_mov_b32 m0, s65
	v_lshl_add_u64 v[224:225], s[26:27], 0, v[156:157]
	global_load_lds_dwordx4 v[222:223], off
	v_lshl_add_u64 v[222:223], s[20:21], 0, v[158:159]
	s_add_i32 m0, s65, 0x2000
	s_nop 0
	global_load_lds_dwordx4 v[222:223], off
	v_lshl_add_u64 v[222:223], s[26:27], 0, v[152:153]
	s_mov_b32 m0, s33
	s_nop 0
	global_load_lds_dwordx4 v[222:223], off
	s_mov_b32 m0, s34
	s_nop 0
	global_load_lds_dwordx4 v[224:225], off
	s_waitcnt vmcnt(8)
	s_waitcnt lgkmcnt(0)
	s_barrier
	s_setprio 1
	s_waitcnt lgkmcnt(0)
	v_mfma_f32_16x16x32_bf16 v[60:63], v[132:135], v[186:189], v[60:63]
	v_mfma_f32_16x16x32_bf16 v[60:63], v[136:139], v[190:193], v[60:63]
	v_mfma_f32_16x16x32_bf16 v[56:59], v[140:143], v[186:189], v[56:59]
	v_mfma_f32_16x16x32_bf16 v[56:59], v[144:147], v[190:193], v[56:59]
	v_mfma_f32_16x16x32_bf16 v[44:47], v[132:135], v[194:197], v[44:47]
	v_mfma_f32_16x16x32_bf16 v[44:47], v[136:139], v[198:201], v[44:47]
	v_mfma_f32_16x16x32_bf16 v[40:43], v[140:143], v[194:197], v[40:43]
	v_mfma_f32_16x16x32_bf16 v[40:43], v[144:147], v[198:201], v[40:43]
	v_mfma_f32_16x16x32_bf16 v[28:31], v[132:135], v[202:205], v[28:31]
	v_mfma_f32_16x16x32_bf16 v[28:31], v[136:139], v[206:209], v[28:31]
	v_mfma_f32_16x16x32_bf16 v[24:27], v[140:143], v[202:205], v[24:27]
	v_mfma_f32_16x16x32_bf16 v[24:27], v[144:147], v[206:209], v[24:27]
	v_mfma_f32_16x16x32_bf16 v[12:15], v[132:135], v[210:213], v[12:15]
	v_mfma_f32_16x16x32_bf16 v[12:15], v[136:139], v[214:217], v[12:15]
	v_mfma_f32_16x16x32_bf16 v[8:11], v[140:143], v[210:213], v[8:11]
	v_mfma_f32_16x16x32_bf16 v[8:11], v[144:147], v[214:217], v[8:11]
	s_setprio 0
	s_setprio 1
	v_mfma_f32_16x16x32_bf16 v[52:55], v[148:151], v[186:189], v[52:55]
	v_mfma_f32_16x16x32_bf16 v[52:55], v[166:169], v[190:193], v[52:55]
	v_mfma_f32_16x16x32_bf16 v[48:51], v[170:173], v[186:189], v[48:51]
	v_mfma_f32_16x16x32_bf16 v[48:51], v[174:177], v[190:193], v[48:51]
	v_mfma_f32_16x16x32_bf16 v[36:39], v[148:151], v[194:197], v[36:39]
	v_mfma_f32_16x16x32_bf16 v[36:39], v[166:169], v[198:201], v[36:39]
	v_mfma_f32_16x16x32_bf16 v[32:35], v[170:173], v[194:197], v[32:35]
	v_mfma_f32_16x16x32_bf16 v[32:35], v[174:177], v[198:201], v[32:35]
	v_mfma_f32_16x16x32_bf16 v[20:23], v[148:151], v[202:205], v[20:23]
	v_mfma_f32_16x16x32_bf16 v[20:23], v[166:169], v[206:209], v[20:23]
	v_mfma_f32_16x16x32_bf16 v[16:19], v[170:173], v[202:205], v[16:19]
	v_mfma_f32_16x16x32_bf16 v[16:19], v[174:177], v[206:209], v[16:19]
	v_mfma_f32_16x16x32_bf16 v[4:7], v[148:151], v[210:213], v[4:7]
	v_mfma_f32_16x16x32_bf16 v[4:7], v[166:169], v[214:217], v[4:7]
	v_mfma_f32_16x16x32_bf16 v[0:3], v[170:173], v[210:213], v[0:3]
	v_mfma_f32_16x16x32_bf16 v[0:3], v[174:177], v[214:217], v[0:3]
	s_setprio 0
	s_barrier
	s_add_i32 s65, 0, 0x18000
	s_add_i32 s66, 0, 0x1c000
	v_add_u32_e32 v144, s65, v178
	v_add_u32_e32 v160, s66, v178
	ds_read_b128 v[132:135], v144
	ds_read_b128 v[136:139], v144 offset:1024
	ds_read_b128 v[140:143], v144 offset:2048
	ds_read_b128 v[144:147], v144 offset:3072
	ds_read_b128 v[148:151], v160
	ds_read_b128 v[166:169], v160 offset:1024
	ds_read_b128 v[170:173], v160 offset:2048
	ds_read_b128 v[174:177], v160 offset:3072
	s_add_u32 s20, s26, 0x160000
	s_addc_u32 s21, s27, 0
	s_mov_b32 m0, s35
	v_lshl_add_u64 v[226:227], s[20:21], 0, v[152:153]
	ds_read_b128 v[186:189], v181 offset:32768
	ds_read_b128 v[190:193], v181 offset:33792
	ds_read_b128 v[194:197], v181 offset:34816
	ds_read_b128 v[198:201], v181 offset:35840
	ds_read_b128 v[202:205], v181 offset:36864
	ds_read_b128 v[206:209], v181 offset:37888
	ds_read_b128 v[210:213], v181 offset:38912
	ds_read_b128 v[214:217], v181 offset:39936
	global_load_lds_dwordx4 v[226:227], off
	v_lshl_add_u64 v[226:227], s[20:21], 0, v[156:157]
	s_mov_b32 m0, s36
	s_nop 0
	global_load_lds_dwordx4 v[226:227], off
	s_waitcnt vmcnt(8)
	s_waitcnt lgkmcnt(0)
	s_barrier
	s_setprio 1
	s_waitcnt lgkmcnt(0)
	v_mfma_f32_16x16x32_bf16 v[124:127], v[132:135], v[186:189], v[124:127]
	v_mfma_f32_16x16x32_bf16 v[124:127], v[136:139], v[190:193], v[124:127]
	v_mfma_f32_16x16x32_bf16 v[120:123], v[140:143], v[186:189], v[120:123]
	v_mfma_f32_16x16x32_bf16 v[120:123], v[144:147], v[190:193], v[120:123]
	v_mfma_f32_16x16x32_bf16 v[108:111], v[132:135], v[194:197], v[108:111]
	v_mfma_f32_16x16x32_bf16 v[108:111], v[136:139], v[198:201], v[108:111]
	v_mfma_f32_16x16x32_bf16 v[104:107], v[140:143], v[194:197], v[104:107]
	v_mfma_f32_16x16x32_bf16 v[104:107], v[144:147], v[198:201], v[104:107]
	v_mfma_f32_16x16x32_bf16 v[92:95], v[132:135], v[202:205], v[92:95]
	v_mfma_f32_16x16x32_bf16 v[92:95], v[136:139], v[206:209], v[92:95]
	v_mfma_f32_16x16x32_bf16 v[88:91], v[140:143], v[202:205], v[88:91]
	v_mfma_f32_16x16x32_bf16 v[88:91], v[144:147], v[206:209], v[88:91]
	v_mfma_f32_16x16x32_bf16 v[76:79], v[132:135], v[210:213], v[76:79]
	v_mfma_f32_16x16x32_bf16 v[76:79], v[136:139], v[214:217], v[76:79]
	v_mfma_f32_16x16x32_bf16 v[72:75], v[140:143], v[210:213], v[72:75]
	v_mfma_f32_16x16x32_bf16 v[72:75], v[144:147], v[214:217], v[72:75]
	s_setprio 0
	s_setprio 1
	v_mfma_f32_16x16x32_bf16 v[116:119], v[148:151], v[186:189], v[116:119]
	v_mfma_f32_16x16x32_bf16 v[116:119], v[166:169], v[190:193], v[116:119]
	v_mfma_f32_16x16x32_bf16 v[112:115], v[170:173], v[186:189], v[112:115]
	v_mfma_f32_16x16x32_bf16 v[112:115], v[174:177], v[190:193], v[112:115]
	v_mfma_f32_16x16x32_bf16 v[100:103], v[148:151], v[194:197], v[100:103]
	v_mfma_f32_16x16x32_bf16 v[100:103], v[166:169], v[198:201], v[100:103]
	v_mfma_f32_16x16x32_bf16 v[96:99], v[170:173], v[194:197], v[96:99]
	v_mfma_f32_16x16x32_bf16 v[96:99], v[174:177], v[198:201], v[96:99]
	v_mfma_f32_16x16x32_bf16 v[84:87], v[148:151], v[202:205], v[84:87]
	v_mfma_f32_16x16x32_bf16 v[84:87], v[166:169], v[206:209], v[84:87]
	v_mfma_f32_16x16x32_bf16 v[80:83], v[170:173], v[202:205], v[80:83]
	v_mfma_f32_16x16x32_bf16 v[80:83], v[174:177], v[206:209], v[80:83]
	v_mfma_f32_16x16x32_bf16 v[68:71], v[148:151], v[210:213], v[68:71]
	v_mfma_f32_16x16x32_bf16 v[68:71], v[166:169], v[214:217], v[68:71]
	v_mfma_f32_16x16x32_bf16 v[64:67], v[170:173], v[210:213], v[64:67]
	v_mfma_f32_16x16x32_bf16 v[64:67], v[174:177], v[214:217], v[64:67]
	s_setprio 0
	s_barrier
	s_add_i32 s20, s65, s31
	v_lshl_add_u64 v[218:219], v[218:219], 0, s[6:7]
	s_mov_b32 m0, s20
	ds_read_b128 v[186:189], v181 offset:49152
	ds_read_b128 v[190:193], v181 offset:50176
	ds_read_b128 v[194:197], v181 offset:51200
	ds_read_b128 v[198:201], v181 offset:52224
	ds_read_b128 v[202:205], v181 offset:53248
	ds_read_b128 v[206:209], v181 offset:54272
	ds_read_b128 v[210:213], v181 offset:55296
	ds_read_b128 v[214:217], v181 offset:56320
	global_load_lds_dwordx4 v[218:219], off
	s_add_i32 m0, s20, 0x2000
	s_add_u32 s20, s24, 0x160080
	v_lshl_add_u64 v[218:219], v[220:221], 0, s[6:7]
	s_addc_u32 s21, s25, 0
	s_add_i32 s24, s66, s31
	global_load_lds_dwordx4 v[218:219], off
	v_lshl_add_u64 v[218:219], s[20:21], 0, v[154:155]
	s_mov_b32 m0, s24
	s_nop 0
	global_load_lds_dwordx4 v[218:219], off
	v_lshl_add_u64 v[218:219], s[20:21], 0, v[158:159]
	s_add_i32 m0, s24, 0x2000
	s_nop 0
	global_load_lds_dwordx4 v[218:219], off
	v_lshl_add_u64 v[218:219], v[222:223], 0, s[6:7]
	s_mov_b32 m0, s39
	s_nop 0
	global_load_lds_dwordx4 v[218:219], off
	v_lshl_add_u64 v[218:219], v[224:225], 0, s[6:7]
	s_mov_b32 m0, s40
	s_nop 0
	global_load_lds_dwordx4 v[218:219], off
	s_waitcnt vmcnt(8)
	s_waitcnt lgkmcnt(0)
	s_barrier
	s_setprio 1
	s_waitcnt lgkmcnt(0)
	v_mfma_f32_16x16x32_bf16 v[60:63], v[132:135], v[186:189], v[60:63]
	v_mfma_f32_16x16x32_bf16 v[60:63], v[136:139], v[190:193], v[60:63]
	v_mfma_f32_16x16x32_bf16 v[56:59], v[140:143], v[186:189], v[56:59]
	v_mfma_f32_16x16x32_bf16 v[56:59], v[144:147], v[190:193], v[56:59]
	v_mfma_f32_16x16x32_bf16 v[44:47], v[132:135], v[194:197], v[44:47]
	v_mfma_f32_16x16x32_bf16 v[44:47], v[136:139], v[198:201], v[44:47]
	v_mfma_f32_16x16x32_bf16 v[40:43], v[140:143], v[194:197], v[40:43]
	v_mfma_f32_16x16x32_bf16 v[40:43], v[144:147], v[198:201], v[40:43]
	v_mfma_f32_16x16x32_bf16 v[28:31], v[132:135], v[202:205], v[28:31]
	v_mfma_f32_16x16x32_bf16 v[28:31], v[136:139], v[206:209], v[28:31]
	v_mfma_f32_16x16x32_bf16 v[24:27], v[140:143], v[202:205], v[24:27]
	v_mfma_f32_16x16x32_bf16 v[24:27], v[144:147], v[206:209], v[24:27]
	v_mfma_f32_16x16x32_bf16 v[12:15], v[132:135], v[210:213], v[12:15]
	v_mfma_f32_16x16x32_bf16 v[12:15], v[136:139], v[214:217], v[12:15]
	v_mfma_f32_16x16x32_bf16 v[8:11], v[140:143], v[210:213], v[8:11]
	v_mfma_f32_16x16x32_bf16 v[8:11], v[144:147], v[214:217], v[8:11]
	s_setprio 0
	s_setprio 1
	v_mfma_f32_16x16x32_bf16 v[52:55], v[148:151], v[186:189], v[52:55]
	v_mfma_f32_16x16x32_bf16 v[52:55], v[166:169], v[190:193], v[52:55]
	v_mfma_f32_16x16x32_bf16 v[48:51], v[170:173], v[186:189], v[48:51]
	v_mfma_f32_16x16x32_bf16 v[48:51], v[174:177], v[190:193], v[48:51]
	v_mfma_f32_16x16x32_bf16 v[36:39], v[148:151], v[194:197], v[36:39]
	v_mfma_f32_16x16x32_bf16 v[36:39], v[166:169], v[198:201], v[36:39]
	v_mfma_f32_16x16x32_bf16 v[32:35], v[170:173], v[194:197], v[32:35]
	v_mfma_f32_16x16x32_bf16 v[32:35], v[174:177], v[198:201], v[32:35]
	v_mfma_f32_16x16x32_bf16 v[20:23], v[148:151], v[202:205], v[20:23]
	v_mfma_f32_16x16x32_bf16 v[20:23], v[166:169], v[206:209], v[20:23]
	v_mfma_f32_16x16x32_bf16 v[16:19], v[170:173], v[202:205], v[16:19]
	v_mfma_f32_16x16x32_bf16 v[16:19], v[174:177], v[206:209], v[16:19]
	v_mfma_f32_16x16x32_bf16 v[4:7], v[148:151], v[210:213], v[4:7]
	v_mfma_f32_16x16x32_bf16 v[4:7], v[166:169], v[214:217], v[4:7]
	v_mfma_f32_16x16x32_bf16 v[0:3], v[170:173], v[210:213], v[0:3]
	v_mfma_f32_16x16x32_bf16 v[0:3], v[174:177], v[214:217], v[0:3]
	s_setprio 0
	s_barrier
	s_add_i32 s64, s64, 2
	s_cmpk_gt_u32 s64, 0x55
	s_mov_b64 s[20:21], s[22:23]
	s_cbranch_scc0 .LBB0_975
	s_and_b64 vcc, exec, s[8:9]
	s_cbranch_vccz .LBB0_978
	s_barrier

	.amdhsa_kernel _Z6mk_fwd4Args
		.amdhsa_group_segment_fixed_size 0
		.amdhsa_private_segment_fixed_size 0
		.amdhsa_kernarg_size 440
		.amdhsa_user_sgpr_count 2
		.amdhsa_user_sgpr_dispatch_ptr 0
		.amdhsa_user_sgpr_queue_ptr 0
		.amdhsa_user_sgpr_kernarg_segment_ptr 1
		.amdhsa_user_sgpr_dispatch_id 0
		.amdhsa_user_sgpr_kernarg_preload_length 0
		.amdhsa_user_sgpr_kernarg_preload_offset 0
		.amdhsa_user_sgpr_private_segment_size 0
		.amdhsa_uses_dynamic_stack 0
		.amdhsa_enable_private_segment 0
		.amdhsa_system_sgpr_workgroup_id_x 1
		.amdhsa_system_sgpr_workgroup_id_y 0
		.amdhsa_system_sgpr_workgroup_id_z 0
		.amdhsa_system_sgpr_workgroup_info 0
		.amdhsa_system_vgpr_workitem_id 2
		.amdhsa_next_free_vgpr 249
		.amdhsa_next_free_sgpr 102
		.amdhsa_accum_offset 252
		.amdhsa_reserve_vcc 1
		.amdhsa_float_round_mode_32 0
		.amdhsa_float_round_mode_16_64 0
		.amdhsa_float_denorm_mode_32 3
		.amdhsa_float_denorm_mode_16_64 3
		.amdhsa_dx10_clamp 1
		.amdhsa_ieee_mode 1
		.amdhsa_fp16_overflow 0
		.amdhsa_tg_split 0
		.amdhsa_exception_fp_ieee_invalid_op 0
		.amdhsa_exception_fp_denorm_src 0
		.amdhsa_exception_fp_ieee_div_zero 0
		.amdhsa_exception_fp_ieee_overflow 0
		.amdhsa_exception_fp_ieee_underflow 0
		.amdhsa_exception_fp_ieee_inexact 0
		.amdhsa_exception_int_div_zero 0
	.end_amdhsa_kernel

amdhsa.kernels:
  - .agpr_count:     0
    .args:
      - .offset:         0
        .size:           184
        .value_kind:     by_value
      - .offset:         184
        .size:           4
        .value_kind:     hidden_block_count_x
      - .offset:         188
        .size:           4
        .value_kind:     hidden_block_count_y
      - .offset:         192
        .size:           4
        .value_kind:     hidden_block_count_z
      - .offset:         196
        .size:           2
        .value_kind:     hidden_group_size_x
      - .offset:         198
        .size:           2
        .value_kind:     hidden_group_size_y
      - .offset:         200
        .size:           2
        .value_kind:     hidden_group_size_z
      - .offset:         202
        .size:           2
        .value_kind:     hidden_remainder_x
      - .offset:         204
        .size:           2
        .value_kind:     hidden_remainder_y
      - .offset:         206
        .size:           2
        .value_kind:     hidden_remainder_z
      - .offset:         224
        .size:           8
        .value_kind:     hidden_global_offset_x
      - .offset:         232
        .size:           8
        .value_kind:     hidden_global_offset_y
      - .offset:         240
        .size:           8
        .value_kind:     hidden_global_offset_z
      - .offset:         248
        .size:           2
        .value_kind:     hidden_grid_dims
      - .offset:         272
        .size:           8
        .value_kind:     hidden_multigrid_sync_arg
      - .offset:         304
        .size:           4
        .value_kind:     hidden_dynamic_lds_size
    .group_segment_fixed_size: 0
    .kernarg_segment_align: 8
    .kernarg_segment_size: 440
    .language:       OpenCL C
    .language_version:
      - 2
      - 0
    .max_flat_workgroup_size: 512
    .name:           _Z6mk_fwd4Args
    .private_segment_fixed_size: 0
    .sgpr_count:     108
    .sgpr_spill_count: 48
    .symbol:         _Z6mk_fwd4Args.kd
    .uniform_work_group_size: 1
    .uses_dynamic_stack: false
    .vgpr_count:     249
    .vgpr_spill_count: 0
    .wavefront_size: 64
